# v4: LDS-DMA address formation via SGPR base + 32-bit offset in attention loop and all six GEMM loops (removes per-DMA 64-bit VALU adds), on top of v3
# speedup vs baseline: 1.0087x; 1.0027x over previous
; #define PG8_STAGE(bufoff, gbase, voff) do { _Pragma("unroll") for (int _i = 0; _i < 2; ++_i) \
;         __builtin_amdgcn_global_load_lds((const unsigned*)((const char*)(gbase) + (voff)[_i]), (LAS unsigned*)(lds + (bufoff) + ldsw + _i * 8192), 16, 0, 0); } while (0)
; #define PG8_LDA(dst, b, h) do { _Pragma("unroll") for (int m = 0; m < 4; ++m) _Pragma("unroll") for (int k = 0; k < 2; ++k) dst[m][k] = *(const LAS bf16x8*)(lds + PG8_SA(b, h) + aoff + m * 2048 + k * 1024); } while (0)
; #define PG8_LDB(dst, b, h) do { _Pragma("unroll") for (int n = 0; n < 2; ++n) _Pragma("unroll") for (int k = 0; k < 2; ++k) dst[n][k] = *(const LAS bf16x8*)(lds + PG8_SB(b, h) + boff + n * 2048 + k * 1024); } while (0)
; #define PG8_MMA(ai, bj, At, Bt) do { __builtin_amdgcn_s_setprio(1); _Pragma("unroll") for (int m = 0; m < 4; ++m) _Pragma("unroll") for (int n = 0; n < 2; ++n) _Pragma("unroll") for (int k = 0; k < 2; ++k) \
;         acc[ai][bj][m][n] = __builtin_amdgcn_mfma_f32_16x16x32_bf16(Bt[n][k], At[m][k], acc[ai][bj][m][n], 0, 0, 0); __builtin_amdgcn_s_setprio(0); } while (0)
; #define PG8_WAIT_V(n) asm volatile("s_waitcnt vmcnt(" #n ")" ::: "memory")
; #define PG8_WAIT_L(n) asm volatile("s_waitcnt lgkmcnt(" #n ")" ::: "memory")
; #define PG8_BAR __builtin_amdgcn_s_barrier()
; template <class Epi, class Sched, bool ALIGN_EPI, bool SP2>
; __device__ __forceinline__ void gemm_phase(LAS unsigned char* lds, const Gemm g, const Sched& S, const Epi& E) {
;     ...
;         for (int t = 0; t < nt; t += 2) {
;             const bool last = (t == nt - 2);
;             const char* a1 = cA + (size_t)(t + 1) * kstep;
;             const char* a2 = last ? nA : cA + (size_t)(t + 2) * kstep; const char* b2 = last ? nB : cB + (size_t)(t + 2) * kstep;
;             const char* a3 = a2 + kstep; const char* b3 = b2 + kstep;
;             if constexpr (SP2) {
;             PG8_LDB(B0, 0, 0); PG8_LDB(B1, 0, 1); PG8_SCHED; PG8_LDA(At, 0, 0); PG8_STAGE(PG8_SA(1, 1), a1 + hstep, voffA);
;             PG8_WAIT_V(8); PG8_WAIT_L(0); PG8_BAR; PG8_MMA(0, 0, At, B0); PG8_MMA(0, 1, At, B1); PG8_BAR; PG8_SCHED;
;             PG8_LDA(At, 0, 1); PG8_STAGE(PG8_SB(0, 0), b2, voffB); PG8_STAGE(PG8_SB(0, 1), b2 + hstep, voffB); PG8_STAGE(PG8_SA(0, 0), a2, voffA);
;             PG8_WAIT_V(8); PG8_WAIT_L(0); PG8_BAR; PG8_MMA(1, 0, At, B0); PG8_MMA(1, 1, At, B1); PG8_BAR; PG8_SCHED;
.LBB0_216:
	ds_read_b128 v[128:131], v177
	ds_read_b128 v[132:135], v177 offset:1024
	ds_read_b128 v[136:139], v177 offset:2048
	ds_read_b128 v[140:143], v177 offset:3072
	ds_read_b128 v[168:171], v178
	ds_read_b128 v[184:187], v178 offset:1024
	ds_read_b128 v[188:191], v178 offset:2048
	ds_read_b128 v[192:195], v178 offset:3072
	s_add_u32 s8, s6, 0xfffc0080
	s_addc_u32 s9, s7, -1
	s_cmp_eq_u32 s43, 12
	s_cselect_b32 s11, s2, s9
	s_cselect_b32 s10, s3, s8
	s_cselect_b32 s9, s5, s42
	s_cselect_b32 s8, s12, s13
	s_add_i32 m0, s71, 0xc000
	ds_read_b128 v[196:199], v179
	ds_read_b128 v[200:203], v179 offset:1024
	ds_read_b128 v[204:207], v179 offset:2048
	ds_read_b128 v[208:211], v179 offset:3072
	ds_read_b128 v[212:215], v179 offset:4096
	ds_read_b128 v[216:219], v179 offset:5120
	ds_read_b128 v[220:223], v179 offset:6144
	ds_read_b128 v[224:227], v179 offset:7168
	global_load_lds_dwordx4 v160, s[6:7]
	s_add_i32 m0, s71, 0xe000
	s_nop 0
	global_load_lds_dwordx4 v162, s[6:7]
	s_waitcnt vmcnt(8)
	s_waitcnt lgkmcnt(0)
	s_barrier
	s_setprio 1
	s_waitcnt lgkmcnt(0)
	v_mfma_f32_16x16x32_bf16 v[124:127], v[128:131], v[196:199], v[124:127]
	v_mfma_f32_16x16x32_bf16 v[120:123], v[136:139], v[196:199], v[120:123]
	v_mfma_f32_16x16x32_bf16 v[116:119], v[128:131], v[204:207], v[116:119]
	v_mfma_f32_16x16x32_bf16 v[112:115], v[136:139], v[204:207], v[112:115]
	v_mfma_f32_16x16x32_bf16 v[108:111], v[128:131], v[212:215], v[108:111]
	v_mfma_f32_16x16x32_bf16 v[104:107], v[136:139], v[212:215], v[104:107]
	v_mfma_f32_16x16x32_bf16 v[100:103], v[128:131], v[220:223], v[100:103]
	v_mfma_f32_16x16x32_bf16 v[96:99], v[136:139], v[220:223], v[96:99]
	v_mfma_f32_16x16x32_bf16 v[124:127], v[132:135], v[200:203], v[124:127]
	v_mfma_f32_16x16x32_bf16 v[120:123], v[140:143], v[200:203], v[120:123]
	v_mfma_f32_16x16x32_bf16 v[116:119], v[132:135], v[208:211], v[116:119]
	v_mfma_f32_16x16x32_bf16 v[112:115], v[140:143], v[208:211], v[112:115]
	v_mfma_f32_16x16x32_bf16 v[108:111], v[132:135], v[216:219], v[108:111]
	v_mfma_f32_16x16x32_bf16 v[104:107], v[140:143], v[216:219], v[104:107]
	v_mfma_f32_16x16x32_bf16 v[100:103], v[132:135], v[224:227], v[100:103]
	v_mfma_f32_16x16x32_bf16 v[96:99], v[140:143], v[224:227], v[96:99]
	s_setprio 0
	s_setprio 1
	v_mfma_f32_16x16x32_bf16 v[60:63], v[168:171], v[196:199], v[60:63]
	v_mfma_f32_16x16x32_bf16 v[56:59], v[188:191], v[196:199], v[56:59]
	v_mfma_f32_16x16x32_bf16 v[52:55], v[168:171], v[204:207], v[52:55]
	v_mfma_f32_16x16x32_bf16 v[48:51], v[188:191], v[204:207], v[48:51]
	v_mfma_f32_16x16x32_bf16 v[44:47], v[168:171], v[212:215], v[44:47]
	v_mfma_f32_16x16x32_bf16 v[40:43], v[188:191], v[212:215], v[40:43]
	v_mfma_f32_16x16x32_bf16 v[36:39], v[168:171], v[220:223], v[36:39]
	v_mfma_f32_16x16x32_bf16 v[32:35], v[188:191], v[220:223], v[32:35]
	v_mfma_f32_16x16x32_bf16 v[60:63], v[184:187], v[200:203], v[60:63]
	v_mfma_f32_16x16x32_bf16 v[56:59], v[192:195], v[200:203], v[56:59]
	v_mfma_f32_16x16x32_bf16 v[52:55], v[184:187], v[208:211], v[52:55]
	v_mfma_f32_16x16x32_bf16 v[48:51], v[192:195], v[208:211], v[48:51]
	v_mfma_f32_16x16x32_bf16 v[44:47], v[184:187], v[216:219], v[44:47]
	v_mfma_f32_16x16x32_bf16 v[40:43], v[192:195], v[216:219], v[40:43]
	v_mfma_f32_16x16x32_bf16 v[36:39], v[184:187], v[224:227], v[36:39]
	v_mfma_f32_16x16x32_bf16 v[32:35], v[192:195], v[224:227], v[32:35]
	s_setprio 0
	s_barrier
	s_add_i32 s44, s74, s70
	s_mov_b32 m0, s44
	ds_read_b128 v[196:199], v179 offset:16384
	ds_read_b128 v[200:203], v179 offset:17408
	ds_read_b128 v[204:207], v179 offset:18432
	ds_read_b128 v[208:211], v179 offset:19456
	ds_read_b128 v[212:215], v179 offset:20480
	ds_read_b128 v[216:219], v179 offset:21504
	ds_read_b128 v[220:223], v179 offset:22528
	ds_read_b128 v[224:227], v179 offset:23552
	global_load_lds_dwordx4 v146, s[8:9]
	s_add_i32 m0, s44, 0x2000
	s_add_u32 s44, s8, 0x40000
	s_addc_u32 s45, s9, 0
	s_add_i32 s50, s75, s70
	global_load_lds_dwordx4 v150, s[8:9]
	s_mov_b32 m0, s50
	s_nop 0
	global_load_lds_dwordx4 v146, s[44:45]
	s_add_i32 m0, s50, 0x2000
	s_nop 0
	global_load_lds_dwordx4 v150, s[44:45]
	s_mov_b32 m0, s71
	s_nop 0
	global_load_lds_dwordx4 v144, s[10:11]
	s_mov_b32 m0, s72
	s_nop 0
	global_load_lds_dwordx4 v148, s[10:11]
	s_waitcnt vmcnt(8)
	s_waitcnt lgkmcnt(0)
	s_barrier
	s_setprio 1
	s_waitcnt lgkmcnt(0)
	v_mfma_f32_16x16x32_bf16 v[92:95], v[128:131], v[196:199], v[92:95]
	v_mfma_f32_16x16x32_bf16 v[88:91], v[136:139], v[196:199], v[88:91]
	v_mfma_f32_16x16x32_bf16 v[84:87], v[128:131], v[204:207], v[84:87]
	v_mfma_f32_16x16x32_bf16 v[80:83], v[136:139], v[204:207], v[80:83]
	v_mfma_f32_16x16x32_bf16 v[76:79], v[128:131], v[212:215], v[76:79]
	v_mfma_f32_16x16x32_bf16 v[72:75], v[136:139], v[212:215], v[72:75]
	v_mfma_f32_16x16x32_bf16 v[68:71], v[128:131], v[220:223], v[68:71]
	v_mfma_f32_16x16x32_bf16 v[64:67], v[136:139], v[220:223], v[64:67]
	v_mfma_f32_16x16x32_bf16 v[92:95], v[132:135], v[200:203], v[92:95]
	v_mfma_f32_16x16x32_bf16 v[88:91], v[140:143], v[200:203], v[88:91]
	v_mfma_f32_16x16x32_bf16 v[84:87], v[132:135], v[208:211], v[84:87]
	v_mfma_f32_16x16x32_bf16 v[80:83], v[140:143], v[208:211], v[80:83]
	v_mfma_f32_16x16x32_bf16 v[76:79], v[132:135], v[216:219], v[76:79]
	v_mfma_f32_16x16x32_bf16 v[72:75], v[140:143], v[216:219], v[72:75]
	v_mfma_f32_16x16x32_bf16 v[68:71], v[132:135], v[224:227], v[68:71]
	v_mfma_f32_16x16x32_bf16 v[64:67], v[140:143], v[224:227], v[64:67]
	s_setprio 0
	s_setprio 1
	v_mfma_f32_16x16x32_bf16 v[28:31], v[168:171], v[196:199], v[28:31]
	v_mfma_f32_16x16x32_bf16 v[24:27], v[188:191], v[196:199], v[24:27]
	v_mfma_f32_16x16x32_bf16 v[20:23], v[168:171], v[204:207], v[20:23]
	v_mfma_f32_16x16x32_bf16 v[16:19], v[188:191], v[204:207], v[16:19]
	v_mfma_f32_16x16x32_bf16 v[12:15], v[168:171], v[212:215], v[12:15]
	v_mfma_f32_16x16x32_bf16 v[8:11], v[188:191], v[212:215], v[8:11]
	v_mfma_f32_16x16x32_bf16 v[4:7], v[168:171], v[220:223], v[4:7]
	v_mfma_f32_16x16x32_bf16 v[0:3], v[188:191], v[220:223], v[0:3]
	v_mfma_f32_16x16x32_bf16 v[28:31], v[184:187], v[200:203], v[28:31]
	v_mfma_f32_16x16x32_bf16 v[24:27], v[192:195], v[200:203], v[24:27]
	v_mfma_f32_16x16x32_bf16 v[20:23], v[184:187], v[208:211], v[20:23]
	v_mfma_f32_16x16x32_bf16 v[16:19], v[192:195], v[208:211], v[16:19]
	v_mfma_f32_16x16x32_bf16 v[12:15], v[184:187], v[216:219], v[12:15]
	v_mfma_f32_16x16x32_bf16 v[8:11], v[192:195], v[216:219], v[8:11]
	v_mfma_f32_16x16x32_bf16 v[4:7], v[184:187], v[224:227], v[4:7]
	v_mfma_f32_16x16x32_bf16 v[0:3], v[192:195], v[224:227], v[0:3]
	s_setprio 0
	s_barrier
; #define PG8_STAGE(bufoff, gbase, voff) do { _Pragma("unroll") for (int _i = 0; _i < 2; ++_i) \
;         __builtin_amdgcn_global_load_lds((const unsigned*)((const char*)(gbase) + (voff)[_i]), (LAS unsigned*)(lds + (bufoff) + ldsw + _i * 8192), 16, 0, 0); } while (0)
; #define PG8_LDA(dst, b, h) do { _Pragma("unroll") for (int m = 0; m < 4; ++m) _Pragma("unroll") for (int k = 0; k < 2; ++k) dst[m][k] = *(const LAS bf16x8*)(lds + PG8_SA(b, h) + aoff + m * 2048 + k * 1024); } while (0)
; #define PG8_LDB(dst, b, h) do { _Pragma("unroll") for (int n = 0; n < 2; ++n) _Pragma("unroll") for (int k = 0; k < 2; ++k) dst[n][k] = *(const LAS bf16x8*)(lds + PG8_SB(b, h) + boff + n * 2048 + k * 1024); } while (0)
; #define PG8_MMA(ai, bj, At, Bt) do { __builtin_amdgcn_s_setprio(1); _Pragma("unroll") for (int m = 0; m < 4; ++m) _Pragma("unroll") for (int n = 0; n < 2; ++n) _Pragma("unroll") for (int k = 0; k < 2; ++k) \
;         acc[ai][bj][m][n] = __builtin_amdgcn_mfma_f32_16x16x32_bf16(Bt[n][k], At[m][k], acc[ai][bj][m][n], 0, 0, 0); __builtin_amdgcn_s_setprio(0); } while (0)
; #define PG8_WAIT_V(n) asm volatile("s_waitcnt vmcnt(" #n ")" ::: "memory")
; #define PG8_WAIT_L(n) asm volatile("s_waitcnt lgkmcnt(" #n ")" ::: "memory")
; #define PG8_BAR __builtin_amdgcn_s_barrier()
; #define PG8_SCHED __builtin_amdgcn_sched_barrier(0)
; template <class Epi, class Sched, bool ALIGN_EPI, bool SP2>
; __device__ __forceinline__ void gemm_phase(LAS unsigned char* lds, const Gemm g, const Sched& S, const Epi& E) {
;     ...
;             PG8_LDB(B0, 1, 0); PG8_LDB(B1, 1, 1); PG8_SCHED; PG8_LDA(At, 1, 0); PG8_STAGE(PG8_SA(0, 1), a2 + hstep, voffA);
;             PG8_WAIT_V(8); PG8_WAIT_L(0); PG8_BAR; PG8_MMA(0, 0, At, B0); PG8_MMA(0, 1, At, B1); PG8_BAR; PG8_SCHED;
;             PG8_LDA(At, 1, 1); PG8_STAGE(PG8_SB(1, 0), b3, voffB); PG8_STAGE(PG8_SB(1, 1), b3 + hstep, voffB); PG8_STAGE(PG8_SA(1, 0), a3, voffA);
;             PG8_WAIT_V(8); PG8_WAIT_L(0); PG8_BAR; PG8_MMA(1, 0, At, B0); PG8_MMA(1, 1, At, B1); PG8_BAR; PG8_SCHED;
	s_add_i32 s44, 0, 0x18000
	s_add_i32 s45, 0, 0x1c000
	v_add_u32_e32 v140, s44, v174
	v_add_u32_e32 v152, s45, v174
	ds_read_b128 v[128:131], v140
	ds_read_b128 v[132:135], v140 offset:1024
	ds_read_b128 v[136:139], v140 offset:2048
	ds_read_b128 v[140:143], v140 offset:3072
	ds_read_b128 v[168:171], v152
	ds_read_b128 v[184:187], v152 offset:1024
	ds_read_b128 v[188:191], v152 offset:2048
	ds_read_b128 v[192:195], v152 offset:3072
	s_add_u32 s10, s10, 0x40000
	s_addc_u32 s11, s11, 0
	s_mov_b32 m0, s73
	ds_read_b128 v[196:199], v179 offset:32768
	ds_read_b128 v[200:203], v179 offset:33792
	ds_read_b128 v[204:207], v179 offset:34816
	ds_read_b128 v[208:211], v179 offset:35840
	ds_read_b128 v[212:215], v179 offset:36864
	ds_read_b128 v[216:219], v179 offset:37888
	ds_read_b128 v[220:223], v179 offset:38912
	ds_read_b128 v[224:227], v179 offset:39936
	global_load_lds_dwordx4 v144, s[10:11]
	s_mov_b32 m0, s82
	s_nop 0
	global_load_lds_dwordx4 v148, s[10:11]
	s_waitcnt vmcnt(8)
	s_waitcnt lgkmcnt(0)
	s_barrier
	s_setprio 1
	s_waitcnt lgkmcnt(0)
	v_mfma_f32_16x16x32_bf16 v[124:127], v[128:131], v[196:199], v[124:127]
	v_mfma_f32_16x16x32_bf16 v[120:123], v[136:139], v[196:199], v[120:123]
	v_mfma_f32_16x16x32_bf16 v[116:119], v[128:131], v[204:207], v[116:119]
	v_mfma_f32_16x16x32_bf16 v[112:115], v[136:139], v[204:207], v[112:115]
	v_mfma_f32_16x16x32_bf16 v[108:111], v[128:131], v[212:215], v[108:111]
	v_mfma_f32_16x16x32_bf16 v[104:107], v[136:139], v[212:215], v[104:107]
	v_mfma_f32_16x16x32_bf16 v[100:103], v[128:131], v[220:223], v[100:103]
	v_mfma_f32_16x16x32_bf16 v[96:99], v[136:139], v[220:223], v[96:99]
	v_mfma_f32_16x16x32_bf16 v[124:127], v[132:135], v[200:203], v[124:127]
	v_mfma_f32_16x16x32_bf16 v[120:123], v[140:143], v[200:203], v[120:123]
	v_mfma_f32_16x16x32_bf16 v[116:119], v[132:135], v[208:211], v[116:119]
	v_mfma_f32_16x16x32_bf16 v[112:115], v[140:143], v[208:211], v[112:115]
	v_mfma_f32_16x16x32_bf16 v[108:111], v[132:135], v[216:219], v[108:111]
	v_mfma_f32_16x16x32_bf16 v[104:107], v[140:143], v[216:219], v[104:107]
	v_mfma_f32_16x16x32_bf16 v[100:103], v[132:135], v[224:227], v[100:103]
	v_mfma_f32_16x16x32_bf16 v[96:99], v[140:143], v[224:227], v[96:99]
	s_setprio 0
	s_setprio 1
	v_mfma_f32_16x16x32_bf16 v[60:63], v[168:171], v[196:199], v[60:63]
	v_mfma_f32_16x16x32_bf16 v[56:59], v[188:191], v[196:199], v[56:59]
	v_mfma_f32_16x16x32_bf16 v[52:55], v[168:171], v[204:207], v[52:55]
	v_mfma_f32_16x16x32_bf16 v[48:51], v[188:191], v[204:207], v[48:51]
	v_mfma_f32_16x16x32_bf16 v[44:47], v[168:171], v[212:215], v[44:47]
	v_mfma_f32_16x16x32_bf16 v[40:43], v[188:191], v[212:215], v[40:43]
	v_mfma_f32_16x16x32_bf16 v[36:39], v[168:171], v[220:223], v[36:39]
	v_mfma_f32_16x16x32_bf16 v[32:35], v[188:191], v[220:223], v[32:35]
	v_mfma_f32_16x16x32_bf16 v[60:63], v[184:187], v[200:203], v[60:63]
	v_mfma_f32_16x16x32_bf16 v[56:59], v[192:195], v[200:203], v[56:59]
	v_mfma_f32_16x16x32_bf16 v[52:55], v[184:187], v[208:211], v[52:55]
	v_mfma_f32_16x16x32_bf16 v[48:51], v[192:195], v[208:211], v[48:51]
	v_mfma_f32_16x16x32_bf16 v[44:47], v[184:187], v[216:219], v[44:47]
	v_mfma_f32_16x16x32_bf16 v[40:43], v[192:195], v[216:219], v[40:43]
	v_mfma_f32_16x16x32_bf16 v[36:39], v[184:187], v[224:227], v[36:39]
	v_mfma_f32_16x16x32_bf16 v[32:35], v[192:195], v[224:227], v[32:35]
	s_setprio 0
	s_barrier
	s_add_u32 s100, s10, 0xfffc0080
	s_addc_u32 s101, s11, -1
	s_add_u32 s98, s8, 0x80
	s_addc_u32 s99, s9, 0
	s_add_i32 s10, s44, s70
	s_mov_b32 m0, s10
	ds_read_b128 v[196:199], v179 offset:49152
	ds_read_b128 v[200:203], v179 offset:50176
	ds_read_b128 v[204:207], v179 offset:51200
	ds_read_b128 v[208:211], v179 offset:52224
	ds_read_b128 v[212:215], v179 offset:53248
	ds_read_b128 v[216:219], v179 offset:54272
	ds_read_b128 v[220:223], v179 offset:55296
	ds_read_b128 v[224:227], v179 offset:56320
	global_load_lds_dwordx4 v146, s[98:99]
	s_add_i32 m0, s10, 0x2000
	s_add_u32 s8, s8, 0x40080
	s_addc_u32 s9, s9, 0
	s_add_i32 s10, s45, s70
	global_load_lds_dwordx4 v150, s[98:99]
	s_mov_b32 m0, s10
	s_nop 0
	global_load_lds_dwordx4 v146, s[8:9]
	s_add_i32 m0, s10, 0x2000
	s_nop 0
	global_load_lds_dwordx4 v150, s[8:9]
	s_mov_b32 m0, s83
	s_nop 0
	global_load_lds_dwordx4 v144, s[100:101]
	s_mov_b32 m0, s84
	s_nop 0
	global_load_lds_dwordx4 v148, s[100:101]
	s_waitcnt vmcnt(8)
	s_waitcnt lgkmcnt(0)
	s_barrier
	s_setprio 1
	s_waitcnt lgkmcnt(0)
	v_mfma_f32_16x16x32_bf16 v[92:95], v[128:131], v[196:199], v[92:95]
	v_mfma_f32_16x16x32_bf16 v[88:91], v[136:139], v[196:199], v[88:91]
	v_mfma_f32_16x16x32_bf16 v[84:87], v[128:131], v[204:207], v[84:87]
	v_mfma_f32_16x16x32_bf16 v[80:83], v[136:139], v[204:207], v[80:83]
	v_mfma_f32_16x16x32_bf16 v[76:79], v[128:131], v[212:215], v[76:79]
	v_mfma_f32_16x16x32_bf16 v[72:75], v[136:139], v[212:215], v[72:75]
	v_mfma_f32_16x16x32_bf16 v[68:71], v[128:131], v[220:223], v[68:71]
	v_mfma_f32_16x16x32_bf16 v[64:67], v[136:139], v[220:223], v[64:67]
	v_mfma_f32_16x16x32_bf16 v[92:95], v[132:135], v[200:203], v[92:95]
	v_mfma_f32_16x16x32_bf16 v[88:91], v[140:143], v[200:203], v[88:91]
	v_mfma_f32_16x16x32_bf16 v[84:87], v[132:135], v[208:211], v[84:87]
	v_mfma_f32_16x16x32_bf16 v[80:83], v[140:143], v[208:211], v[80:83]
	v_mfma_f32_16x16x32_bf16 v[76:79], v[132:135], v[216:219], v[76:79]
	v_mfma_f32_16x16x32_bf16 v[72:75], v[140:143], v[216:219], v[72:75]
	v_mfma_f32_16x16x32_bf16 v[68:71], v[132:135], v[224:227], v[68:71]
	v_mfma_f32_16x16x32_bf16 v[64:67], v[140:143], v[224:227], v[64:67]
	s_setprio 0
	s_setprio 1
	v_mfma_f32_16x16x32_bf16 v[28:31], v[168:171], v[196:199], v[28:31]
	v_mfma_f32_16x16x32_bf16 v[24:27], v[188:191], v[196:199], v[24:27]
	v_mfma_f32_16x16x32_bf16 v[20:23], v[168:171], v[204:207], v[20:23]
	v_mfma_f32_16x16x32_bf16 v[16:19], v[188:191], v[204:207], v[16:19]
	v_mfma_f32_16x16x32_bf16 v[12:15], v[168:171], v[212:215], v[12:15]
	v_mfma_f32_16x16x32_bf16 v[8:11], v[188:191], v[212:215], v[8:11]
	v_mfma_f32_16x16x32_bf16 v[4:7], v[168:171], v[220:223], v[4:7]
	v_mfma_f32_16x16x32_bf16 v[0:3], v[188:191], v[220:223], v[0:3]
	v_mfma_f32_16x16x32_bf16 v[28:31], v[184:187], v[200:203], v[28:31]
	v_mfma_f32_16x16x32_bf16 v[24:27], v[192:195], v[200:203], v[24:27]
	v_mfma_f32_16x16x32_bf16 v[20:23], v[184:187], v[208:211], v[20:23]
	v_mfma_f32_16x16x32_bf16 v[16:19], v[192:195], v[208:211], v[16:19]
	v_mfma_f32_16x16x32_bf16 v[12:15], v[184:187], v[216:219], v[12:15]
	v_mfma_f32_16x16x32_bf16 v[8:11], v[192:195], v[216:219], v[8:11]
	v_mfma_f32_16x16x32_bf16 v[4:7], v[184:187], v[224:227], v[4:7]
	v_mfma_f32_16x16x32_bf16 v[0:3], v[192:195], v[224:227], v[0:3]
	s_setprio 0
	s_barrier
	s_add_i32 s43, s43, 2
	s_add_u32 s6, s6, 0x100
	s_addc_u32 s7, s7, 0
	s_add_u32 s13, s13, 0x100
	s_addc_u32 s42, s42, 0
	s_cmp_gt_u32 s43, 13
	s_cbranch_scc0 .LBB0_216
	s_and_b64 vcc, exec, s[34:35]
	s_cbranch_vccnz .LBB0_221
	v_lshl_add_u32 v168, s4, 8, v155
	s_cmp_lg_u32 s16, 2
	s_mov_b64 s[4:5], -1
	s_cbranch_scc1 .LBB0_222

; #define PG8_STAGE(bufoff, gbase, voff) do { _Pragma("unroll") for (int _i = 0; _i < 2; ++_i) \
;         __builtin_amdgcn_global_load_lds((const unsigned*)((const char*)(gbase) + (voff)[_i]), (LAS unsigned*)(lds + (bufoff) + ldsw + _i * 8192), 16, 0, 0); } while (0)
; #define PG8_LDA(dst, b, h) do { _Pragma("unroll") for (int m = 0; m < 4; ++m) _Pragma("unroll") for (int k = 0; k < 2; ++k) dst[m][k] = *(const LAS bf16x8*)(lds + PG8_SA(b, h) + aoff + m * 2048 + k * 1024); } while (0)
; #define PG8_LDB(dst, b, h) do { _Pragma("unroll") for (int n = 0; n < 2; ++n) _Pragma("unroll") for (int k = 0; k < 2; ++k) dst[n][k] = *(const LAS bf16x8*)(lds + PG8_SB(b, h) + boff + n * 2048 + k * 1024); } while (0)
; #define PG8_MMA(ai, bj, At, Bt) do { __builtin_amdgcn_s_setprio(1); _Pragma("unroll") for (int m = 0; m < 4; ++m) _Pragma("unroll") for (int n = 0; n < 2; ++n) _Pragma("unroll") for (int k = 0; k < 2; ++k) \
;         acc[ai][bj][m][n] = __builtin_amdgcn_mfma_f32_16x16x32_bf16(Bt[n][k], At[m][k], acc[ai][bj][m][n], 0, 0, 0); __builtin_amdgcn_s_setprio(0); } while (0)
; #define PG8_WAIT_V(n) asm volatile("s_waitcnt vmcnt(" #n ")" ::: "memory")
; #define PG8_WAIT_L(n) asm volatile("s_waitcnt lgkmcnt(" #n ")" ::: "memory")
; #define PG8_BAR __builtin_amdgcn_s_barrier()
; template <class Epi, class Sched, bool ALIGN_EPI, bool SP2>
; __device__ __forceinline__ void gemm_phase(LAS unsigned char* lds, const Gemm g, const Sched& S, const Epi& E) {
;     ...
;         for (int t = 0; t < nt; t += 2) {
;             const bool last = (t == nt - 2);
;             const char* a1 = cA + (size_t)(t + 1) * kstep;
;             const char* a2 = last ? nA : cA + (size_t)(t + 2) * kstep; const char* b2 = last ? nB : cB + (size_t)(t + 2) * kstep;
;             const char* a3 = a2 + kstep; const char* b3 = b2 + kstep;
;             if constexpr (SP2) {
;             PG8_LDB(B0, 0, 0); PG8_LDB(B1, 0, 1); PG8_SCHED; PG8_LDA(At, 0, 0); PG8_STAGE(PG8_SA(1, 1), a1 + hstep, voffA);
;             PG8_WAIT_V(8); PG8_WAIT_L(0); PG8_BAR; PG8_MMA(0, 0, At, B0); PG8_MMA(0, 1, At, B1); PG8_BAR; PG8_SCHED;
;             PG8_LDA(At, 0, 1); PG8_STAGE(PG8_SB(0, 0), b2, voffB); PG8_STAGE(PG8_SB(0, 1), b2 + hstep, voffB); PG8_STAGE(PG8_SA(0, 0), a2, voffA);
;             PG8_WAIT_V(8); PG8_WAIT_L(0); PG8_BAR; PG8_MMA(1, 0, At, B0); PG8_MMA(1, 1, At, B1); PG8_BAR; PG8_SCHED;
.LBB0_293:
	ds_read_b128 v[152:155], v149
	ds_read_b128 v[156:159], v149 offset:1024
	ds_read_b128 v[160:163], v149 offset:2048
	ds_read_b128 v[164:167], v149 offset:3072
	ds_read_b128 v[168:171], v150
	ds_read_b128 v[176:179], v150 offset:1024
	ds_read_b128 v[180:183], v150 offset:2048
	ds_read_b128 v[184:187], v150 offset:3072
	s_add_u32 s36, s34, 0xfffc0080
	s_addc_u32 s37, s35, -1
	s_cmp_eq_u32 s62, 12
	s_cselect_b32 s39, s27, s37
	s_cselect_b32 s38, s58, s36
	s_cselect_b32 s37, s25, s61
	s_cselect_b32 s36, s59, s60
	s_add_i32 m0, s23, 0xc000
	ds_read_b128 v[188:191], v151
	ds_read_b128 v[192:195], v151 offset:1024
	ds_read_b128 v[196:199], v151 offset:2048
	ds_read_b128 v[200:203], v151 offset:3072
	ds_read_b128 v[204:207], v151 offset:4096
	ds_read_b128 v[208:211], v151 offset:5120
	ds_read_b128 v[212:215], v151 offset:6144
	ds_read_b128 v[216:219], v151 offset:7168
	global_load_lds_dwordx4 v138, s[34:35]
	s_add_i32 m0, s23, 0xe000
	s_nop 0
	global_load_lds_dwordx4 v140, s[34:35]
	s_waitcnt vmcnt(8)
	s_waitcnt lgkmcnt(0)
	s_barrier
	s_setprio 1
	s_waitcnt lgkmcnt(0)
	v_mfma_f32_16x16x32_bf16 v[124:127], v[152:155], v[188:191], v[124:127]
	v_mfma_f32_16x16x32_bf16 v[120:123], v[160:163], v[188:191], v[120:123]
	v_mfma_f32_16x16x32_bf16 v[116:119], v[152:155], v[196:199], v[116:119]
	v_mfma_f32_16x16x32_bf16 v[112:115], v[160:163], v[196:199], v[112:115]
	v_mfma_f32_16x16x32_bf16 v[100:103], v[152:155], v[204:207], v[100:103]
	v_mfma_f32_16x16x32_bf16 v[96:99], v[160:163], v[204:207], v[96:99]
	v_mfma_f32_16x16x32_bf16 v[84:87], v[152:155], v[212:215], v[84:87]
	v_mfma_f32_16x16x32_bf16 v[80:83], v[160:163], v[212:215], v[80:83]
	v_mfma_f32_16x16x32_bf16 v[124:127], v[156:159], v[192:195], v[124:127]
	v_mfma_f32_16x16x32_bf16 v[120:123], v[164:167], v[192:195], v[120:123]
	v_mfma_f32_16x16x32_bf16 v[116:119], v[156:159], v[200:203], v[116:119]
	v_mfma_f32_16x16x32_bf16 v[112:115], v[164:167], v[200:203], v[112:115]
	v_mfma_f32_16x16x32_bf16 v[100:103], v[156:159], v[208:211], v[100:103]
	v_mfma_f32_16x16x32_bf16 v[96:99], v[164:167], v[208:211], v[96:99]
	v_mfma_f32_16x16x32_bf16 v[84:87], v[156:159], v[216:219], v[84:87]
	v_mfma_f32_16x16x32_bf16 v[80:83], v[164:167], v[216:219], v[80:83]
	s_setprio 0
	s_setprio 1
	v_mfma_f32_16x16x32_bf16 v[108:111], v[168:171], v[188:191], v[108:111]
	v_mfma_f32_16x16x32_bf16 v[104:107], v[180:183], v[188:191], v[104:107]
	v_mfma_f32_16x16x32_bf16 v[92:95], v[168:171], v[196:199], v[92:95]
	v_mfma_f32_16x16x32_bf16 v[88:91], v[180:183], v[196:199], v[88:91]
	v_mfma_f32_16x16x32_bf16 v[76:79], v[168:171], v[204:207], v[76:79]
	v_mfma_f32_16x16x32_bf16 v[72:75], v[180:183], v[204:207], v[72:75]
	v_mfma_f32_16x16x32_bf16 v[68:71], v[168:171], v[212:215], v[68:71]
	v_mfma_f32_16x16x32_bf16 v[64:67], v[180:183], v[212:215], v[64:67]
	v_mfma_f32_16x16x32_bf16 v[108:111], v[176:179], v[192:195], v[108:111]
	v_mfma_f32_16x16x32_bf16 v[104:107], v[184:187], v[192:195], v[104:107]
	v_mfma_f32_16x16x32_bf16 v[92:95], v[176:179], v[200:203], v[92:95]
	v_mfma_f32_16x16x32_bf16 v[88:91], v[184:187], v[200:203], v[88:91]
	v_mfma_f32_16x16x32_bf16 v[76:79], v[176:179], v[208:211], v[76:79]
	v_mfma_f32_16x16x32_bf16 v[72:75], v[184:187], v[208:211], v[72:75]
	v_mfma_f32_16x16x32_bf16 v[68:71], v[176:179], v[216:219], v[68:71]
	v_mfma_f32_16x16x32_bf16 v[64:67], v[184:187], v[216:219], v[64:67]
	s_setprio 0
	s_barrier
	s_add_i32 s63, s50, s33
	s_mov_b32 m0, s63
	ds_read_b128 v[188:191], v151 offset:16384
	ds_read_b128 v[192:195], v151 offset:17408
	ds_read_b128 v[196:199], v151 offset:18432
	ds_read_b128 v[200:203], v151 offset:19456
	ds_read_b128 v[204:207], v151 offset:20480
	ds_read_b128 v[208:211], v151 offset:21504
	ds_read_b128 v[212:215], v151 offset:22528
	ds_read_b128 v[216:219], v151 offset:23552
	global_load_lds_dwordx4 v130, s[36:37]
	s_add_i32 m0, s63, 0x2000
	s_add_u32 s64, s36, 0x40000
	s_addc_u32 s65, s37, 0
	s_add_i32 s63, s51, s33
	global_load_lds_dwordx4 v134, s[36:37]
	s_mov_b32 m0, s63
	s_nop 0
	global_load_lds_dwordx4 v130, s[64:65]
	s_add_i32 m0, s63, 0x2000
	s_nop 0
	global_load_lds_dwordx4 v134, s[64:65]
	s_mov_b32 m0, s23
	s_nop 0
	global_load_lds_dwordx4 v128, s[38:39]
	s_mov_b32 m0, s42
	s_nop 0
	global_load_lds_dwordx4 v132, s[38:39]
	s_waitcnt vmcnt(8)
	s_waitcnt lgkmcnt(0)
	s_barrier
	s_setprio 1
	s_waitcnt lgkmcnt(0)
	v_mfma_f32_16x16x32_bf16 v[60:63], v[152:155], v[188:191], v[60:63]
	v_mfma_f32_16x16x32_bf16 v[56:59], v[160:163], v[188:191], v[56:59]
	v_mfma_f32_16x16x32_bf16 v[52:55], v[152:155], v[196:199], v[52:55]
	v_mfma_f32_16x16x32_bf16 v[48:51], v[160:163], v[196:199], v[48:51]
	v_mfma_f32_16x16x32_bf16 v[36:39], v[152:155], v[204:207], v[36:39]
	v_mfma_f32_16x16x32_bf16 v[32:35], v[160:163], v[204:207], v[32:35]
	v_mfma_f32_16x16x32_bf16 v[20:23], v[152:155], v[212:215], v[20:23]
	v_mfma_f32_16x16x32_bf16 v[16:19], v[160:163], v[212:215], v[16:19]
	v_mfma_f32_16x16x32_bf16 v[60:63], v[156:159], v[192:195], v[60:63]
	v_mfma_f32_16x16x32_bf16 v[56:59], v[164:167], v[192:195], v[56:59]
	v_mfma_f32_16x16x32_bf16 v[52:55], v[156:159], v[200:203], v[52:55]
	v_mfma_f32_16x16x32_bf16 v[48:51], v[164:167], v[200:203], v[48:51]
	v_mfma_f32_16x16x32_bf16 v[36:39], v[156:159], v[208:211], v[36:39]
	v_mfma_f32_16x16x32_bf16 v[32:35], v[164:167], v[208:211], v[32:35]
	v_mfma_f32_16x16x32_bf16 v[20:23], v[156:159], v[216:219], v[20:23]
	v_mfma_f32_16x16x32_bf16 v[16:19], v[164:167], v[216:219], v[16:19]
	s_setprio 0
	s_setprio 1
	v_mfma_f32_16x16x32_bf16 v[44:47], v[168:171], v[188:191], v[44:47]
	v_mfma_f32_16x16x32_bf16 v[40:43], v[180:183], v[188:191], v[40:43]
	v_mfma_f32_16x16x32_bf16 v[28:31], v[168:171], v[196:199], v[28:31]
	v_mfma_f32_16x16x32_bf16 v[24:27], v[180:183], v[196:199], v[24:27]
	v_mfma_f32_16x16x32_bf16 v[12:15], v[168:171], v[204:207], v[12:15]
	v_mfma_f32_16x16x32_bf16 v[8:11], v[180:183], v[204:207], v[8:11]
	v_mfma_f32_16x16x32_bf16 v[4:7], v[168:171], v[212:215], v[4:7]
	v_mfma_f32_16x16x32_bf16 v[0:3], v[180:183], v[212:215], v[0:3]
	v_mfma_f32_16x16x32_bf16 v[44:47], v[176:179], v[192:195], v[44:47]
	v_mfma_f32_16x16x32_bf16 v[40:43], v[184:187], v[192:195], v[40:43]
	v_mfma_f32_16x16x32_bf16 v[28:31], v[176:179], v[200:203], v[28:31]
	v_mfma_f32_16x16x32_bf16 v[24:27], v[184:187], v[200:203], v[24:27]
	v_mfma_f32_16x16x32_bf16 v[12:15], v[176:179], v[208:211], v[12:15]
	v_mfma_f32_16x16x32_bf16 v[8:11], v[184:187], v[208:211], v[8:11]
	v_mfma_f32_16x16x32_bf16 v[4:7], v[176:179], v[216:219], v[4:7]
	v_mfma_f32_16x16x32_bf16 v[0:3], v[184:187], v[216:219], v[0:3]
	s_setprio 0
	s_barrier
; #define PG8_STAGE(bufoff, gbase, voff) do { _Pragma("unroll") for (int _i = 0; _i < 2; ++_i) \
;         __builtin_amdgcn_global_load_lds((const unsigned*)((const char*)(gbase) + (voff)[_i]), (LAS unsigned*)(lds + (bufoff) + ldsw + _i * 8192), 16, 0, 0); } while (0)
; #define PG8_LDA(dst, b, h) do { _Pragma("unroll") for (int m = 0; m < 4; ++m) _Pragma("unroll") for (int k = 0; k < 2; ++k) dst[m][k] = *(const LAS bf16x8*)(lds + PG8_SA(b, h) + aoff + m * 2048 + k * 1024); } while (0)
; #define PG8_LDB(dst, b, h) do { _Pragma("unroll") for (int n = 0; n < 2; ++n) _Pragma("unroll") for (int k = 0; k < 2; ++k) dst[n][k] = *(const LAS bf16x8*)(lds + PG8_SB(b, h) + boff + n * 2048 + k * 1024); } while (0)
; #define PG8_MMA(ai, bj, At, Bt) do { __builtin_amdgcn_s_setprio(1); _Pragma("unroll") for (int m = 0; m < 4; ++m) _Pragma("unroll") for (int n = 0; n < 2; ++n) _Pragma("unroll") for (int k = 0; k < 2; ++k) \
;         acc[ai][bj][m][n] = __builtin_amdgcn_mfma_f32_16x16x32_bf16(Bt[n][k], At[m][k], acc[ai][bj][m][n], 0, 0, 0); __builtin_amdgcn_s_setprio(0); } while (0)
; #define PG8_WAIT_V(n) asm volatile("s_waitcnt vmcnt(" #n ")" ::: "memory")
; #define PG8_WAIT_L(n) asm volatile("s_waitcnt lgkmcnt(" #n ")" ::: "memory")
; #define PG8_BAR __builtin_amdgcn_s_barrier()
; #define PG8_SCHED __builtin_amdgcn_sched_barrier(0)
; template <class Epi, class Sched, bool ALIGN_EPI, bool SP2>
; __device__ __forceinline__ void gemm_phase(LAS unsigned char* lds, const Gemm g, const Sched& S, const Epi& E) {
;     ...
;             PG8_LDB(B0, 1, 0); PG8_LDB(B1, 1, 1); PG8_SCHED; PG8_LDA(At, 1, 0); PG8_STAGE(PG8_SA(0, 1), a2 + hstep, voffA);
;             PG8_WAIT_V(8); PG8_WAIT_L(0); PG8_BAR; PG8_MMA(0, 0, At, B0); PG8_MMA(0, 1, At, B1); PG8_BAR; PG8_SCHED;
	s_add_i32 s63, 0, 0x18000
	v_add_u32_e32 v136, s63, v147
	s_add_i32 s64, 0, 0x1c000
	ds_read_b128 v[152:155], v136
	ds_read_b128 v[156:159], v136 offset:1024
	ds_read_b128 v[160:163], v136 offset:2048
	ds_read_b128 v[164:167], v136 offset:3072
	v_add_u32_e32 v136, s64, v147
	ds_read_b128 v[168:171], v136
	ds_read_b128 v[176:179], v136 offset:1024
	ds_read_b128 v[180:183], v136 offset:2048
	ds_read_b128 v[184:187], v136 offset:3072
	s_add_u32 s38, s38, 0x40000
	s_addc_u32 s39, s39, 0
	s_mov_b32 m0, s43
	ds_read_b128 v[188:191], v151 offset:32768
	ds_read_b128 v[192:195], v151 offset:33792
	ds_read_b128 v[196:199], v151 offset:34816
	ds_read_b128 v[200:203], v151 offset:35840
	ds_read_b128 v[204:207], v151 offset:36864
	ds_read_b128 v[208:211], v151 offset:37888
	ds_read_b128 v[212:215], v151 offset:38912
	ds_read_b128 v[216:219], v151 offset:39936
	global_load_lds_dwordx4 v128, s[38:39]
	s_mov_b32 m0, s44
	s_nop 0
	global_load_lds_dwordx4 v132, s[38:39]
	s_waitcnt vmcnt(8)
	s_waitcnt lgkmcnt(0)
	s_barrier
	s_setprio 1
	s_waitcnt lgkmcnt(0)
	v_mfma_f32_16x16x32_bf16 v[124:127], v[152:155], v[188:191], v[124:127]
	v_mfma_f32_16x16x32_bf16 v[120:123], v[160:163], v[188:191], v[120:123]
	v_mfma_f32_16x16x32_bf16 v[116:119], v[152:155], v[196:199], v[116:119]
	v_mfma_f32_16x16x32_bf16 v[112:115], v[160:163], v[196:199], v[112:115]
	v_mfma_f32_16x16x32_bf16 v[100:103], v[152:155], v[204:207], v[100:103]
	v_mfma_f32_16x16x32_bf16 v[96:99], v[160:163], v[204:207], v[96:99]
	v_mfma_f32_16x16x32_bf16 v[84:87], v[152:155], v[212:215], v[84:87]
	v_mfma_f32_16x16x32_bf16 v[80:83], v[160:163], v[212:215], v[80:83]
	v_mfma_f32_16x16x32_bf16 v[124:127], v[156:159], v[192:195], v[124:127]
	v_mfma_f32_16x16x32_bf16 v[120:123], v[164:167], v[192:195], v[120:123]
	v_mfma_f32_16x16x32_bf16 v[116:119], v[156:159], v[200:203], v[116:119]
	v_mfma_f32_16x16x32_bf16 v[112:115], v[164:167], v[200:203], v[112:115]
	v_mfma_f32_16x16x32_bf16 v[100:103], v[156:159], v[208:211], v[100:103]
	v_mfma_f32_16x16x32_bf16 v[96:99], v[164:167], v[208:211], v[96:99]
	v_mfma_f32_16x16x32_bf16 v[84:87], v[156:159], v[216:219], v[84:87]
	v_mfma_f32_16x16x32_bf16 v[80:83], v[164:167], v[216:219], v[80:83]
	s_setprio 0
	s_setprio 1
	v_mfma_f32_16x16x32_bf16 v[108:111], v[168:171], v[188:191], v[108:111]
	v_mfma_f32_16x16x32_bf16 v[104:107], v[180:183], v[188:191], v[104:107]
	v_mfma_f32_16x16x32_bf16 v[92:95], v[168:171], v[196:199], v[92:95]
	v_mfma_f32_16x16x32_bf16 v[88:91], v[180:183], v[196:199], v[88:91]
	v_mfma_f32_16x16x32_bf16 v[76:79], v[168:171], v[204:207], v[76:79]
	v_mfma_f32_16x16x32_bf16 v[72:75], v[180:183], v[204:207], v[72:75]
	v_mfma_f32_16x16x32_bf16 v[68:71], v[168:171], v[212:215], v[68:71]
	v_mfma_f32_16x16x32_bf16 v[64:67], v[180:183], v[212:215], v[64:67]
	v_mfma_f32_16x16x32_bf16 v[108:111], v[176:179], v[192:195], v[108:111]
	v_mfma_f32_16x16x32_bf16 v[104:107], v[184:187], v[192:195], v[104:107]
	v_mfma_f32_16x16x32_bf16 v[92:95], v[176:179], v[200:203], v[92:95]
	v_mfma_f32_16x16x32_bf16 v[88:91], v[184:187], v[200:203], v[88:91]
	v_mfma_f32_16x16x32_bf16 v[76:79], v[176:179], v[208:211], v[76:79]
	v_mfma_f32_16x16x32_bf16 v[72:75], v[184:187], v[208:211], v[72:75]
	v_mfma_f32_16x16x32_bf16 v[68:71], v[176:179], v[216:219], v[68:71]
	v_mfma_f32_16x16x32_bf16 v[64:67], v[184:187], v[216:219], v[64:67]
	s_setprio 0
	s_barrier
; #define PG8_STAGE(bufoff, gbase, voff) do { _Pragma("unroll") for (int _i = 0; _i < 2; ++_i) \
;         __builtin_amdgcn_global_load_lds((const unsigned*)((const char*)(gbase) + (voff)[_i]), (LAS unsigned*)(lds + (bufoff) + ldsw + _i * 8192), 16, 0, 0); } while (0)
; #define PG8_LDA(dst, b, h) do { _Pragma("unroll") for (int m = 0; m < 4; ++m) _Pragma("unroll") for (int k = 0; k < 2; ++k) dst[m][k] = *(const LAS bf16x8*)(lds + PG8_SA(b, h) + aoff + m * 2048 + k * 1024); } while (0)
; #define PG8_MMA(ai, bj, At, Bt) do { __builtin_amdgcn_s_setprio(1); _Pragma("unroll") for (int m = 0; m < 4; ++m) _Pragma("unroll") for (int n = 0; n < 2; ++n) _Pragma("unroll") for (int k = 0; k < 2; ++k) \
;         acc[ai][bj][m][n] = __builtin_amdgcn_mfma_f32_16x16x32_bf16(Bt[n][k], At[m][k], acc[ai][bj][m][n], 0, 0, 0); __builtin_amdgcn_s_setprio(0); } while (0)
; #define PG8_WAIT_V(n) asm volatile("s_waitcnt vmcnt(" #n ")" ::: "memory")
; #define PG8_WAIT_L(n) asm volatile("s_waitcnt lgkmcnt(" #n ")" ::: "memory")
; #define PG8_BAR __builtin_amdgcn_s_barrier()
; #define PG8_SCHED __builtin_amdgcn_sched_barrier(0)
; template <class Epi, class Sched, bool ALIGN_EPI, bool SP2>
; __device__ __forceinline__ void gemm_phase(LAS unsigned char* lds, const Gemm g, const Sched& S, const Epi& E) {
;     ...
;             PG8_LDA(At, 1, 1); PG8_STAGE(PG8_SB(1, 0), b3, voffB); PG8_STAGE(PG8_SB(1, 1), b3 + hstep, voffB); PG8_STAGE(PG8_SA(1, 0), a3, voffA);
;             PG8_WAIT_V(8); PG8_WAIT_L(0); PG8_BAR; PG8_MMA(1, 0, At, B0); PG8_MMA(1, 1, At, B1); PG8_BAR; PG8_SCHED;
	s_add_u32 s100, s38, 0xfffc0080
	s_addc_u32 s101, s39, -1
	s_add_u32 s98, s36, 0x80
	s_addc_u32 s99, s37, 0
	s_add_i32 s38, s63, s33
	s_mov_b32 m0, s38
	ds_read_b128 v[188:191], v151 offset:49152
	ds_read_b128 v[192:195], v151 offset:50176
	ds_read_b128 v[196:199], v151 offset:51200
	ds_read_b128 v[200:203], v151 offset:52224
	ds_read_b128 v[204:207], v151 offset:53248
	ds_read_b128 v[208:211], v151 offset:54272
	ds_read_b128 v[212:215], v151 offset:55296
	ds_read_b128 v[216:219], v151 offset:56320
	global_load_lds_dwordx4 v130, s[98:99]
	s_add_i32 m0, s38, 0x2000
	s_add_u32 s36, s36, 0x40080
	s_addc_u32 s37, s37, 0
	s_add_i32 s38, s64, s33
	global_load_lds_dwordx4 v134, s[98:99]
	s_mov_b32 m0, s38
	s_nop 0
	global_load_lds_dwordx4 v130, s[36:37]
	s_add_i32 m0, s38, 0x2000
	s_nop 0
	global_load_lds_dwordx4 v134, s[36:37]
	s_mov_b32 m0, s46
	s_nop 0
	global_load_lds_dwordx4 v128, s[100:101]
	s_mov_b32 m0, s47
	s_nop 0
	global_load_lds_dwordx4 v132, s[100:101]
	s_waitcnt vmcnt(8)
	s_waitcnt lgkmcnt(0)
	s_barrier
	s_setprio 1
	s_waitcnt lgkmcnt(0)
	v_mfma_f32_16x16x32_bf16 v[60:63], v[152:155], v[188:191], v[60:63]
	v_mfma_f32_16x16x32_bf16 v[56:59], v[160:163], v[188:191], v[56:59]
	v_mfma_f32_16x16x32_bf16 v[52:55], v[152:155], v[196:199], v[52:55]
	v_mfma_f32_16x16x32_bf16 v[48:51], v[160:163], v[196:199], v[48:51]
	v_mfma_f32_16x16x32_bf16 v[36:39], v[152:155], v[204:207], v[36:39]
	v_mfma_f32_16x16x32_bf16 v[32:35], v[160:163], v[204:207], v[32:35]
	v_mfma_f32_16x16x32_bf16 v[20:23], v[152:155], v[212:215], v[20:23]
	v_mfma_f32_16x16x32_bf16 v[16:19], v[160:163], v[212:215], v[16:19]
	v_mfma_f32_16x16x32_bf16 v[60:63], v[156:159], v[192:195], v[60:63]
	v_mfma_f32_16x16x32_bf16 v[56:59], v[164:167], v[192:195], v[56:59]
	v_mfma_f32_16x16x32_bf16 v[52:55], v[156:159], v[200:203], v[52:55]
	v_mfma_f32_16x16x32_bf16 v[48:51], v[164:167], v[200:203], v[48:51]
	v_mfma_f32_16x16x32_bf16 v[36:39], v[156:159], v[208:211], v[36:39]
	v_mfma_f32_16x16x32_bf16 v[32:35], v[164:167], v[208:211], v[32:35]
	v_mfma_f32_16x16x32_bf16 v[20:23], v[156:159], v[216:219], v[20:23]
	v_mfma_f32_16x16x32_bf16 v[16:19], v[164:167], v[216:219], v[16:19]
	s_setprio 0
	s_setprio 1
	v_mfma_f32_16x16x32_bf16 v[44:47], v[168:171], v[188:191], v[44:47]
	v_mfma_f32_16x16x32_bf16 v[40:43], v[180:183], v[188:191], v[40:43]
	v_mfma_f32_16x16x32_bf16 v[28:31], v[168:171], v[196:199], v[28:31]
	v_mfma_f32_16x16x32_bf16 v[24:27], v[180:183], v[196:199], v[24:27]
	v_mfma_f32_16x16x32_bf16 v[12:15], v[168:171], v[204:207], v[12:15]
	v_mfma_f32_16x16x32_bf16 v[8:11], v[180:183], v[204:207], v[8:11]
	v_mfma_f32_16x16x32_bf16 v[4:7], v[168:171], v[212:215], v[4:7]
	v_mfma_f32_16x16x32_bf16 v[0:3], v[180:183], v[212:215], v[0:3]
	v_mfma_f32_16x16x32_bf16 v[44:47], v[176:179], v[192:195], v[44:47]
	v_mfma_f32_16x16x32_bf16 v[40:43], v[184:187], v[192:195], v[40:43]
	v_mfma_f32_16x16x32_bf16 v[28:31], v[176:179], v[200:203], v[28:31]
	v_mfma_f32_16x16x32_bf16 v[24:27], v[184:187], v[200:203], v[24:27]
	v_mfma_f32_16x16x32_bf16 v[12:15], v[176:179], v[208:211], v[12:15]
	v_mfma_f32_16x16x32_bf16 v[8:11], v[184:187], v[208:211], v[8:11]
	v_mfma_f32_16x16x32_bf16 v[4:7], v[176:179], v[216:219], v[4:7]
	v_mfma_f32_16x16x32_bf16 v[0:3], v[184:187], v[216:219], v[0:3]
	s_setprio 0
	s_barrier
	s_add_i32 s62, s62, 2
	s_add_u32 s34, s34, 0x100
	s_addc_u32 s35, s35, 0
	s_add_u32 s60, s60, 0x100
	s_addc_u32 s61, s61, 0
	s_cmp_gt_u32 s62, 13
	s_cbranch_scc0 .LBB0_293
	v_readlane_b32 s60, v236, 28
	v_readlane_b32 s64, v236, 32
	v_readlane_b32 s65, v236, 33
	v_readlane_b32 s66, v236, 34
	v_readlane_b32 s67, v236, 35
	v_readlane_b32 s72, v236, 40
	v_readlane_b32 s73, v236, 41
	v_readlane_b32 s74, v236, 42
	v_readlane_b32 s75, v236, 43
	s_mov_b64 s[58:59], s[66:67]
	s_mov_b64 s[64:65], s[72:73]
	s_and_b64 vcc, exec, s[10:11]
	s_mov_b64 s[66:67], s[74:75]
	v_readlane_b32 s61, v236, 29
	v_readlane_b32 s62, v236, 30
	v_readlane_b32 s63, v236, 31
	v_readlane_b32 s68, v236, 36
	v_readlane_b32 s69, v236, 37
	v_readlane_b32 s70, v236, 38
	v_readlane_b32 s71, v236, 39
	s_cbranch_vccz .LBB0_296
	s_barrier

; __device__ __forceinline__ void attn_unit(LAS unsigned char* lds, const bf16_t* __restrict__ DQ, const bf16_t* __restrict__ DK, const bf16_t* __restrict__ VT,
;                                           bf16_t* __restrict__ OD, const float* __restrict__ g_out, float lam, int b, int h, int qb) {
;     ...
;     { const bf16_t* qp = DQ + (tok0 + qb * 128 + sub * 32 + r) * 512 + h * 128 + map * 64 + hh * 8;
; #pragma unroll
;       for (int s = 0; s < 4; ++s) qf[s] = *(const bf16x8*)(qp + 16 * s); }
;     asm volatile("" : "+v"(qf[0]), "+v"(qf[1]), "+v"(qf[2]), "+v"(qf[3]));
;     const char* ksrc[2]; const char* vsrc[2];
; #pragma unroll
;     for (int i = 0; i < 2; ++i) { const int key = (4 * i + (lane >> 4)) & 7, c = (lane & 7) ^ key;
;         const int krow = ((wid & 3) * 2 + i) * 8 + (lane >> 3), vrow = (wid * 2 + i) * 8 + (lane >> 3);
;         ksrc[i] = (const char*)(DK + (tok0 + krow) * 512 + h * 128 + map * 64 + c * 8);
;         vsrc[i] = (const char*)(VT + ((size_t)b * 1024 + 512 + h * 128 + vrow) * SEQ + c * 8); }
;     const unsigned dbase = (unsigned)wid * 2048u;
;     ...
;     const int NT = 2 * qb + 2, my_nt = (sub < 2) ? NT - 1 : NT;
;     f32x16 o[4];
; #pragma unroll
;     for (int d = 0; d < 4; ++d)
; #pragma unroll
;         for (int i = 0; i < 16; ++i) o[d][i] = 0.f;
;     float lsum = 0.f;
;     int foff[4];
; #pragma unroll
;     for (int s = 0; s < 4; ++s) foff[s] = r * 128 + (((2 * s + hh) ^ ((r >> 1) & 7)) * 16);
;     AT_DMA(0, 0); AT_DMA(1, 1);
;     asm volatile("s_waitcnt vmcnt(0)" ::: "memory"); __builtin_amdgcn_s_barrier(); asm volatile("" ::: "memory");
.LBB0_365:
	s_or_b64 exec, exec, s[0:1]
	s_waitcnt lgkmcnt(0)
	s_barrier
	ds_read_b32 v0, v160
	s_movk_i32 s0, 0x107
	s_waitcnt lgkmcnt(0)
	s_barrier
	v_cmp_lt_u32_e32 vcc, s0, v0
	v_readfirstlane_b32 s10, v0
	s_mov_b64 s[0:1], -1
	s_cbranch_vccnz .LBB0_360
	s_cmp_gt_u32 s10, 7
	s_cbranch_scc0 .LBB0_378
	v_mov_b32_e32 v161, v175
	s_add_i32 s1, s10, -8
	s_lshr_b32 s0, s1, 5
	v_readfirstlane_b32 s12, v161
	s_and_b32 s8, s1, 31
	s_ashr_i32 s9, s12, 6
	s_add_i32 s0, s0, s2
	s_xor_b32 s14, s8, 31
	s_and_b32 s11, s9, 3
	s_lshr_b32 s48, s0, 2
	s_lshl_b32 s0, s14, 7
	s_lshl_b32 s4, s11, 5
	s_lshl_b64 s[6:7], s[48:49], 12
	s_or_b32 s0, s4, s0
	v_and_b32_e32 v164, 31, v161
	s_or_b32 s0, s6, s0
	s_ashr_i32 s13, s12, 8
	v_or_b32_e32 v0, s0, v164
	v_mov_b32_e32 v1, s7
	s_lshl_b32 s1, s1, 2
	v_lshlrev_b64 v[2:3], 10, v[0:1]
	s_and_b32 s1, s1, 0x180
	s_lshl_b32 s16, s13, 6
	v_lshl_add_u64 v[2:3], s[62:63], 0, v[2:3]
	s_lshl_b32 s4, s1, 1
	s_mov_b32 s5, s49
	s_ashr_i32 s17, s16, 31
	v_bfe_u32 v163, v161, 5, 1
	v_lshl_add_u64 v[2:3], v[2:3], 0, s[4:5]
	s_lshl_b64 s[16:17], s[16:17], 1
	v_lshl_add_u64 v[2:3], v[2:3], 0, s[16:17]
	v_lshlrev_b32_e32 v146, 4, v163
	v_lshl_add_u64 v[2:3], v[2:3], 0, v[146:147]
	global_load_dwordx4 v[128:131], v[2:3], off offset:96
	global_load_dwordx4 v[132:135], v[2:3], off offset:64
	global_load_dwordx4 v[136:139], v[2:3], off offset:32
	global_load_dwordx4 v[140:143], v[2:3], off
	v_bfe_u32 v162, v161, 4, 2
	v_and_b32_e32 v0, 7, v161
	v_bfe_u32 v7, v161, 3, 3
	v_bitop3_b32 v0, v162, v0, 4 bitop3:0x36
	s_add_u32 s5, s97, s4
	v_lshlrev_b32_e32 v4, 4, v0
	v_lshl_or_b32 v0, s11, 4, v7
	s_addc_u32 s15, s42, 0
	v_or_b32_e32 v0, s6, v0
	s_add_u32 s16, s5, s16
	v_lshlrev_b64 v[10:11], 10, v[0:1]
	v_or_b32_e32 v0, 8, v0
	s_addc_u32 s17, s15, s17
	s_lshl_b64 s[18:19], s[48:49], 10
	v_lshl_or_b32 v6, s9, 4, v7
	v_lshlrev_b64 v[0:1], 10, v[0:1]
	s_or_b32 s6, s18, s1
	v_mov_b32_e32 v5, v147
	v_ashrrev_i32_e32 v7, 31, v6
	v_lshl_add_u64 v[0:1], s[16:17], 0, v[0:1]
	s_or_b32 s18, s6, 0x200
	v_bitop3_b32 v2, v162, v161, 7 bitop3:0x78
	v_or_b32_e32 v8, 8, v6
	s_lshl_b32 s5, s9, 11
	v_lshl_add_u64 v[152:153], v[0:1], 0, v[4:5]
	v_lshl_add_u64 v[0:1], s[18:19], 0, v[6:7]
	v_mov_b32_e32 v3, v147
	v_lshlrev_b32_e32 v2, 4, v2
	v_ashrrev_i32_e32 v9, 31, v8
	v_lshl_add_u64 v[10:11], s[16:17], 0, v[10:11]
	s_add_i32 s1, s5, 0
	v_lshlrev_b64 v[0:1], 13, v[0:1]
	v_lshl_add_u64 v[150:151], v[10:11], 0, v[2:3]
	s_add_i32 s5, s1, 0x4000
	v_lshl_add_u64 v[6:7], s[18:19], 0, v[8:9]
	v_lshl_add_u64 v[0:1], s[64:65], 0, v[0:1]
	s_mov_b32 m0, s1
	v_lshlrev_b64 v[6:7], 13, v[6:7]
	v_lshl_add_u64 v[154:155], v[0:1], 0, v[2:3]
	v_lshl_add_u64 v[6:7], s[64:65], 0, v[6:7]
	v_lshl_add_u64 v[156:157], v[6:7], 0, v[4:5]
	s_add_i32 s6, s1, 0xc000
	v_readfirstlane_b32 s98, v150
	v_readfirstlane_b32 s99, v151
	v_readfirstlane_b32 s100, v154
	v_readfirstlane_b32 s101, v155
	s_nop 3
	s_sub_u32 s98, s98, 0x80
	s_subb_u32 s99, s99, 0
	s_sub_u32 s100, s100, 0x80
	s_subb_u32 s101, s101, 0
	v_subrev_u32_e32 v150, s98, v150
	v_subrev_u32_e32 v152, s98, v152
	v_subrev_u32_e32 v154, s100, v154
	v_subrev_u32_e32 v156, s100, v156
	s_add_u32 s16, s98, s52
	s_addc_u32 s17, s99, s53
	s_add_u32 s18, s100, s54
	s_addc_u32 s19, s101, s55
	v_bfe_u32 v2, v161, 1, 3
	s_waitcnt vmcnt(0)
	global_load_lds_dwordx4 v150, s[98:99]
	s_mov_b32 m0, s5
	s_lshl_b32 s5, s13, 13
	global_load_lds_dwordx4 v154, s[100:101]
	s_add_i32 m0, s1, 0x400
	s_nop 0
	global_load_lds_dwordx4 v152, s[98:99]
	s_add_i32 m0, s1, 0x4400
	s_nop 0
	global_load_lds_dwordx4 v156, s[100:101]
	s_add_i32 m0, s1, 0x8000
	s_nop 0
	global_load_lds_dwordx4 v150, s[16:17]
	s_mov_b32 m0, s6
	s_nop 0
	global_load_lds_dwordx4 v154, s[18:19]
	s_add_i32 m0, s1, 0x8400
	s_nop 0
	global_load_lds_dwordx4 v152, s[16:17]
	s_add_i32 m0, s1, 0xc400
	s_cmp_eq_u32 s8, 31
	global_load_lds_dwordx4 v156, s[18:19]
	v_lshrrev_b32_e32 v1, 1, v161
	v_lshlrev_b32_e32 v0, 7, v164
	v_bitop3_b32 v1, v163, v1, 7 bitop3:0x78
	v_lshl_or_b32 v168, v1, 4, v0
	v_bitop3_b32 v1, v163, v2, 2 bitop3:0x36
	v_lshl_or_b32 v167, v1, 4, v0
	v_bitop3_b32 v1, v163, v2, 4 bitop3:0x36
	s_waitcnt vmcnt(0)
	s_barrier
	v_lshl_or_b32 v166, v1, 4, v0
	v_bitop3_b32 v1, v163, v2, 6 bitop3:0x36
	v_lshl_or_b32 v165, v1, 4, v0
	s_cbranch_scc1 .LBB0_370
	v_mov_b32_e32 v64, 0
	v_mov_b32_e32 v149, 0
	s_mov_b32 s8, 3
	s_mov_b32 s6, 0x10000
	s_mov_b32 s15, s14
	v_mov_b32_e32 v0, v149
	v_mov_b32_e32 v1, v149
	v_mov_b32_e32 v2, v149
	v_mov_b32_e32 v3, v149
	v_mov_b32_e32 v4, v149
	v_mov_b32_e32 v5, v149
	v_mov_b32_e32 v6, v149
	v_mov_b32_e32 v7, v149
	v_mov_b32_e32 v8, v149
	v_mov_b32_e32 v9, v149
	v_mov_b32_e32 v10, v149
	v_mov_b32_e32 v11, v149
	v_mov_b32_e32 v12, v149
	v_mov_b32_e32 v13, v149
	v_mov_b32_e32 v14, v149
	v_mov_b32_e32 v15, v149
	v_mov_b32_e32 v16, v149
	v_mov_b32_e32 v17, v149
	v_mov_b32_e32 v18, v149
	v_mov_b32_e32 v19, v149
	v_mov_b32_e32 v20, v149
	v_mov_b32_e32 v21, v149
	v_mov_b32_e32 v22, v149
	v_mov_b32_e32 v23, v149
	v_mov_b32_e32 v24, v149
	v_mov_b32_e32 v25, v149
	v_mov_b32_e32 v26, v149
	v_mov_b32_e32 v27, v149
	v_mov_b32_e32 v28, v149
	v_mov_b32_e32 v29, v149
	v_mov_b32_e32 v30, v149
	v_mov_b32_e32 v31, v149
	v_mov_b32_e32 v32, v149
	v_mov_b32_e32 v33, v149
	v_mov_b32_e32 v34, v149
	v_mov_b32_e32 v35, v149
	v_mov_b32_e32 v36, v149
	v_mov_b32_e32 v37, v149
	v_mov_b32_e32 v38, v149
	v_mov_b32_e32 v39, v149
	v_mov_b32_e32 v40, v149
	v_mov_b32_e32 v41, v149
	v_mov_b32_e32 v42, v149
	v_mov_b32_e32 v43, v149
	v_mov_b32_e32 v44, v149
	v_mov_b32_e32 v45, v149
	v_mov_b32_e32 v46, v149
	v_mov_b32_e32 v47, v149
	v_mov_b32_e32 v48, v149
	v_mov_b32_e32 v49, v149
	v_mov_b32_e32 v50, v149
	v_mov_b32_e32 v51, v149
	v_mov_b32_e32 v52, v149
	v_mov_b32_e32 v53, v149
	v_mov_b32_e32 v54, v149
	v_mov_b32_e32 v55, v149
	v_mov_b32_e32 v56, v149
	v_mov_b32_e32 v57, v149
	v_mov_b32_e32 v58, v149
	v_mov_b32_e32 v59, v149
	v_mov_b32_e32 v60, v149
	v_mov_b32_e32 v61, v149
	v_mov_b32_e32 v62, v149
	v_mov_b32_e32 v63, v149
	v_mov_b32_e32 v65, v64
	v_mov_b32_e32 v66, v64
	v_mov_b32_e32 v67, v64
	v_mov_b32_e32 v68, v64
	v_mov_b32_e32 v69, v64
	v_mov_b32_e32 v70, v64
	v_mov_b32_e32 v71, v64
	v_mov_b32_e32 v80, v64
	v_mov_b32_e32 v81, v64
	v_mov_b32_e32 v82, v64
	v_mov_b32_e32 v83, v64
	v_mov_b32_e32 v84, v64
	v_mov_b32_e32 v85, v64
	v_mov_b32_e32 v86, v64
	v_mov_b32_e32 v87, v64
	v_mov_b32_e32 v72, v64
	v_mov_b32_e32 v73, v64
	v_mov_b32_e32 v74, v64
	v_mov_b32_e32 v75, v64
; #define LAS __attribute__((address_space(3)))
; #define AT_SB() __builtin_amdgcn_sched_barrier(0)
; #define AT_KLD(KB) do { _Pragma("unroll") for (int s_ = 0; s_ < 4; ++s_) { kf[2 * s_] = *(const LAS bf16x8*)((KB) + foff[s_]); kf[2 * s_ + 1] = *(const LAS bf16x8*)((KB) + 4096 + foff[s_]); } } while (0)
; #define AT_QK(S0, S1) do { _Pragma("unroll") for (int i_ = 0; i_ < 16; ++i_) { S0[i_] = 0.f; S1[i_] = 0.f; } \
;         _Pragma("unroll") for (int s_ = 0; s_ < 4; ++s_) { S0 = __builtin_amdgcn_mfma_f32_32x32x16_bf16(kf[2 * s_], qf[s_], S0, 0, 0, 0); \
;             S1 = __builtin_amdgcn_mfma_f32_32x32x16_bf16(kf[2 * s_ + 1], qf[s_], S1, 0, 0, 0); } } while (0)
; #define AT_PV(VF, PF) do { _Pragma("unroll") for (int dt_ = 0; dt_ < 4; ++dt_) o[dt_] = __builtin_amdgcn_mfma_f32_32x32x16_bf16(VF[dt_], PF, o[dt_], 0, 0, 0); } while (0)
; #define AT_VLD(VF, VB, KS) do { _Pragma("unroll") for (int dt_ = 0; dt_ < 4; ++dt_) VF[dt_] = *(const LAS bf16x8*)((VB) + dt_ * 4096 + foff[KS]); } while (0)
; __device__ __forceinline__ void attn_unit(LAS unsigned char* lds, const bf16_t* __restrict__ DQ, const bf16_t* __restrict__ DK, const bf16_t* __restrict__ VT,
;                                           bf16_t* __restrict__ OD, const float* __restrict__ g_out, float lam, int b, int h, int qb) {
;     ...
;     for (int j = 0; j < NP - 1; ++j) {
;         const int st0 = (j & 1) * 2, sn = ((j + 1) & 1) * 2;
;         const LAS unsigned char* kb0 = lds + st0 * STB + map * 8192; const LAS unsigned char* vb0 = lds + st0 * STB + ST_V;
;         const LAS unsigned char* kb1 = kb0 + STB; const LAS unsigned char* vb1 = vb0 + STB;
;         f32x16 a0, a1, b0, b1;
;         AT_DMA(2 * j + 2, sn); AT_KLD(kb0); AT_VLD(vfa, vb0, 0); AT_PV(vfb, pfn); AT_SB();
;         AT_QK(a0, a1); AT_SB();
;         AT_DMA(2 * j + 3, sn + 1); AT_KLD(kb1); AT_SB();
;         AT_QK(b0, b1); AT_EXPBLK(a0, 0, pfc); AT_SB();
;         AT_VLD(vfb, vb0, 1); AT_PV(vfa, pfc); AT_EXPBLK(a0, 8, pfn); AT_SB();
.LBB0_369:
	s_and_b32 s9, s6, 0x10000
	s_add_i32 s48, s8, -1
	s_lshl_b64 s[16:17], s[48:49], 16
	s_add_u32 s16, s16, s98
	s_addc_u32 s17, s17, s99
	s_add_i32 s22, s1, s9
	s_lshl_b64 s[18:19], s[48:49], 7
	s_add_u32 s18, s18, s100
	s_addc_u32 s19, s19, s101
	s_add_i32 s9, s22, 0x4000
	s_mov_b32 m0, s22
	s_waitcnt lgkmcnt(0)
	v_mfma_f32_32x32x16_bf16 v[48:63], v[84:87], v[72:75], v[48:63]
	global_load_lds_dwordx4 v150, s[16:17]
	s_mov_b32 m0, s9
	s_add_i32 s9, s6, 0xffff0000
	global_load_lds_dwordx4 v154, s[18:19]
	s_add_i32 m0, s22, 0x400
	s_and_b32 s9, s9, 0x10000
	global_load_lds_dwordx4 v152, s[16:17]
	s_add_i32 m0, s22, 0x4400
	s_add_i32 s16, s9, 0
	global_load_lds_dwordx4 v156, s[18:19]
	s_add_i32 s9, s16, s5
	v_add_u32_e32 v148, s9, v168
	v_mfma_f32_32x32x16_bf16 v[32:47], v[80:83], v[72:75], v[32:47]
	v_add_u32_e32 v169, s9, v167
	v_add_u32_e32 v174, s9, v166
	v_add_u32_e32 v200, s9, v165
	v_add_u32_e32 v208, s16, v168
	ds_read_b128 v[76:79], v148
	ds_read_b128 v[84:87], v148 offset:4096
	ds_read_b128 v[80:83], v169
	ds_read_b128 v[88:91], v169 offset:4096
	ds_read_b128 v[92:95], v174
	ds_read_b128 v[112:115], v174 offset:4096
	v_mfma_f32_32x32x16_bf16 v[16:31], v[68:71], v[72:75], v[16:31]
	ds_read_b128 v[68:71], v200
	ds_read_b128 v[116:119], v200 offset:4096
	ds_read_b128 v[170:173], v208 offset:16384
	ds_read_b128 v[176:179], v208 offset:20480
	ds_read_b128 v[180:183], v208 offset:24576
	ds_read_b128 v[184:187], v208 offset:28672
	v_mfma_f32_32x32x16_bf16 v[0:15], v[64:67], v[72:75], v[0:15]
	s_waitcnt lgkmcnt(0)
	v_mfma_f32_32x32x16_bf16 v[96:111], v[84:87], v[140:143], 0
	v_mfma_f32_32x32x16_bf16 v[96:111], v[88:91], v[136:139], v[96:111]
	v_mfma_f32_32x32x16_bf16 v[96:111], v[112:115], v[132:135], v[96:111]
	v_mfma_f32_32x32x16_bf16 v[96:111], v[116:119], v[128:131], v[96:111]
	s_mov_b32 s9, s49
	s_lshl_b64 s[18:19], s[8:9], 16
	s_add_u32 s18, s18, s98
	s_addc_u32 s19, s19, s99
	s_add_i32 m0, s22, 0x8000
	s_lshl_b64 s[20:21], s[8:9], 7
	s_add_u32 s20, s20, s100
	s_addc_u32 s21, s21, s101
	s_add_i32 s9, s22, 0xc000
	global_load_lds_dwordx4 v150, s[18:19]
	s_mov_b32 m0, s9
	v_mfma_f32_32x32x16_bf16 v[112:127], v[76:79], v[140:143], 0
	global_load_lds_dwordx4 v154, s[20:21]
	s_add_i32 m0, s22, 0x8400
	s_nop 0
	global_load_lds_dwordx4 v152, s[18:19]
	s_add_i32 m0, s22, 0xc400
	v_mfma_f32_32x32x16_bf16 v[112:127], v[80:83], v[136:139], v[112:127]
	global_load_lds_dwordx4 v156, s[20:21]
	v_mfma_f32_32x32x16_bf16 v[112:127], v[92:95], v[132:135], v[112:127]
	ds_read_b128 v[80:83], v148 offset:32768
	ds_read_b128 v[64:67], v148 offset:36864
	ds_read_b128 v[188:191], v169 offset:32768
	ds_read_b128 v[84:87], v169 offset:36864
	ds_read_b128 v[192:195], v174 offset:32768
	ds_read_b128 v[88:91], v174 offset:36864
	ds_read_b128 v[196:199], v200 offset:32768
	ds_read_b128 v[92:95], v200 offset:36864
	v_mfma_f32_32x32x16_bf16 v[112:127], v[68:71], v[128:131], v[112:127]
	s_waitcnt lgkmcnt(0)
	v_mfma_f32_32x32x16_bf16 v[64:79], v[64:67], v[140:143], 0
	s_nop 9
	v_exp_f32_e32 v112, v112
	v_mfma_f32_32x32x16_bf16 v[64:79], v[84:87], v[136:139], v[64:79]
	v_mfma_f32_32x32x16_bf16 v[64:79], v[88:91], v[132:135], v[64:79]
	v_mfma_f32_32x32x16_bf16 v[64:79], v[92:95], v[128:131], v[64:79]
	v_mfma_f32_32x32x16_bf16 v[80:95], v[80:83], v[140:143], 0
	v_mfma_f32_32x32x16_bf16 v[80:95], v[188:191], v[136:139], v[80:95]
	v_exp_f32_e32 v188, v113
	v_exp_f32_e32 v113, v114
	v_exp_f32_e32 v189, v115
	v_exp_f32_e32 v114, v116
	v_exp_f32_e32 v116, v117
	v_exp_f32_e32 v115, v118
	v_exp_f32_e32 v117, v119
	v_mfma_f32_32x32x16_bf16 v[80:95], v[192:195], v[132:135], v[80:95]
	v_add_f32_e64 v118, v112, v188
	v_add_f32_e64 v119, v113, v189
	v_cvt_pk_bf16_f32 v112, v112, v188
	v_add_f32_e64 v200, v118, v118
	v_add_f32_e64 v201, v118, v119
	v_pk_add_f32 v[118:119], v[114:115], v[116:117]
	v_cvt_pk_bf16_f32 v113, v113, v189
	v_pk_add_f32 v[202:203], v[118:119], v[118:119] op_sel_hi:[0,1]
	v_cvt_pk_bf16_f32 v114, v114, v116
	v_mfma_f32_32x32x16_bf16 v[80:95], v[196:199], v[128:131], v[80:95]
	v_cvt_pk_bf16_f32 v115, v115, v117
	s_nop 1
	v_mfma_f32_32x32x16_bf16 v[48:63], v[170:173], v[112:115], v[48:63]
	v_add_u32_e32 v169, s16, v167
	ds_read_b128 v[116:119], v169 offset:16384
	ds_read_b128 v[170:173], v169 offset:20480
	ds_read_b128 v[188:191], v169 offset:24576
	ds_read_b128 v[192:195], v169 offset:28672
	v_exp_f32_e32 v120, v120
	v_exp_f32_e32 v121, v121
	v_exp_f32_e32 v122, v122
	v_exp_f32_e32 v123, v123
	v_exp_f32_e32 v124, v124
	v_mfma_f32_32x32x16_bf16 v[32:47], v[176:179], v[112:115], v[32:47]
	v_exp_f32_e32 v125, v125
	v_exp_f32_e32 v126, v126
	v_exp_f32_e32 v127, v127
	v_add_f32_e32 v197, v120, v121
	v_add_f32_e32 v199, v122, v123
	v_add_f32_e32 v205, v124, v125
	v_add_f32_e32 v207, v126, v127
	v_mfma_f32_32x32x16_bf16 v[16:31], v[180:183], v[112:115], v[16:31]
	v_cvt_pk_bf16_f32 v120, v120, v121
	v_cvt_pk_bf16_f32 v121, v122, v123
	v_cvt_pk_bf16_f32 v122, v124, v125
	v_cvt_pk_bf16_f32 v123, v126, v127
	v_mfma_f32_32x32x16_bf16 v[0:15], v[184:187], v[112:115], v[0:15]
	s_waitcnt lgkmcnt(0)
	v_mfma_f32_32x32x16_bf16 v[48:63], v[116:119], v[120:123], v[48:63]
	v_add_u32_e32 v174, s16, v166
	ds_read_b128 v[112:115], v174 offset:16384
	ds_read_b128 v[116:119], v174 offset:20480
	v_exp_f32_e32 v196, v96
	v_exp_f32_e32 v198, v97
	v_exp_f32_e32 v204, v98
	v_exp_f32_e32 v98, v100
	v_exp_f32_e32 v100, v101
	v_mfma_f32_32x32x16_bf16 v[32:47], v[170:173], v[120:123], v[32:47]
	ds_read_b128 v[124:127], v174 offset:24576
	ds_read_b128 v[170:173], v174 offset:28672
	v_exp_f32_e32 v206, v99
	v_exp_f32_e32 v200, v102
	v_exp_f32_e32 v202, v103
	v_add_f32_e32 v148, v98, v100
	v_cvt_pk_bf16_f32 v96, v196, v198
	v_cvt_pk_bf16_f32 v97, v204, v206
	v_mfma_f32_32x32x16_bf16 v[16:31], v[188:191], v[120:123], v[16:31]
	v_cvt_pk_bf16_f32 v98, v98, v100
	v_cvt_pk_bf16_f32 v99, v200, v202
	v_mfma_f32_32x32x16_bf16 v[0:15], v[192:195], v[120:123], v[0:15]
	v_add_u32_e32 v186, s16, v165
	s_waitcnt lgkmcnt(0)
; #define AT_SB() __builtin_amdgcn_sched_barrier(0)
; #define AT_QK(S0, S1) do { _Pragma("unroll") for (int i_ = 0; i_ < 16; ++i_) { S0[i_] = 0.f; S1[i_] = 0.f; } \
;         _Pragma("unroll") for (int s_ = 0; s_ < 4; ++s_) { S0 = __builtin_amdgcn_mfma_f32_32x32x16_bf16(kf[2 * s_], qf[s_], S0, 0, 0, 0); \
;             S1 = __builtin_amdgcn_mfma_f32_32x32x16_bf16(kf[2 * s_ + 1], qf[s_], S1, 0, 0, 0); } } while (0)
; #define AT_PV(VF, PF) do { _Pragma("unroll") for (int dt_ = 0; dt_ < 4; ++dt_) o[dt_] = __builtin_amdgcn_mfma_f32_32x32x16_bf16(VF[dt_], PF, o[dt_], 0, 0, 0); } while (0)
; #define AT_VLD(VF, VB, KS) do { _Pragma("unroll") for (int dt_ = 0; dt_ < 4; ++dt_) VF[dt_] = *(const LAS bf16x8*)((VB) + dt_ * 4096 + foff[KS]); } while (0)
; __device__ __forceinline__ void attn_unit(LAS unsigned char* lds, const bf16_t* __restrict__ DQ, const bf16_t* __restrict__ DK, const bf16_t* __restrict__ VT,
;                                           bf16_t* __restrict__ OD, const float* __restrict__ g_out, float lam, int b, int h, int qb) {
;     ...
;         AT_QK(b0, b1); AT_EXPBLK(a0, 0, pfc); AT_SB();
;         AT_VLD(vfb, vb0, 1); AT_PV(vfa, pfc); AT_EXPBLK(a0, 8, pfn); AT_SB();
;         AT_VLD(vfa, vb0, 2); AT_PV(vfb, pfn); AT_EXPBLK(a1, 0, pfc); AT_SB();
;         AT_VLD(vfb, vb0, 3); AT_PV(vfa, pfc); AT_EXPBLK(a1, 8, pfn); AT_SB();
;         AT_VLD(vfa, vb1, 0); AT_PV(vfb, pfn); AT_EXPBLK(b0, 0, pfc); AT_SB();
;         AT_VLD(vfb, vb1, 1); AT_PV(vfa, pfc); AT_EXPBLK(b0, 8, pfn); AT_SB();
;         AT_VLD(vfa, vb1, 2); AT_PV(vfb, pfn); AT_EXPBLK(b1, 0, pfc); AT_SB();
;         AT_VLD(vfb, vb1, 3); AT_PV(vfa, pfc); AT_EXPBLK(b1, 8, pfn); AT_SB();
;         asm volatile("s_waitcnt vmcnt(0)" ::: "memory");
;         __builtin_amdgcn_s_barrier(); asm volatile("" ::: "memory");
	v_mfma_f32_32x32x16_bf16 v[48:63], v[112:115], v[96:99], v[48:63]
	v_add_f32_e64 v112, v196, v198
	v_add_f32_e64 v113, v197, v199
	v_add_f32_e64 v114, v204, v206
	v_add_f32_e64 v115, v205, v207
	ds_read_b128 v[100:103], v186 offset:16384
	ds_read_b128 v[120:123], v186 offset:20480
	ds_read_b128 v[176:179], v186 offset:24576
	ds_read_b128 v[180:183], v186 offset:28672
	v_pk_add_f32 v[112:113], v[112:113], v[114:115]
	v_pk_add_f32 v[114:115], v[200:201], v[202:203]
	v_exp_f32_e32 v184, v105
	v_pk_add_f32 v[114:115], v[148:149], v[114:115]
	v_mfma_f32_32x32x16_bf16 v[32:47], v[116:119], v[96:99], v[32:47]
	v_exp_f32_e32 v148, v104
	v_exp_f32_e32 v106, v106
	v_exp_f32_e32 v116, v107
	v_exp_f32_e32 v149, v108
	v_exp_f32_e32 v185, v109
	v_exp_f32_e32 v107, v110
	v_exp_f32_e32 v117, v111
	v_mfma_f32_32x32x16_bf16 v[16:31], v[124:127], v[96:99], v[16:31]
	v_add_f32_e64 v104, v148, v184
	v_add_f32_e64 v105, v149, v185
	v_add_f32_e64 v118, v112, v114
	v_add_f32_e64 v119, v113, v115
	v_add_f32_e64 v108, v106, v116
	v_add_f32_e64 v109, v107, v117
	v_cvt_pk_bf16_f32 v107, v107, v117
	v_pk_add_f32 v[104:105], v[104:105], v[108:109]
	s_nop 0
	v_pk_add_f32 v[124:125], v[104:105], v[104:105] op_sel_hi:[0,1]
	v_mfma_f32_32x32x16_bf16 v[0:15], v[170:173], v[96:99], v[0:15]
	v_cvt_pk_bf16_f32 v104, v148, v184
	v_cvt_pk_bf16_f32 v105, v106, v116
	v_cvt_pk_bf16_f32 v106, v149, v185
	s_waitcnt lgkmcnt(0)
	s_nop 0
	v_mfma_f32_32x32x16_bf16 v[48:63], v[100:103], v[104:107], v[48:63]
	ds_read_b128 v[96:99], v208 offset:49152
	ds_read_b128 v[100:103], v208 offset:53248
	ds_read_b128 v[108:111], v208 offset:57344
	ds_read_b128 v[112:115], v208 offset:61440
	v_exp_f32_e32 v80, v80
	v_exp_f32_e32 v116, v81
	v_exp_f32_e32 v81, v82
	v_exp_f32_e32 v117, v83
	v_exp_f32_e32 v82, v84
	v_exp_f32_e32 v84, v85
	v_mfma_f32_32x32x16_bf16 v[32:47], v[120:123], v[104:107], v[32:47]
	v_exp_f32_e32 v83, v86
	v_exp_f32_e32 v85, v87
	v_pk_add_f32 v[86:87], v[80:81], v[116:117]
	v_cvt_pk_bf16_f32 v80, v80, v116
	v_pk_add_f32 v[120:121], v[86:87], v[86:87] op_sel_hi:[0,1]
	v_pk_add_f32 v[86:87], v[82:83], v[84:85]
	v_cvt_pk_bf16_f32 v81, v81, v117
	v_mfma_f32_32x32x16_bf16 v[16:31], v[176:179], v[104:107], v[16:31]
	v_cvt_pk_bf16_f32 v82, v82, v84
	v_cvt_pk_bf16_f32 v83, v83, v85
	v_add_f32_e64 v126, v118, v118
	v_add_f32_e64 v127, v118, v119
	v_add_f32_e64 v122, v86, v86
	v_add_f32_e64 v123, v86, v87
	v_mfma_f32_32x32x16_bf16 v[0:15], v[180:183], v[104:107], v[0:15]
	s_waitcnt lgkmcnt(0)
	v_mfma_f32_32x32x16_bf16 v[48:63], v[96:99], v[80:83], v[48:63]
	ds_read_b128 v[84:87], v169 offset:49152
	ds_read_b128 v[96:99], v169 offset:53248
	ds_read_b128 v[104:107], v169 offset:57344
	ds_read_b128 v[116:119], v169 offset:61440
	v_exp_f32_e32 v88, v88
	v_exp_f32_e32 v89, v89
	v_exp_f32_e32 v90, v90
	v_exp_f32_e32 v91, v91
	v_exp_f32_e32 v92, v92
	v_exp_f32_e32 v93, v93
	v_mfma_f32_32x32x16_bf16 v[32:47], v[100:103], v[80:83], v[32:47]
	v_exp_f32_e32 v94, v94
	v_exp_f32_e32 v95, v95
	v_add_f32_e32 v149, v88, v89
	v_add_f32_e32 v171, v90, v91
	v_add_f32_e32 v173, v92, v93
	v_add_f32_e32 v177, v94, v95
	v_cvt_pk_bf16_f32 v88, v88, v89
	v_mfma_f32_32x32x16_bf16 v[16:31], v[108:111], v[80:83], v[16:31]
	v_cvt_pk_bf16_f32 v89, v90, v91
	v_cvt_pk_bf16_f32 v90, v92, v93
	v_cvt_pk_bf16_f32 v91, v94, v95
	v_mfma_f32_32x32x16_bf16 v[0:15], v[112:115], v[80:83], v[0:15]
	s_waitcnt lgkmcnt(0)
	v_mfma_f32_32x32x16_bf16 v[48:63], v[84:87], v[88:91], v[48:63]
	v_exp_f32_e32 v148, v64
	v_exp_f32_e32 v170, v65
	v_exp_f32_e32 v172, v66
	v_exp_f32_e32 v176, v67
	v_exp_f32_e32 v124, v68
	v_exp_f32_e32 v126, v69
	v_exp_f32_e32 v120, v70
	v_mfma_f32_32x32x16_bf16 v[32:47], v[96:99], v[88:91], v[32:47]
	ds_read_b128 v[92:95], v174 offset:49152
	ds_read_b128 v[96:99], v174 offset:53248
	ds_read_b128 v[100:103], v174 offset:57344
	ds_read_b128 v[108:111], v174 offset:61440
	v_exp_f32_e32 v122, v71
	v_mfma_f32_32x32x16_bf16 v[16:31], v[104:107], v[88:91], v[16:31]
	v_cvt_pk_bf16_f32 v104, v148, v170
	v_cvt_pk_bf16_f32 v105, v172, v176
	v_cvt_pk_bf16_f32 v106, v124, v126
	v_cvt_pk_bf16_f32 v107, v120, v122
	v_mfma_f32_32x32x16_bf16 v[0:15], v[116:119], v[88:91], v[0:15]
	v_add_f32_e64 v88, v148, v170
	v_add_f32_e64 v89, v149, v171
	v_add_f32_e64 v90, v172, v176
	v_add_f32_e64 v91, v173, v177
	s_waitcnt lgkmcnt(0)
	v_mfma_f32_32x32x16_bf16 v[48:63], v[92:95], v[104:107], v[48:63]
	v_add_f32_e64 v88, v88, v90
	v_add_f32_e64 v89, v89, v91
	v_add_f32_e64 v90, v124, v126
	v_add_f32_e64 v91, v125, v127
	v_add_f32_e64 v92, v120, v122
	v_add_f32_e64 v93, v121, v123
	v_exp_f32_e32 v94, v73
	v_pk_add_f32 v[90:91], v[90:91], v[92:93]
	v_exp_f32_e32 v92, v72
	v_exp_f32_e32 v74, v74
	v_mfma_f32_32x32x16_bf16 v[32:47], v[96:99], v[104:107], v[32:47]
	v_exp_f32_e32 v96, v75
	v_exp_f32_e32 v93, v76
	v_exp_f32_e32 v95, v77
	v_exp_f32_e32 v75, v78
	v_exp_f32_e32 v97, v79
	ds_read_b128 v[84:87], v186 offset:49152
	ds_read_b128 v[80:83], v186 offset:53248
	ds_read_b128 v[68:71], v186 offset:57344
	ds_read_b128 v[64:67], v186 offset:61440
	v_pk_add_f32 v[76:77], v[92:93], v[94:95]
	v_mfma_f32_32x32x16_bf16 v[16:31], v[100:103], v[104:107], v[16:31]
	v_add_f32_e64 v78, v74, v96
	v_add_f32_e64 v79, v75, v97
	v_add_f32_e64 v72, v88, v90
	v_add_f32_e64 v73, v89, v91
	v_add_f32_e64 v76, v76, v78
	v_add_f32_e64 v77, v77, v79
	v_add_f32_e32 v72, v72, v73
	v_add_f32_e32 v73, v76, v77
	v_add_f32_e32 v149, v73, v72
	v_cvt_pk_bf16_f32 v72, v92, v94
	v_mfma_f32_32x32x16_bf16 v[0:15], v[108:111], v[104:107], v[0:15]
	v_cvt_pk_bf16_f32 v73, v74, v96
	v_cvt_pk_bf16_f32 v74, v93, v95
	v_cvt_pk_bf16_f32 v75, v75, v97
	s_waitcnt vmcnt(0)
	s_barrier
	s_add_i32 s8, s8, 2
	s_add_i32 s15, s15, -1
	s_add_i32 s6, s6, 0x10000
	s_cmp_eq_u32 s15, 0
	s_cbranch_scc0 .LBB0_369
	s_branch .LBB0_371

; #define PG8_STAGE(bufoff, gbase, voff) do { _Pragma("unroll") for (int _i = 0; _i < 2; ++_i) \
;         __builtin_amdgcn_global_load_lds((const unsigned*)((const char*)(gbase) + (voff)[_i]), (LAS unsigned*)(lds + (bufoff) + ldsw + _i * 8192), 16, 0, 0); } while (0)
; #define PG8_LDA(dst, b, h) do { _Pragma("unroll") for (int m = 0; m < 4; ++m) _Pragma("unroll") for (int k = 0; k < 2; ++k) dst[m][k] = *(const LAS bf16x8*)(lds + PG8_SA(b, h) + aoff + m * 2048 + k * 1024); } while (0)
; #define PG8_LDB(dst, b, h) do { _Pragma("unroll") for (int n = 0; n < 2; ++n) _Pragma("unroll") for (int k = 0; k < 2; ++k) dst[n][k] = *(const LAS bf16x8*)(lds + PG8_SB(b, h) + boff + n * 2048 + k * 1024); } while (0)
; #define PG8_MMA(ai, bj, At, Bt) do { __builtin_amdgcn_s_setprio(1); _Pragma("unroll") for (int m = 0; m < 4; ++m) _Pragma("unroll") for (int n = 0; n < 2; ++n) _Pragma("unroll") for (int k = 0; k < 2; ++k) \
;         acc[ai][bj][m][n] = __builtin_amdgcn_mfma_f32_16x16x32_bf16(Bt[n][k], At[m][k], acc[ai][bj][m][n], 0, 0, 0); __builtin_amdgcn_s_setprio(0); } while (0)
; #define PG8_WAIT_V(n) asm volatile("s_waitcnt vmcnt(" #n ")" ::: "memory")
; #define PG8_WAIT_L(n) asm volatile("s_waitcnt lgkmcnt(" #n ")" ::: "memory")
; #define PG8_BAR __builtin_amdgcn_s_barrier()
; template <class Epi, class Sched, bool ALIGN_EPI, bool SP2>
; __device__ __forceinline__ void gemm_phase(LAS unsigned char* lds, const Gemm g, const Sched& S, const Epi& E) {
;     ...
;         for (int t = 0; t < nt; t += 2) {
;             const bool last = (t == nt - 2);
;             const char* a1 = cA + (size_t)(t + 1) * kstep;
;             const char* a2 = last ? nA : cA + (size_t)(t + 2) * kstep; const char* b2 = last ? nB : cB + (size_t)(t + 2) * kstep;
;             const char* a3 = a2 + kstep; const char* b3 = b2 + kstep;
;             if constexpr (SP2) {
;             PG8_LDB(B0, 0, 0); PG8_LDB(B1, 0, 1); PG8_SCHED; PG8_LDA(At, 0, 0); PG8_STAGE(PG8_SA(1, 1), a1 + hstep, voffA);
;             PG8_WAIT_V(8); PG8_WAIT_L(0); PG8_BAR; PG8_MMA(0, 0, At, B0); PG8_MMA(0, 1, At, B1); PG8_BAR; PG8_SCHED;
;             PG8_LDA(At, 0, 1); PG8_STAGE(PG8_SB(0, 0), b2, voffB); PG8_STAGE(PG8_SB(0, 1), b2 + hstep, voffB); PG8_STAGE(PG8_SA(0, 0), a2, voffA);
;             PG8_WAIT_V(8); PG8_WAIT_L(0); PG8_BAR; PG8_MMA(1, 0, At, B0); PG8_MMA(1, 1, At, B1); PG8_BAR; PG8_SCHED;
.LBB0_468:
	v_add_u32_e32 v140, s62, v187
	v_add_u32_e32 v156, s63, v187
	ds_read_b128 v[128:131], v140
	ds_read_b128 v[132:135], v140 offset:1024
	ds_read_b128 v[136:139], v140 offset:2048
	ds_read_b128 v[140:143], v140 offset:3072
	ds_read_b128 v[144:147], v156
	ds_read_b128 v[148:151], v156 offset:1024
	ds_read_b128 v[152:155], v156 offset:2048
	ds_read_b128 v[156:159], v156 offset:3072
	s_add_u32 s34, s28, 0xfffe0080
	s_addc_u32 s35, s29, -1
	s_cmp_eq_u32 s58, 4
	s_cselect_b32 s37, s21, s35
	s_cselect_b32 s36, s50, s34
	s_cselect_b32 s35, s23, s57
	s_cselect_b32 s34, s51, s56
	s_add_i32 m0, s43, 0xc000
	ds_read_b128 v[160:163], v188
	ds_read_b128 v[190:193], v188 offset:1024
	ds_read_b128 v[194:197], v188 offset:2048
	ds_read_b128 v[198:201], v188 offset:3072
	ds_read_b128 v[202:205], v188 offset:4096
	ds_read_b128 v[206:209], v188 offset:5120
	ds_read_b128 v[210:213], v188 offset:6144
	ds_read_b128 v[214:217], v188 offset:7168
	global_load_lds_dwordx4 v176, s[28:29]
	s_add_i32 m0, s43, 0xe000
	s_nop 0
	global_load_lds_dwordx4 v178, s[28:29]
	s_waitcnt vmcnt(8)
	s_waitcnt lgkmcnt(0)
	s_barrier
	s_setprio 1
	s_waitcnt lgkmcnt(0)
	v_mfma_f32_16x16x32_bf16 v[124:127], v[128:131], v[160:163], v[124:127]
	v_mfma_f32_16x16x32_bf16 v[120:123], v[136:139], v[160:163], v[120:123]
	v_mfma_f32_16x16x32_bf16 v[116:119], v[128:131], v[194:197], v[116:119]
	v_mfma_f32_16x16x32_bf16 v[112:115], v[136:139], v[194:197], v[112:115]
	v_mfma_f32_16x16x32_bf16 v[108:111], v[128:131], v[202:205], v[108:111]
	v_mfma_f32_16x16x32_bf16 v[104:107], v[136:139], v[202:205], v[104:107]
	v_mfma_f32_16x16x32_bf16 v[100:103], v[128:131], v[210:213], v[100:103]
	v_mfma_f32_16x16x32_bf16 v[96:99], v[136:139], v[210:213], v[96:99]
	v_mfma_f32_16x16x32_bf16 v[124:127], v[132:135], v[190:193], v[124:127]
	v_mfma_f32_16x16x32_bf16 v[120:123], v[140:143], v[190:193], v[120:123]
	v_mfma_f32_16x16x32_bf16 v[116:119], v[132:135], v[198:201], v[116:119]
	v_mfma_f32_16x16x32_bf16 v[112:115], v[140:143], v[198:201], v[112:115]
	v_mfma_f32_16x16x32_bf16 v[108:111], v[132:135], v[206:209], v[108:111]
	v_mfma_f32_16x16x32_bf16 v[104:107], v[140:143], v[206:209], v[104:107]
	v_mfma_f32_16x16x32_bf16 v[100:103], v[132:135], v[214:217], v[100:103]
	v_mfma_f32_16x16x32_bf16 v[96:99], v[140:143], v[214:217], v[96:99]
	s_setprio 0
	s_setprio 1
	v_mfma_f32_16x16x32_bf16 v[92:95], v[144:147], v[160:163], v[92:95]
	v_mfma_f32_16x16x32_bf16 v[88:91], v[152:155], v[160:163], v[88:91]
	v_mfma_f32_16x16x32_bf16 v[84:87], v[144:147], v[194:197], v[84:87]
	v_mfma_f32_16x16x32_bf16 v[80:83], v[152:155], v[194:197], v[80:83]
	v_mfma_f32_16x16x32_bf16 v[76:79], v[144:147], v[202:205], v[76:79]
	v_mfma_f32_16x16x32_bf16 v[72:75], v[152:155], v[202:205], v[72:75]
	v_mfma_f32_16x16x32_bf16 v[68:71], v[144:147], v[210:213], v[68:71]
	v_mfma_f32_16x16x32_bf16 v[64:67], v[152:155], v[210:213], v[64:67]
	v_mfma_f32_16x16x32_bf16 v[92:95], v[148:151], v[190:193], v[92:95]
	v_mfma_f32_16x16x32_bf16 v[88:91], v[156:159], v[190:193], v[88:91]
	v_mfma_f32_16x16x32_bf16 v[84:87], v[148:151], v[198:201], v[84:87]
	v_mfma_f32_16x16x32_bf16 v[80:83], v[156:159], v[198:201], v[80:83]
	v_mfma_f32_16x16x32_bf16 v[76:79], v[148:151], v[206:209], v[76:79]
	v_mfma_f32_16x16x32_bf16 v[72:75], v[156:159], v[206:209], v[72:75]
	v_mfma_f32_16x16x32_bf16 v[68:71], v[148:151], v[214:217], v[68:71]
	v_mfma_f32_16x16x32_bf16 v[64:67], v[156:159], v[214:217], v[64:67]
	s_setprio 0
	s_barrier
	s_add_i32 s59, s62, s42
	s_mov_b32 m0, s59
	ds_read_b128 v[160:163], v188 offset:16384
	ds_read_b128 v[190:193], v188 offset:17408
	ds_read_b128 v[194:197], v188 offset:18432
	ds_read_b128 v[198:201], v188 offset:19456
	ds_read_b128 v[202:205], v188 offset:20480
	ds_read_b128 v[206:209], v188 offset:21504
	ds_read_b128 v[210:213], v188 offset:22528
	ds_read_b128 v[214:217], v188 offset:23552
	global_load_lds_dwordx4 v166, s[34:35]
	s_add_i32 m0, s59, 0x2000
	s_add_u32 s72, s34, 0x20000
	s_addc_u32 s73, s35, 0
	s_add_i32 s59, s63, s42
	global_load_lds_dwordx4 v170, s[34:35]
	s_mov_b32 m0, s59
	s_nop 0
	global_load_lds_dwordx4 v166, s[72:73]
	s_add_i32 m0, s59, 0x2000
	s_nop 0
	global_load_lds_dwordx4 v170, s[72:73]
	s_mov_b32 m0, s43
	s_nop 0
	global_load_lds_dwordx4 v164, s[36:37]
	s_mov_b32 m0, s44
	s_nop 0
	global_load_lds_dwordx4 v168, s[36:37]
	s_waitcnt vmcnt(8)
	s_waitcnt lgkmcnt(0)
	s_barrier
	s_setprio 1
	s_waitcnt lgkmcnt(0)
	v_mfma_f32_16x16x32_bf16 v[60:63], v[128:131], v[160:163], v[60:63]
	v_mfma_f32_16x16x32_bf16 v[56:59], v[136:139], v[160:163], v[56:59]
	v_mfma_f32_16x16x32_bf16 v[52:55], v[128:131], v[194:197], v[52:55]
	v_mfma_f32_16x16x32_bf16 v[48:51], v[136:139], v[194:197], v[48:51]
	v_mfma_f32_16x16x32_bf16 v[44:47], v[128:131], v[202:205], v[44:47]
	v_mfma_f32_16x16x32_bf16 v[40:43], v[136:139], v[202:205], v[40:43]
	v_mfma_f32_16x16x32_bf16 v[36:39], v[128:131], v[210:213], v[36:39]
	v_mfma_f32_16x16x32_bf16 v[32:35], v[136:139], v[210:213], v[32:35]
	v_mfma_f32_16x16x32_bf16 v[60:63], v[132:135], v[190:193], v[60:63]
	v_mfma_f32_16x16x32_bf16 v[56:59], v[140:143], v[190:193], v[56:59]
	v_mfma_f32_16x16x32_bf16 v[52:55], v[132:135], v[198:201], v[52:55]
	v_mfma_f32_16x16x32_bf16 v[48:51], v[140:143], v[198:201], v[48:51]
	v_mfma_f32_16x16x32_bf16 v[44:47], v[132:135], v[206:209], v[44:47]
	v_mfma_f32_16x16x32_bf16 v[40:43], v[140:143], v[206:209], v[40:43]
	v_mfma_f32_16x16x32_bf16 v[36:39], v[132:135], v[214:217], v[36:39]
	v_mfma_f32_16x16x32_bf16 v[32:35], v[140:143], v[214:217], v[32:35]
	s_setprio 0
	s_setprio 1
	v_mfma_f32_16x16x32_bf16 v[28:31], v[144:147], v[160:163], v[28:31]
	v_mfma_f32_16x16x32_bf16 v[24:27], v[152:155], v[160:163], v[24:27]
	v_mfma_f32_16x16x32_bf16 v[20:23], v[144:147], v[194:197], v[20:23]
	v_mfma_f32_16x16x32_bf16 v[16:19], v[152:155], v[194:197], v[16:19]
	v_mfma_f32_16x16x32_bf16 v[12:15], v[144:147], v[202:205], v[12:15]
	v_mfma_f32_16x16x32_bf16 v[8:11], v[152:155], v[202:205], v[8:11]
	v_mfma_f32_16x16x32_bf16 v[4:7], v[144:147], v[210:213], v[4:7]
	v_mfma_f32_16x16x32_bf16 v[0:3], v[152:155], v[210:213], v[0:3]
	v_mfma_f32_16x16x32_bf16 v[28:31], v[148:151], v[190:193], v[28:31]
	v_mfma_f32_16x16x32_bf16 v[24:27], v[156:159], v[190:193], v[24:27]
	v_mfma_f32_16x16x32_bf16 v[20:23], v[148:151], v[198:201], v[20:23]
	v_mfma_f32_16x16x32_bf16 v[16:19], v[156:159], v[198:201], v[16:19]
	v_mfma_f32_16x16x32_bf16 v[12:15], v[148:151], v[206:209], v[12:15]
	v_mfma_f32_16x16x32_bf16 v[8:11], v[156:159], v[206:209], v[8:11]
	v_mfma_f32_16x16x32_bf16 v[4:7], v[148:151], v[214:217], v[4:7]
	v_mfma_f32_16x16x32_bf16 v[0:3], v[156:159], v[214:217], v[0:3]
	s_setprio 0
	s_barrier
; #define PG8_STAGE(bufoff, gbase, voff) do { _Pragma("unroll") for (int _i = 0; _i < 2; ++_i) \
;         __builtin_amdgcn_global_load_lds((const unsigned*)((const char*)(gbase) + (voff)[_i]), (LAS unsigned*)(lds + (bufoff) + ldsw + _i * 8192), 16, 0, 0); } while (0)
; #define PG8_LDA(dst, b, h) do { _Pragma("unroll") for (int m = 0; m < 4; ++m) _Pragma("unroll") for (int k = 0; k < 2; ++k) dst[m][k] = *(const LAS bf16x8*)(lds + PG8_SA(b, h) + aoff + m * 2048 + k * 1024); } while (0)
; #define PG8_LDB(dst, b, h) do { _Pragma("unroll") for (int n = 0; n < 2; ++n) _Pragma("unroll") for (int k = 0; k < 2; ++k) dst[n][k] = *(const LAS bf16x8*)(lds + PG8_SB(b, h) + boff + n * 2048 + k * 1024); } while (0)
; #define PG8_MMA(ai, bj, At, Bt) do { __builtin_amdgcn_s_setprio(1); _Pragma("unroll") for (int m = 0; m < 4; ++m) _Pragma("unroll") for (int n = 0; n < 2; ++n) _Pragma("unroll") for (int k = 0; k < 2; ++k) \
;         acc[ai][bj][m][n] = __builtin_amdgcn_mfma_f32_16x16x32_bf16(Bt[n][k], At[m][k], acc[ai][bj][m][n], 0, 0, 0); __builtin_amdgcn_s_setprio(0); } while (0)
; #define PG8_WAIT_V(n) asm volatile("s_waitcnt vmcnt(" #n ")" ::: "memory")
; #define PG8_WAIT_L(n) asm volatile("s_waitcnt lgkmcnt(" #n ")" ::: "memory")
; #define PG8_BAR __builtin_amdgcn_s_barrier()
; #define PG8_SCHED __builtin_amdgcn_sched_barrier(0)
; template <class Epi, class Sched, bool ALIGN_EPI, bool SP2>
; __device__ __forceinline__ void gemm_phase(LAS unsigned char* lds, const Gemm g, const Sched& S, const Epi& E) {
;     ...
;             PG8_LDB(B0, 1, 0); PG8_LDB(B1, 1, 1); PG8_SCHED; PG8_LDA(At, 1, 0); PG8_STAGE(PG8_SA(0, 1), a2 + hstep, voffA);
;             PG8_WAIT_V(8); PG8_WAIT_L(0); PG8_BAR; PG8_MMA(0, 0, At, B0); PG8_MMA(0, 1, At, B1); PG8_BAR; PG8_SCHED;
;             PG8_LDA(At, 1, 1); PG8_STAGE(PG8_SB(1, 0), b3, voffB); PG8_STAGE(PG8_SB(1, 1), b3 + hstep, voffB); PG8_STAGE(PG8_SA(1, 0), a3, voffA);
;             PG8_WAIT_V(8); PG8_WAIT_L(0); PG8_BAR; PG8_MMA(1, 0, At, B0); PG8_MMA(1, 1, At, B1); PG8_BAR; PG8_SCHED;
	s_add_i32 s59, 0, 0x18000
	s_add_i32 s71, 0, 0x1c000
	v_add_u32_e32 v140, s59, v187
	v_add_u32_e32 v156, s71, v187
	ds_read_b128 v[128:131], v140
	ds_read_b128 v[132:135], v140 offset:1024
	ds_read_b128 v[136:139], v140 offset:2048
	ds_read_b128 v[140:143], v140 offset:3072
	ds_read_b128 v[144:147], v156
	ds_read_b128 v[148:151], v156 offset:1024
	ds_read_b128 v[152:155], v156 offset:2048
	ds_read_b128 v[156:159], v156 offset:3072
	s_add_u32 s36, s36, 0x20000
	s_addc_u32 s37, s37, 0
	s_mov_b32 m0, s45
	ds_read_b128 v[160:163], v188 offset:32768
	ds_read_b128 v[190:193], v188 offset:33792
	ds_read_b128 v[194:197], v188 offset:34816
	ds_read_b128 v[198:201], v188 offset:35840
	ds_read_b128 v[202:205], v188 offset:36864
	ds_read_b128 v[206:209], v188 offset:37888
	ds_read_b128 v[210:213], v188 offset:38912
	ds_read_b128 v[214:217], v188 offset:39936
	global_load_lds_dwordx4 v164, s[36:37]
	s_mov_b32 m0, s46
	s_nop 0
	global_load_lds_dwordx4 v168, s[36:37]
	s_waitcnt vmcnt(8)
	s_waitcnt lgkmcnt(0)
	s_barrier
	s_setprio 1
	s_waitcnt lgkmcnt(0)
	v_mfma_f32_16x16x32_bf16 v[124:127], v[128:131], v[160:163], v[124:127]
	v_mfma_f32_16x16x32_bf16 v[120:123], v[136:139], v[160:163], v[120:123]
	v_mfma_f32_16x16x32_bf16 v[116:119], v[128:131], v[194:197], v[116:119]
	v_mfma_f32_16x16x32_bf16 v[112:115], v[136:139], v[194:197], v[112:115]
	v_mfma_f32_16x16x32_bf16 v[108:111], v[128:131], v[202:205], v[108:111]
	v_mfma_f32_16x16x32_bf16 v[104:107], v[136:139], v[202:205], v[104:107]
	v_mfma_f32_16x16x32_bf16 v[100:103], v[128:131], v[210:213], v[100:103]
	v_mfma_f32_16x16x32_bf16 v[96:99], v[136:139], v[210:213], v[96:99]
	v_mfma_f32_16x16x32_bf16 v[124:127], v[132:135], v[190:193], v[124:127]
	v_mfma_f32_16x16x32_bf16 v[120:123], v[140:143], v[190:193], v[120:123]
	v_mfma_f32_16x16x32_bf16 v[116:119], v[132:135], v[198:201], v[116:119]
	v_mfma_f32_16x16x32_bf16 v[112:115], v[140:143], v[198:201], v[112:115]
	v_mfma_f32_16x16x32_bf16 v[108:111], v[132:135], v[206:209], v[108:111]
	v_mfma_f32_16x16x32_bf16 v[104:107], v[140:143], v[206:209], v[104:107]
	v_mfma_f32_16x16x32_bf16 v[100:103], v[132:135], v[214:217], v[100:103]
	v_mfma_f32_16x16x32_bf16 v[96:99], v[140:143], v[214:217], v[96:99]
	s_setprio 0
	s_setprio 1
	v_mfma_f32_16x16x32_bf16 v[92:95], v[144:147], v[160:163], v[92:95]
	v_mfma_f32_16x16x32_bf16 v[88:91], v[152:155], v[160:163], v[88:91]
	v_mfma_f32_16x16x32_bf16 v[84:87], v[144:147], v[194:197], v[84:87]
	v_mfma_f32_16x16x32_bf16 v[80:83], v[152:155], v[194:197], v[80:83]
	v_mfma_f32_16x16x32_bf16 v[76:79], v[144:147], v[202:205], v[76:79]
	v_mfma_f32_16x16x32_bf16 v[72:75], v[152:155], v[202:205], v[72:75]
	v_mfma_f32_16x16x32_bf16 v[68:71], v[144:147], v[210:213], v[68:71]
	v_mfma_f32_16x16x32_bf16 v[64:67], v[152:155], v[210:213], v[64:67]
	v_mfma_f32_16x16x32_bf16 v[92:95], v[148:151], v[190:193], v[92:95]
	v_mfma_f32_16x16x32_bf16 v[88:91], v[156:159], v[190:193], v[88:91]
	v_mfma_f32_16x16x32_bf16 v[84:87], v[148:151], v[198:201], v[84:87]
	v_mfma_f32_16x16x32_bf16 v[80:83], v[156:159], v[198:201], v[80:83]
	v_mfma_f32_16x16x32_bf16 v[76:79], v[148:151], v[206:209], v[76:79]
	v_mfma_f32_16x16x32_bf16 v[72:75], v[156:159], v[206:209], v[72:75]
	v_mfma_f32_16x16x32_bf16 v[68:71], v[148:151], v[214:217], v[68:71]
	v_mfma_f32_16x16x32_bf16 v[64:67], v[156:159], v[214:217], v[64:67]
	s_setprio 0
	s_barrier
	s_add_u32 s100, s36, 0xfffe0080
	s_addc_u32 s101, s37, -1
	s_add_u32 s98, s34, 0x80
	s_addc_u32 s99, s35, 0
	s_add_i32 s36, s59, s42
	s_mov_b32 m0, s36
	ds_read_b128 v[160:163], v188 offset:49152
	ds_read_b128 v[190:193], v188 offset:50176
	ds_read_b128 v[194:197], v188 offset:51200
	ds_read_b128 v[198:201], v188 offset:52224
	ds_read_b128 v[202:205], v188 offset:53248
	ds_read_b128 v[206:209], v188 offset:54272
	ds_read_b128 v[210:213], v188 offset:55296
	ds_read_b128 v[214:217], v188 offset:56320
	global_load_lds_dwordx4 v166, s[98:99]
	s_add_i32 m0, s36, 0x2000
	s_add_u32 s34, s34, 0x20080
	s_addc_u32 s35, s35, 0
	s_add_i32 s36, s71, s42
	global_load_lds_dwordx4 v170, s[98:99]
	s_mov_b32 m0, s36
	s_nop 0
	global_load_lds_dwordx4 v166, s[34:35]
	s_add_i32 m0, s36, 0x2000
	s_nop 0
	global_load_lds_dwordx4 v170, s[34:35]
	s_mov_b32 m0, s54
	s_nop 0
	global_load_lds_dwordx4 v164, s[100:101]
	s_mov_b32 m0, s55
	s_nop 0
	global_load_lds_dwordx4 v168, s[100:101]
	s_waitcnt vmcnt(8)
	s_waitcnt lgkmcnt(0)
	s_barrier
	s_setprio 1
	s_waitcnt lgkmcnt(0)
	v_mfma_f32_16x16x32_bf16 v[60:63], v[128:131], v[160:163], v[60:63]
	v_mfma_f32_16x16x32_bf16 v[56:59], v[136:139], v[160:163], v[56:59]
	v_mfma_f32_16x16x32_bf16 v[52:55], v[128:131], v[194:197], v[52:55]
	v_mfma_f32_16x16x32_bf16 v[48:51], v[136:139], v[194:197], v[48:51]
	v_mfma_f32_16x16x32_bf16 v[44:47], v[128:131], v[202:205], v[44:47]
	v_mfma_f32_16x16x32_bf16 v[40:43], v[136:139], v[202:205], v[40:43]
	v_mfma_f32_16x16x32_bf16 v[36:39], v[128:131], v[210:213], v[36:39]
	v_mfma_f32_16x16x32_bf16 v[32:35], v[136:139], v[210:213], v[32:35]
	v_mfma_f32_16x16x32_bf16 v[60:63], v[132:135], v[190:193], v[60:63]
	v_mfma_f32_16x16x32_bf16 v[56:59], v[140:143], v[190:193], v[56:59]
	v_mfma_f32_16x16x32_bf16 v[52:55], v[132:135], v[198:201], v[52:55]
	v_mfma_f32_16x16x32_bf16 v[48:51], v[140:143], v[198:201], v[48:51]
	v_mfma_f32_16x16x32_bf16 v[44:47], v[132:135], v[206:209], v[44:47]
	v_mfma_f32_16x16x32_bf16 v[40:43], v[140:143], v[206:209], v[40:43]
	v_mfma_f32_16x16x32_bf16 v[36:39], v[132:135], v[214:217], v[36:39]
	v_mfma_f32_16x16x32_bf16 v[32:35], v[140:143], v[214:217], v[32:35]
	s_setprio 0
	s_setprio 1
	v_mfma_f32_16x16x32_bf16 v[28:31], v[144:147], v[160:163], v[28:31]
	v_mfma_f32_16x16x32_bf16 v[24:27], v[152:155], v[160:163], v[24:27]
	v_mfma_f32_16x16x32_bf16 v[20:23], v[144:147], v[194:197], v[20:23]
	v_mfma_f32_16x16x32_bf16 v[16:19], v[152:155], v[194:197], v[16:19]
	v_mfma_f32_16x16x32_bf16 v[12:15], v[144:147], v[202:205], v[12:15]
	v_mfma_f32_16x16x32_bf16 v[8:11], v[152:155], v[202:205], v[8:11]
	v_mfma_f32_16x16x32_bf16 v[4:7], v[144:147], v[210:213], v[4:7]
	v_mfma_f32_16x16x32_bf16 v[0:3], v[152:155], v[210:213], v[0:3]
	v_mfma_f32_16x16x32_bf16 v[28:31], v[148:151], v[190:193], v[28:31]
	v_mfma_f32_16x16x32_bf16 v[24:27], v[156:159], v[190:193], v[24:27]
	v_mfma_f32_16x16x32_bf16 v[20:23], v[148:151], v[198:201], v[20:23]
	v_mfma_f32_16x16x32_bf16 v[16:19], v[156:159], v[198:201], v[16:19]
	v_mfma_f32_16x16x32_bf16 v[12:15], v[148:151], v[206:209], v[12:15]
	v_mfma_f32_16x16x32_bf16 v[8:11], v[156:159], v[206:209], v[8:11]
	v_mfma_f32_16x16x32_bf16 v[4:7], v[148:151], v[214:217], v[4:7]
	v_mfma_f32_16x16x32_bf16 v[0:3], v[156:159], v[214:217], v[0:3]
	s_setprio 0
	s_barrier
	s_add_i32 s58, s58, 2
	s_add_u32 s28, s28, 0x100
	s_addc_u32 s29, s29, 0
	s_add_u32 s56, s56, 0x100
	s_addc_u32 s57, s57, 0
	s_cmp_gt_u32 s58, 5
	s_cbranch_scc0 .LBB0_468
	s_and_b64 vcc, exec, s[18:19]
	s_cbranch_vccz .LBB0_471
	s_barrier

; #define PG8_STAGE(bufoff, gbase, voff) do { _Pragma("unroll") for (int _i = 0; _i < 2; ++_i) \
;         __builtin_amdgcn_global_load_lds((const unsigned*)((const char*)(gbase) + (voff)[_i]), (LAS unsigned*)(lds + (bufoff) + ldsw + _i * 8192), 16, 0, 0); } while (0)
; #define PG8_LDA(dst, b, h) do { _Pragma("unroll") for (int m = 0; m < 4; ++m) _Pragma("unroll") for (int k = 0; k < 2; ++k) dst[m][k] = *(const LAS bf16x8*)(lds + PG8_SA(b, h) + aoff + m * 2048 + k * 1024); } while (0)
; #define PG8_LDB(dst, b, h) do { _Pragma("unroll") for (int n = 0; n < 2; ++n) _Pragma("unroll") for (int k = 0; k < 2; ++k) dst[n][k] = *(const LAS bf16x8*)(lds + PG8_SB(b, h) + boff + n * 2048 + k * 1024); } while (0)
; #define PG8_MMA(ai, bj, At, Bt) do { __builtin_amdgcn_s_setprio(1); _Pragma("unroll") for (int m = 0; m < 4; ++m) _Pragma("unroll") for (int n = 0; n < 2; ++n) _Pragma("unroll") for (int k = 0; k < 2; ++k) \
;         acc[ai][bj][m][n] = __builtin_amdgcn_mfma_f32_16x16x32_bf16(Bt[n][k], At[m][k], acc[ai][bj][m][n], 0, 0, 0); __builtin_amdgcn_s_setprio(0); } while (0)
; #define PG8_WAIT_V(n) asm volatile("s_waitcnt vmcnt(" #n ")" ::: "memory")
; #define PG8_WAIT_L(n) asm volatile("s_waitcnt lgkmcnt(" #n ")" ::: "memory")
; #define PG8_BAR __builtin_amdgcn_s_barrier()
; template <class Epi, class Sched, bool ALIGN_EPI, bool SP2>
; __device__ __forceinline__ void gemm_phase(LAS unsigned char* lds, const Gemm g, const Sched& S, const Epi& E) {
;     ...
;         for (int t = 0; t < nt; t += 2) {
;             const bool last = (t == nt - 2);
;             const char* a1 = cA + (size_t)(t + 1) * kstep;
;             const char* a2 = last ? nA : cA + (size_t)(t + 2) * kstep; const char* b2 = last ? nB : cB + (size_t)(t + 2) * kstep;
;             const char* a3 = a2 + kstep; const char* b3 = b2 + kstep;
;             if constexpr (SP2) {
;             PG8_LDB(B0, 0, 0); PG8_LDB(B1, 0, 1); PG8_SCHED; PG8_LDA(At, 0, 0); PG8_STAGE(PG8_SA(1, 1), a1 + hstep, voffA);
;             PG8_WAIT_V(8); PG8_WAIT_L(0); PG8_BAR; PG8_MMA(0, 0, At, B0); PG8_MMA(0, 1, At, B1); PG8_BAR; PG8_SCHED;
;             PG8_LDA(At, 0, 1); PG8_STAGE(PG8_SB(0, 0), b2, voffB); PG8_STAGE(PG8_SB(0, 1), b2 + hstep, voffB); PG8_STAGE(PG8_SA(0, 0), a2, voffA);
;             PG8_WAIT_V(8); PG8_WAIT_L(0); PG8_BAR; PG8_MMA(1, 0, At, B0); PG8_MMA(1, 1, At, B1); PG8_BAR; PG8_SCHED;
.LBB0_553:
	ds_read_b128 v[128:131], v167
	ds_read_b128 v[132:135], v167 offset:1024
	ds_read_b128 v[136:139], v167 offset:2048
	ds_read_b128 v[140:143], v167 offset:3072
	ds_read_b128 v[160:163], v168
	ds_read_b128 v[170:173], v168 offset:1024
	ds_read_b128 v[176:179], v168 offset:2048
	ds_read_b128 v[180:183], v168 offset:3072
	s_add_u32 s36, s34, 0xfffc0080
	s_addc_u32 s37, s35, -1
	s_cmp_eq_u32 s59, 12
	s_cselect_b32 s39, s23, s37
	s_cselect_b32 s38, s51, s36
	s_cselect_b32 s37, s25, s58
	s_cselect_b32 s36, s56, s57
	s_add_i32 m0, s31, 0xc000
	ds_read_b128 v[184:187], v169
	ds_read_b128 v[188:191], v169 offset:1024
	ds_read_b128 v[192:195], v169 offset:2048
	ds_read_b128 v[196:199], v169 offset:3072
	ds_read_b128 v[200:203], v169 offset:4096
	ds_read_b128 v[204:207], v169 offset:5120
	ds_read_b128 v[208:211], v169 offset:6144
	ds_read_b128 v[212:215], v169 offset:7168
	global_load_lds_dwordx4 v152, s[34:35]
	s_add_i32 m0, s31, 0xe000
	s_nop 0
	global_load_lds_dwordx4 v154, s[34:35]
	s_waitcnt vmcnt(8)
	s_waitcnt lgkmcnt(0)
	s_barrier
	s_setprio 1
	s_waitcnt lgkmcnt(0)
	v_mfma_f32_16x16x32_bf16 v[124:127], v[128:131], v[184:187], v[124:127]
	v_mfma_f32_16x16x32_bf16 v[120:123], v[136:139], v[184:187], v[120:123]
	v_mfma_f32_16x16x32_bf16 v[108:111], v[128:131], v[192:195], v[108:111]
	v_mfma_f32_16x16x32_bf16 v[104:107], v[136:139], v[192:195], v[104:107]
	v_mfma_f32_16x16x32_bf16 v[92:95], v[128:131], v[200:203], v[92:95]
	v_mfma_f32_16x16x32_bf16 v[88:91], v[136:139], v[200:203], v[88:91]
	v_mfma_f32_16x16x32_bf16 v[76:79], v[128:131], v[208:211], v[76:79]
	v_mfma_f32_16x16x32_bf16 v[72:75], v[136:139], v[208:211], v[72:75]
	v_mfma_f32_16x16x32_bf16 v[124:127], v[132:135], v[188:191], v[124:127]
	v_mfma_f32_16x16x32_bf16 v[120:123], v[140:143], v[188:191], v[120:123]
	v_mfma_f32_16x16x32_bf16 v[108:111], v[132:135], v[196:199], v[108:111]
	v_mfma_f32_16x16x32_bf16 v[104:107], v[140:143], v[196:199], v[104:107]
	v_mfma_f32_16x16x32_bf16 v[92:95], v[132:135], v[204:207], v[92:95]
	v_mfma_f32_16x16x32_bf16 v[88:91], v[140:143], v[204:207], v[88:91]
	v_mfma_f32_16x16x32_bf16 v[76:79], v[132:135], v[212:215], v[76:79]
	v_mfma_f32_16x16x32_bf16 v[72:75], v[140:143], v[212:215], v[72:75]
	s_setprio 0
	s_setprio 1
	v_mfma_f32_16x16x32_bf16 v[116:119], v[160:163], v[184:187], v[116:119]
	v_mfma_f32_16x16x32_bf16 v[112:115], v[176:179], v[184:187], v[112:115]
	v_mfma_f32_16x16x32_bf16 v[100:103], v[160:163], v[192:195], v[100:103]
	v_mfma_f32_16x16x32_bf16 v[96:99], v[176:179], v[192:195], v[96:99]
	v_mfma_f32_16x16x32_bf16 v[84:87], v[160:163], v[200:203], v[84:87]
	v_mfma_f32_16x16x32_bf16 v[80:83], v[176:179], v[200:203], v[80:83]
	v_mfma_f32_16x16x32_bf16 v[68:71], v[160:163], v[208:211], v[68:71]
	v_mfma_f32_16x16x32_bf16 v[64:67], v[176:179], v[208:211], v[64:67]
	v_mfma_f32_16x16x32_bf16 v[116:119], v[170:173], v[188:191], v[116:119]
	v_mfma_f32_16x16x32_bf16 v[112:115], v[180:183], v[188:191], v[112:115]
	v_mfma_f32_16x16x32_bf16 v[100:103], v[170:173], v[196:199], v[100:103]
	v_mfma_f32_16x16x32_bf16 v[96:99], v[180:183], v[196:199], v[96:99]
	v_mfma_f32_16x16x32_bf16 v[84:87], v[170:173], v[204:207], v[84:87]
	v_mfma_f32_16x16x32_bf16 v[80:83], v[180:183], v[204:207], v[80:83]
	v_mfma_f32_16x16x32_bf16 v[68:71], v[170:173], v[212:215], v[68:71]
	v_mfma_f32_16x16x32_bf16 v[64:67], v[180:183], v[212:215], v[64:67]
	s_setprio 0
	s_barrier
	s_add_i32 s64, s62, s73
	s_mov_b32 m0, s64
	ds_read_b128 v[184:187], v169 offset:16384
	ds_read_b128 v[188:191], v169 offset:17408
	ds_read_b128 v[192:195], v169 offset:18432
	ds_read_b128 v[196:199], v169 offset:19456
	ds_read_b128 v[200:203], v169 offset:20480
	ds_read_b128 v[204:207], v169 offset:21504
	ds_read_b128 v[208:211], v169 offset:22528
	ds_read_b128 v[212:215], v169 offset:23552
	global_load_lds_dwordx4 v146, s[36:37]
	s_add_i32 m0, s64, 0x2000
	s_add_u32 s64, s36, 0x40000
	s_addc_u32 s65, s37, 0
	s_add_i32 s66, s63, s73
	global_load_lds_dwordx4 v150, s[36:37]
	s_mov_b32 m0, s66
	s_nop 0
	global_load_lds_dwordx4 v146, s[64:65]
	s_add_i32 m0, s66, 0x2000
	s_nop 0
	global_load_lds_dwordx4 v150, s[64:65]
	s_mov_b32 m0, s31
	s_nop 0
	global_load_lds_dwordx4 v144, s[38:39]
	s_mov_b32 m0, s68
	s_nop 0
	global_load_lds_dwordx4 v148, s[38:39]
	s_waitcnt vmcnt(8)
	s_waitcnt lgkmcnt(0)
	s_barrier
	s_setprio 1
	s_waitcnt lgkmcnt(0)
	v_mfma_f32_16x16x32_bf16 v[60:63], v[128:131], v[184:187], v[60:63]
	v_mfma_f32_16x16x32_bf16 v[56:59], v[136:139], v[184:187], v[56:59]
	v_mfma_f32_16x16x32_bf16 v[44:47], v[128:131], v[192:195], v[44:47]
	v_mfma_f32_16x16x32_bf16 v[40:43], v[136:139], v[192:195], v[40:43]
	v_mfma_f32_16x16x32_bf16 v[28:31], v[128:131], v[200:203], v[28:31]
	v_mfma_f32_16x16x32_bf16 v[24:27], v[136:139], v[200:203], v[24:27]
	v_mfma_f32_16x16x32_bf16 v[12:15], v[128:131], v[208:211], v[12:15]
	v_mfma_f32_16x16x32_bf16 v[8:11], v[136:139], v[208:211], v[8:11]
	v_mfma_f32_16x16x32_bf16 v[60:63], v[132:135], v[188:191], v[60:63]
	v_mfma_f32_16x16x32_bf16 v[56:59], v[140:143], v[188:191], v[56:59]
	v_mfma_f32_16x16x32_bf16 v[44:47], v[132:135], v[196:199], v[44:47]
	v_mfma_f32_16x16x32_bf16 v[40:43], v[140:143], v[196:199], v[40:43]
	v_mfma_f32_16x16x32_bf16 v[28:31], v[132:135], v[204:207], v[28:31]
	v_mfma_f32_16x16x32_bf16 v[24:27], v[140:143], v[204:207], v[24:27]
	v_mfma_f32_16x16x32_bf16 v[12:15], v[132:135], v[212:215], v[12:15]
	v_mfma_f32_16x16x32_bf16 v[8:11], v[140:143], v[212:215], v[8:11]
	s_setprio 0
	s_setprio 1
	v_mfma_f32_16x16x32_bf16 v[52:55], v[160:163], v[184:187], v[52:55]
	v_mfma_f32_16x16x32_bf16 v[48:51], v[176:179], v[184:187], v[48:51]
	v_mfma_f32_16x16x32_bf16 v[36:39], v[160:163], v[192:195], v[36:39]
	v_mfma_f32_16x16x32_bf16 v[32:35], v[176:179], v[192:195], v[32:35]
	v_mfma_f32_16x16x32_bf16 v[20:23], v[160:163], v[200:203], v[20:23]
	v_mfma_f32_16x16x32_bf16 v[16:19], v[176:179], v[200:203], v[16:19]
	v_mfma_f32_16x16x32_bf16 v[4:7], v[160:163], v[208:211], v[4:7]
	v_mfma_f32_16x16x32_bf16 v[0:3], v[176:179], v[208:211], v[0:3]
	v_mfma_f32_16x16x32_bf16 v[52:55], v[170:173], v[188:191], v[52:55]
	v_mfma_f32_16x16x32_bf16 v[48:51], v[180:183], v[188:191], v[48:51]
	v_mfma_f32_16x16x32_bf16 v[36:39], v[170:173], v[196:199], v[36:39]
	v_mfma_f32_16x16x32_bf16 v[32:35], v[180:183], v[196:199], v[32:35]
	v_mfma_f32_16x16x32_bf16 v[20:23], v[170:173], v[204:207], v[20:23]
	v_mfma_f32_16x16x32_bf16 v[16:19], v[180:183], v[204:207], v[16:19]
	v_mfma_f32_16x16x32_bf16 v[4:7], v[170:173], v[212:215], v[4:7]
	v_mfma_f32_16x16x32_bf16 v[0:3], v[180:183], v[212:215], v[0:3]
	s_setprio 0
	s_barrier
; #define PG8_STAGE(bufoff, gbase, voff) do { _Pragma("unroll") for (int _i = 0; _i < 2; ++_i) \
;         __builtin_amdgcn_global_load_lds((const unsigned*)((const char*)(gbase) + (voff)[_i]), (LAS unsigned*)(lds + (bufoff) + ldsw + _i * 8192), 16, 0, 0); } while (0)
; #define PG8_LDA(dst, b, h) do { _Pragma("unroll") for (int m = 0; m < 4; ++m) _Pragma("unroll") for (int k = 0; k < 2; ++k) dst[m][k] = *(const LAS bf16x8*)(lds + PG8_SA(b, h) + aoff + m * 2048 + k * 1024); } while (0)
; #define PG8_LDB(dst, b, h) do { _Pragma("unroll") for (int n = 0; n < 2; ++n) _Pragma("unroll") for (int k = 0; k < 2; ++k) dst[n][k] = *(const LAS bf16x8*)(lds + PG8_SB(b, h) + boff + n * 2048 + k * 1024); } while (0)
; #define PG8_MMA(ai, bj, At, Bt) do { __builtin_amdgcn_s_setprio(1); _Pragma("unroll") for (int m = 0; m < 4; ++m) _Pragma("unroll") for (int n = 0; n < 2; ++n) _Pragma("unroll") for (int k = 0; k < 2; ++k) \
;         acc[ai][bj][m][n] = __builtin_amdgcn_mfma_f32_16x16x32_bf16(Bt[n][k], At[m][k], acc[ai][bj][m][n], 0, 0, 0); __builtin_amdgcn_s_setprio(0); } while (0)
; #define PG8_WAIT_V(n) asm volatile("s_waitcnt vmcnt(" #n ")" ::: "memory")
; #define PG8_WAIT_L(n) asm volatile("s_waitcnt lgkmcnt(" #n ")" ::: "memory")
; #define PG8_BAR __builtin_amdgcn_s_barrier()
; #define PG8_SCHED __builtin_amdgcn_sched_barrier(0)
; template <class Epi, class Sched, bool ALIGN_EPI, bool SP2>
; __device__ __forceinline__ void gemm_phase(LAS unsigned char* lds, const Gemm g, const Sched& S, const Epi& E) {
;     ...
;             PG8_LDB(B0, 1, 0); PG8_LDB(B1, 1, 1); PG8_SCHED; PG8_LDA(At, 1, 0); PG8_STAGE(PG8_SA(0, 1), a2 + hstep, voffA);
;             PG8_WAIT_V(8); PG8_WAIT_L(0); PG8_BAR; PG8_MMA(0, 0, At, B0); PG8_MMA(0, 1, At, B1); PG8_BAR; PG8_SCHED;
;             PG8_LDA(At, 1, 1); PG8_STAGE(PG8_SB(1, 0), b3, voffB); PG8_STAGE(PG8_SB(1, 1), b3 + hstep, voffB); PG8_STAGE(PG8_SA(1, 0), a3, voffA);
;             PG8_WAIT_V(8); PG8_WAIT_L(0); PG8_BAR; PG8_MMA(1, 0, At, B0); PG8_MMA(1, 1, At, B1); PG8_BAR; PG8_SCHED;
	s_add_i32 s64, 0, 0x18000
	s_add_i32 s65, 0, 0x1c000
	v_add_u32_e32 v140, s64, v165
	v_add_u32_e32 v174, s65, v165
	ds_read_b128 v[128:131], v140
	ds_read_b128 v[132:135], v140 offset:1024
	ds_read_b128 v[136:139], v140 offset:2048
	ds_read_b128 v[140:143], v140 offset:3072
	ds_read_b128 v[160:163], v174
	ds_read_b128 v[170:173], v174 offset:1024
	ds_read_b128 v[176:179], v174 offset:2048
	ds_read_b128 v[180:183], v174 offset:3072
	s_add_u32 s38, s38, 0x40000
	s_addc_u32 s39, s39, 0
	s_mov_b32 m0, s69
	ds_read_b128 v[184:187], v169 offset:32768
	ds_read_b128 v[188:191], v169 offset:33792
	ds_read_b128 v[192:195], v169 offset:34816
	ds_read_b128 v[196:199], v169 offset:35840
	ds_read_b128 v[200:203], v169 offset:36864
	ds_read_b128 v[204:207], v169 offset:37888
	ds_read_b128 v[208:211], v169 offset:38912
	ds_read_b128 v[212:215], v169 offset:39936
	global_load_lds_dwordx4 v144, s[38:39]
	s_mov_b32 m0, s70
	s_nop 0
	global_load_lds_dwordx4 v148, s[38:39]
	s_waitcnt vmcnt(8)
	s_waitcnt lgkmcnt(0)
	s_barrier
	s_setprio 1
	s_waitcnt lgkmcnt(0)
	v_mfma_f32_16x16x32_bf16 v[124:127], v[128:131], v[184:187], v[124:127]
	v_mfma_f32_16x16x32_bf16 v[120:123], v[136:139], v[184:187], v[120:123]
	v_mfma_f32_16x16x32_bf16 v[108:111], v[128:131], v[192:195], v[108:111]
	v_mfma_f32_16x16x32_bf16 v[104:107], v[136:139], v[192:195], v[104:107]
	v_mfma_f32_16x16x32_bf16 v[92:95], v[128:131], v[200:203], v[92:95]
	v_mfma_f32_16x16x32_bf16 v[88:91], v[136:139], v[200:203], v[88:91]
	v_mfma_f32_16x16x32_bf16 v[76:79], v[128:131], v[208:211], v[76:79]
	v_mfma_f32_16x16x32_bf16 v[72:75], v[136:139], v[208:211], v[72:75]
	v_mfma_f32_16x16x32_bf16 v[124:127], v[132:135], v[188:191], v[124:127]
	v_mfma_f32_16x16x32_bf16 v[120:123], v[140:143], v[188:191], v[120:123]
	v_mfma_f32_16x16x32_bf16 v[108:111], v[132:135], v[196:199], v[108:111]
	v_mfma_f32_16x16x32_bf16 v[104:107], v[140:143], v[196:199], v[104:107]
	v_mfma_f32_16x16x32_bf16 v[92:95], v[132:135], v[204:207], v[92:95]
	v_mfma_f32_16x16x32_bf16 v[88:91], v[140:143], v[204:207], v[88:91]
	v_mfma_f32_16x16x32_bf16 v[76:79], v[132:135], v[212:215], v[76:79]
	v_mfma_f32_16x16x32_bf16 v[72:75], v[140:143], v[212:215], v[72:75]
	s_setprio 0
	s_setprio 1
	v_mfma_f32_16x16x32_bf16 v[116:119], v[160:163], v[184:187], v[116:119]
	v_mfma_f32_16x16x32_bf16 v[112:115], v[176:179], v[184:187], v[112:115]
	v_mfma_f32_16x16x32_bf16 v[100:103], v[160:163], v[192:195], v[100:103]
	v_mfma_f32_16x16x32_bf16 v[96:99], v[176:179], v[192:195], v[96:99]
	v_mfma_f32_16x16x32_bf16 v[84:87], v[160:163], v[200:203], v[84:87]
	v_mfma_f32_16x16x32_bf16 v[80:83], v[176:179], v[200:203], v[80:83]
	v_mfma_f32_16x16x32_bf16 v[68:71], v[160:163], v[208:211], v[68:71]
	v_mfma_f32_16x16x32_bf16 v[64:67], v[176:179], v[208:211], v[64:67]
	v_mfma_f32_16x16x32_bf16 v[116:119], v[170:173], v[188:191], v[116:119]
	v_mfma_f32_16x16x32_bf16 v[112:115], v[180:183], v[188:191], v[112:115]
	v_mfma_f32_16x16x32_bf16 v[100:103], v[170:173], v[196:199], v[100:103]
	v_mfma_f32_16x16x32_bf16 v[96:99], v[180:183], v[196:199], v[96:99]
	v_mfma_f32_16x16x32_bf16 v[84:87], v[170:173], v[204:207], v[84:87]
	v_mfma_f32_16x16x32_bf16 v[80:83], v[180:183], v[204:207], v[80:83]
	v_mfma_f32_16x16x32_bf16 v[68:71], v[170:173], v[212:215], v[68:71]
	v_mfma_f32_16x16x32_bf16 v[64:67], v[180:183], v[212:215], v[64:67]
	s_setprio 0
	s_barrier
	s_add_u32 s100, s38, 0xfffc0080
	s_addc_u32 s101, s39, -1
	s_add_u32 s98, s36, 0x80
	s_addc_u32 s99, s37, 0
	s_add_i32 s38, s64, s73
	s_mov_b32 m0, s38
	ds_read_b128 v[184:187], v169 offset:49152
	ds_read_b128 v[188:191], v169 offset:50176
	ds_read_b128 v[192:195], v169 offset:51200
	ds_read_b128 v[196:199], v169 offset:52224
	ds_read_b128 v[200:203], v169 offset:53248
	ds_read_b128 v[204:207], v169 offset:54272
	ds_read_b128 v[208:211], v169 offset:55296
	ds_read_b128 v[212:215], v169 offset:56320
	global_load_lds_dwordx4 v146, s[98:99]
	s_add_i32 m0, s38, 0x2000
	s_add_u32 s36, s36, 0x40080
	s_addc_u32 s37, s37, 0
	s_add_i32 s38, s65, s73
	global_load_lds_dwordx4 v150, s[98:99]
	s_mov_b32 m0, s38
	s_nop 0
	global_load_lds_dwordx4 v146, s[36:37]
	s_add_i32 m0, s38, 0x2000
	s_nop 0
	global_load_lds_dwordx4 v150, s[36:37]
	s_mov_b32 m0, s54
	s_nop 0
	global_load_lds_dwordx4 v144, s[100:101]
	s_mov_b32 m0, s55
	s_nop 0
	global_load_lds_dwordx4 v148, s[100:101]
	s_waitcnt vmcnt(8)
	s_waitcnt lgkmcnt(0)
	s_barrier
	s_setprio 1
	s_waitcnt lgkmcnt(0)
	v_mfma_f32_16x16x32_bf16 v[60:63], v[128:131], v[184:187], v[60:63]
	v_mfma_f32_16x16x32_bf16 v[56:59], v[136:139], v[184:187], v[56:59]
	v_mfma_f32_16x16x32_bf16 v[44:47], v[128:131], v[192:195], v[44:47]
	v_mfma_f32_16x16x32_bf16 v[40:43], v[136:139], v[192:195], v[40:43]
	v_mfma_f32_16x16x32_bf16 v[28:31], v[128:131], v[200:203], v[28:31]
	v_mfma_f32_16x16x32_bf16 v[24:27], v[136:139], v[200:203], v[24:27]
	v_mfma_f32_16x16x32_bf16 v[12:15], v[128:131], v[208:211], v[12:15]
	v_mfma_f32_16x16x32_bf16 v[8:11], v[136:139], v[208:211], v[8:11]
	v_mfma_f32_16x16x32_bf16 v[60:63], v[132:135], v[188:191], v[60:63]
	v_mfma_f32_16x16x32_bf16 v[56:59], v[140:143], v[188:191], v[56:59]
	v_mfma_f32_16x16x32_bf16 v[44:47], v[132:135], v[196:199], v[44:47]
	v_mfma_f32_16x16x32_bf16 v[40:43], v[140:143], v[196:199], v[40:43]
	v_mfma_f32_16x16x32_bf16 v[28:31], v[132:135], v[204:207], v[28:31]
	v_mfma_f32_16x16x32_bf16 v[24:27], v[140:143], v[204:207], v[24:27]
	v_mfma_f32_16x16x32_bf16 v[12:15], v[132:135], v[212:215], v[12:15]
	v_mfma_f32_16x16x32_bf16 v[8:11], v[140:143], v[212:215], v[8:11]
	s_setprio 0
	s_setprio 1
	v_mfma_f32_16x16x32_bf16 v[52:55], v[160:163], v[184:187], v[52:55]
	v_mfma_f32_16x16x32_bf16 v[48:51], v[176:179], v[184:187], v[48:51]
	v_mfma_f32_16x16x32_bf16 v[36:39], v[160:163], v[192:195], v[36:39]
	v_mfma_f32_16x16x32_bf16 v[32:35], v[176:179], v[192:195], v[32:35]
	v_mfma_f32_16x16x32_bf16 v[20:23], v[160:163], v[200:203], v[20:23]
	v_mfma_f32_16x16x32_bf16 v[16:19], v[176:179], v[200:203], v[16:19]
	v_mfma_f32_16x16x32_bf16 v[4:7], v[160:163], v[208:211], v[4:7]
	v_mfma_f32_16x16x32_bf16 v[0:3], v[176:179], v[208:211], v[0:3]
	v_mfma_f32_16x16x32_bf16 v[52:55], v[170:173], v[188:191], v[52:55]
	v_mfma_f32_16x16x32_bf16 v[48:51], v[180:183], v[188:191], v[48:51]
	v_mfma_f32_16x16x32_bf16 v[36:39], v[170:173], v[196:199], v[36:39]
	v_mfma_f32_16x16x32_bf16 v[32:35], v[180:183], v[196:199], v[32:35]
	v_mfma_f32_16x16x32_bf16 v[20:23], v[170:173], v[204:207], v[20:23]
	v_mfma_f32_16x16x32_bf16 v[16:19], v[180:183], v[204:207], v[16:19]
	v_mfma_f32_16x16x32_bf16 v[4:7], v[170:173], v[212:215], v[4:7]
	v_mfma_f32_16x16x32_bf16 v[0:3], v[180:183], v[212:215], v[0:3]
	s_setprio 0
	s_barrier
	s_add_i32 s59, s59, 2
	s_add_u32 s34, s34, 0x100
	s_addc_u32 s35, s35, 0
	s_add_u32 s57, s57, 0x100
	s_addc_u32 s58, s58, 0
	s_cmp_gt_u32 s59, 13
	s_cbranch_scc0 .LBB0_553
	s_and_b64 vcc, exec, s[12:13]
	s_cbranch_vccz .LBB0_556
	s_barrier

; #define PG8_STAGE(bufoff, gbase, voff) do { _Pragma("unroll") for (int _i = 0; _i < 2; ++_i) \
;         __builtin_amdgcn_global_load_lds((const unsigned*)((const char*)(gbase) + (voff)[_i]), (LAS unsigned*)(lds + (bufoff) + ldsw + _i * 8192), 16, 0, 0); } while (0)
; #define PG8_LDA(dst, b, h) do { _Pragma("unroll") for (int m = 0; m < 4; ++m) _Pragma("unroll") for (int k = 0; k < 2; ++k) dst[m][k] = *(const LAS bf16x8*)(lds + PG8_SA(b, h) + aoff + m * 2048 + k * 1024); } while (0)
; #define PG8_LDB(dst, b, h) do { _Pragma("unroll") for (int n = 0; n < 2; ++n) _Pragma("unroll") for (int k = 0; k < 2; ++k) dst[n][k] = *(const LAS bf16x8*)(lds + PG8_SB(b, h) + boff + n * 2048 + k * 1024); } while (0)
; #define PG8_MMA(ai, bj, At, Bt) do { __builtin_amdgcn_s_setprio(1); _Pragma("unroll") for (int m = 0; m < 4; ++m) _Pragma("unroll") for (int n = 0; n < 2; ++n) _Pragma("unroll") for (int k = 0; k < 2; ++k) \
;         acc[ai][bj][m][n] = __builtin_amdgcn_mfma_f32_16x16x32_bf16(Bt[n][k], At[m][k], acc[ai][bj][m][n], 0, 0, 0); __builtin_amdgcn_s_setprio(0); } while (0)
; #define PG8_WAIT_V(n) asm volatile("s_waitcnt vmcnt(" #n ")" ::: "memory")
; #define PG8_WAIT_L(n) asm volatile("s_waitcnt lgkmcnt(" #n ")" ::: "memory")
; #define PG8_BAR __builtin_amdgcn_s_barrier()
; template <class Epi, class Sched, bool ALIGN_EPI, bool SP2>
; __device__ __forceinline__ void gemm_phase(LAS unsigned char* lds, const Gemm g, const Sched& S, const Epi& E) {
;     ...
;         for (int t = 0; t < nt; t += 2) {
;             const bool last = (t == nt - 2);
;             const char* a1 = cA + (size_t)(t + 1) * kstep;
;             const char* a2 = last ? nA : cA + (size_t)(t + 2) * kstep; const char* b2 = last ? nB : cB + (size_t)(t + 2) * kstep;
;             const char* a3 = a2 + kstep; const char* b3 = b2 + kstep;
;             if constexpr (SP2) {
;             PG8_LDB(B0, 0, 0); PG8_LDB(B1, 0, 1); PG8_SCHED; PG8_LDA(At, 0, 0); PG8_STAGE(PG8_SA(1, 1), a1 + hstep, voffA);
;             PG8_WAIT_V(8); PG8_WAIT_L(0); PG8_BAR; PG8_MMA(0, 0, At, B0); PG8_MMA(0, 1, At, B1); PG8_BAR; PG8_SCHED;
;             PG8_LDA(At, 0, 1); PG8_STAGE(PG8_SB(0, 0), b2, voffB); PG8_STAGE(PG8_SB(0, 1), b2 + hstep, voffB); PG8_STAGE(PG8_SA(0, 0), a2, voffA);
;             PG8_WAIT_V(8); PG8_WAIT_L(0); PG8_BAR; PG8_MMA(1, 0, At, B0); PG8_MMA(1, 1, At, B1); PG8_BAR; PG8_SCHED;
.LBB0_683:
	ds_read_b128 v[150:153], v147
	ds_read_b128 v[154:157], v147 offset:1024
	ds_read_b128 v[158:161], v147 offset:2048
	ds_read_b128 v[162:165], v147 offset:3072
	ds_read_b128 v[166:169], v148
	ds_read_b128 v[170:173], v148 offset:1024
	ds_read_b128 v[176:179], v148 offset:2048
	ds_read_b128 v[180:183], v148 offset:3072
	s_add_u32 s26, s24, 0xfffc0080
	s_addc_u32 s27, s25, -1
	s_cmp_eq_u32 s52, 12
	s_cselect_b32 s29, s15, s27
	s_cselect_b32 s28, s48, s26
	s_cselect_b32 s27, s17, s51
	s_cselect_b32 s26, s49, s50
	s_add_i32 m0, s23, 0xc000
	ds_read_b128 v[184:187], v149
	ds_read_b128 v[188:191], v149 offset:1024
	ds_read_b128 v[192:195], v149 offset:2048
	ds_read_b128 v[196:199], v149 offset:3072
	ds_read_b128 v[200:203], v149 offset:4096
	ds_read_b128 v[204:207], v149 offset:5120
	ds_read_b128 v[208:211], v149 offset:6144
	ds_read_b128 v[212:215], v149 offset:7168
	global_load_lds_dwordx4 v136, s[24:25]
	s_add_i32 m0, s23, 0xe000
	s_nop 0
	global_load_lds_dwordx4 v138, s[24:25]
	s_waitcnt vmcnt(8)
	s_waitcnt lgkmcnt(0)
	s_barrier
	s_setprio 1
	s_waitcnt lgkmcnt(0)
	v_mfma_f32_16x16x32_bf16 v[124:127], v[150:153], v[184:187], v[124:127]
	v_mfma_f32_16x16x32_bf16 v[120:123], v[158:161], v[184:187], v[120:123]
	v_mfma_f32_16x16x32_bf16 v[108:111], v[150:153], v[192:195], v[108:111]
	v_mfma_f32_16x16x32_bf16 v[104:107], v[158:161], v[192:195], v[104:107]
	v_mfma_f32_16x16x32_bf16 v[92:95], v[150:153], v[200:203], v[92:95]
	v_mfma_f32_16x16x32_bf16 v[88:91], v[158:161], v[200:203], v[88:91]
	v_mfma_f32_16x16x32_bf16 v[76:79], v[150:153], v[208:211], v[76:79]
	v_mfma_f32_16x16x32_bf16 v[72:75], v[158:161], v[208:211], v[72:75]
	v_mfma_f32_16x16x32_bf16 v[124:127], v[154:157], v[188:191], v[124:127]
	v_mfma_f32_16x16x32_bf16 v[120:123], v[162:165], v[188:191], v[120:123]
	v_mfma_f32_16x16x32_bf16 v[108:111], v[154:157], v[196:199], v[108:111]
	v_mfma_f32_16x16x32_bf16 v[104:107], v[162:165], v[196:199], v[104:107]
	v_mfma_f32_16x16x32_bf16 v[92:95], v[154:157], v[204:207], v[92:95]
	v_mfma_f32_16x16x32_bf16 v[88:91], v[162:165], v[204:207], v[88:91]
	v_mfma_f32_16x16x32_bf16 v[76:79], v[154:157], v[212:215], v[76:79]
	v_mfma_f32_16x16x32_bf16 v[72:75], v[162:165], v[212:215], v[72:75]
	s_setprio 0
	s_setprio 1
	v_mfma_f32_16x16x32_bf16 v[116:119], v[166:169], v[184:187], v[116:119]
	v_mfma_f32_16x16x32_bf16 v[112:115], v[176:179], v[184:187], v[112:115]
	v_mfma_f32_16x16x32_bf16 v[100:103], v[166:169], v[192:195], v[100:103]
	v_mfma_f32_16x16x32_bf16 v[96:99], v[176:179], v[192:195], v[96:99]
	v_mfma_f32_16x16x32_bf16 v[84:87], v[166:169], v[200:203], v[84:87]
	v_mfma_f32_16x16x32_bf16 v[80:83], v[176:179], v[200:203], v[80:83]
	v_mfma_f32_16x16x32_bf16 v[68:71], v[166:169], v[208:211], v[68:71]
	v_mfma_f32_16x16x32_bf16 v[64:67], v[176:179], v[208:211], v[64:67]
	v_mfma_f32_16x16x32_bf16 v[116:119], v[170:173], v[188:191], v[116:119]
	v_mfma_f32_16x16x32_bf16 v[112:115], v[180:183], v[188:191], v[112:115]
	v_mfma_f32_16x16x32_bf16 v[100:103], v[170:173], v[196:199], v[100:103]
	v_mfma_f32_16x16x32_bf16 v[96:99], v[180:183], v[196:199], v[96:99]
	v_mfma_f32_16x16x32_bf16 v[84:87], v[170:173], v[204:207], v[84:87]
	v_mfma_f32_16x16x32_bf16 v[80:83], v[180:183], v[204:207], v[80:83]
	v_mfma_f32_16x16x32_bf16 v[68:71], v[170:173], v[212:215], v[68:71]
	v_mfma_f32_16x16x32_bf16 v[64:67], v[180:183], v[212:215], v[64:67]
	s_setprio 0
	s_barrier
	s_add_i32 s53, s44, s30
	s_mov_b32 m0, s53
	ds_read_b128 v[184:187], v149 offset:16384
	ds_read_b128 v[188:191], v149 offset:17408
	ds_read_b128 v[192:195], v149 offset:18432
	ds_read_b128 v[196:199], v149 offset:19456
	ds_read_b128 v[200:203], v149 offset:20480
	ds_read_b128 v[204:207], v149 offset:21504
	ds_read_b128 v[208:211], v149 offset:22528
	ds_read_b128 v[212:215], v149 offset:23552
	global_load_lds_dwordx4 v132, s[26:27]
	s_add_i32 m0, s53, 0x2000
	s_add_u32 s54, s26, 0x40000
	s_addc_u32 s55, s27, 0
	s_add_i32 s53, s45, s30
	global_load_lds_dwordx4 v128, s[26:27]
	s_mov_b32 m0, s53
	s_nop 0
	global_load_lds_dwordx4 v132, s[54:55]
	s_add_i32 m0, s53, 0x2000
	s_nop 0
	global_load_lds_dwordx4 v128, s[54:55]
	s_mov_b32 m0, s23
	s_nop 0
	global_load_lds_dwordx4 v134, s[28:29]
	s_mov_b32 m0, s34
	s_nop 0
	global_load_lds_dwordx4 v130, s[28:29]
	s_waitcnt vmcnt(8)
	s_waitcnt lgkmcnt(0)
	s_barrier
	s_setprio 1
	s_waitcnt lgkmcnt(0)
	v_mfma_f32_16x16x32_bf16 v[60:63], v[150:153], v[184:187], v[60:63]
	v_mfma_f32_16x16x32_bf16 v[56:59], v[158:161], v[184:187], v[56:59]
	v_mfma_f32_16x16x32_bf16 v[44:47], v[150:153], v[192:195], v[44:47]
	v_mfma_f32_16x16x32_bf16 v[40:43], v[158:161], v[192:195], v[40:43]
	v_mfma_f32_16x16x32_bf16 v[28:31], v[150:153], v[200:203], v[28:31]
	v_mfma_f32_16x16x32_bf16 v[24:27], v[158:161], v[200:203], v[24:27]
	v_mfma_f32_16x16x32_bf16 v[12:15], v[150:153], v[208:211], v[12:15]
	v_mfma_f32_16x16x32_bf16 v[8:11], v[158:161], v[208:211], v[8:11]
	v_mfma_f32_16x16x32_bf16 v[60:63], v[154:157], v[188:191], v[60:63]
	v_mfma_f32_16x16x32_bf16 v[56:59], v[162:165], v[188:191], v[56:59]
	v_mfma_f32_16x16x32_bf16 v[44:47], v[154:157], v[196:199], v[44:47]
	v_mfma_f32_16x16x32_bf16 v[40:43], v[162:165], v[196:199], v[40:43]
	v_mfma_f32_16x16x32_bf16 v[28:31], v[154:157], v[204:207], v[28:31]
	v_mfma_f32_16x16x32_bf16 v[24:27], v[162:165], v[204:207], v[24:27]
	v_mfma_f32_16x16x32_bf16 v[12:15], v[154:157], v[212:215], v[12:15]
	v_mfma_f32_16x16x32_bf16 v[8:11], v[162:165], v[212:215], v[8:11]
	s_setprio 0
	s_setprio 1
	v_mfma_f32_16x16x32_bf16 v[52:55], v[166:169], v[184:187], v[52:55]
	v_mfma_f32_16x16x32_bf16 v[48:51], v[176:179], v[184:187], v[48:51]
	v_mfma_f32_16x16x32_bf16 v[36:39], v[166:169], v[192:195], v[36:39]
	v_mfma_f32_16x16x32_bf16 v[32:35], v[176:179], v[192:195], v[32:35]
	v_mfma_f32_16x16x32_bf16 v[20:23], v[166:169], v[200:203], v[20:23]
	v_mfma_f32_16x16x32_bf16 v[16:19], v[176:179], v[200:203], v[16:19]
	v_mfma_f32_16x16x32_bf16 v[4:7], v[166:169], v[208:211], v[4:7]
	v_mfma_f32_16x16x32_bf16 v[0:3], v[176:179], v[208:211], v[0:3]
	v_mfma_f32_16x16x32_bf16 v[52:55], v[170:173], v[188:191], v[52:55]
	v_mfma_f32_16x16x32_bf16 v[48:51], v[180:183], v[188:191], v[48:51]
	v_mfma_f32_16x16x32_bf16 v[36:39], v[170:173], v[196:199], v[36:39]
	v_mfma_f32_16x16x32_bf16 v[32:35], v[180:183], v[196:199], v[32:35]
	v_mfma_f32_16x16x32_bf16 v[20:23], v[170:173], v[204:207], v[20:23]
	v_mfma_f32_16x16x32_bf16 v[16:19], v[180:183], v[204:207], v[16:19]
	v_mfma_f32_16x16x32_bf16 v[4:7], v[170:173], v[212:215], v[4:7]
	v_mfma_f32_16x16x32_bf16 v[0:3], v[180:183], v[212:215], v[0:3]
	s_setprio 0
	s_barrier
; #define PG8_STAGE(bufoff, gbase, voff) do { _Pragma("unroll") for (int _i = 0; _i < 2; ++_i) \
;         __builtin_amdgcn_global_load_lds((const unsigned*)((const char*)(gbase) + (voff)[_i]), (LAS unsigned*)(lds + (bufoff) + ldsw + _i * 8192), 16, 0, 0); } while (0)
; #define PG8_LDA(dst, b, h) do { _Pragma("unroll") for (int m = 0; m < 4; ++m) _Pragma("unroll") for (int k = 0; k < 2; ++k) dst[m][k] = *(const LAS bf16x8*)(lds + PG8_SA(b, h) + aoff + m * 2048 + k * 1024); } while (0)
; #define PG8_LDB(dst, b, h) do { _Pragma("unroll") for (int n = 0; n < 2; ++n) _Pragma("unroll") for (int k = 0; k < 2; ++k) dst[n][k] = *(const LAS bf16x8*)(lds + PG8_SB(b, h) + boff + n * 2048 + k * 1024); } while (0)
; #define PG8_MMA(ai, bj, At, Bt) do { __builtin_amdgcn_s_setprio(1); _Pragma("unroll") for (int m = 0; m < 4; ++m) _Pragma("unroll") for (int n = 0; n < 2; ++n) _Pragma("unroll") for (int k = 0; k < 2; ++k) \
;         acc[ai][bj][m][n] = __builtin_amdgcn_mfma_f32_16x16x32_bf16(Bt[n][k], At[m][k], acc[ai][bj][m][n], 0, 0, 0); __builtin_amdgcn_s_setprio(0); } while (0)
; #define PG8_WAIT_V(n) asm volatile("s_waitcnt vmcnt(" #n ")" ::: "memory")
; #define PG8_WAIT_L(n) asm volatile("s_waitcnt lgkmcnt(" #n ")" ::: "memory")
; #define PG8_BAR __builtin_amdgcn_s_barrier()
; #define PG8_SCHED __builtin_amdgcn_sched_barrier(0)
; template <class Epi, class Sched, bool ALIGN_EPI, bool SP2>
; __device__ __forceinline__ void gemm_phase(LAS unsigned char* lds, const Gemm g, const Sched& S, const Epi& E) {
;     ...
;             PG8_LDB(B0, 1, 0); PG8_LDB(B1, 1, 1); PG8_SCHED; PG8_LDA(At, 1, 0); PG8_STAGE(PG8_SA(0, 1), a2 + hstep, voffA);
;             PG8_WAIT_V(8); PG8_WAIT_L(0); PG8_BAR; PG8_MMA(0, 0, At, B0); PG8_MMA(0, 1, At, B1); PG8_BAR; PG8_SCHED;
;             PG8_LDA(At, 1, 1); PG8_STAGE(PG8_SB(1, 0), b3, voffB); PG8_STAGE(PG8_SB(1, 1), b3 + hstep, voffB); PG8_STAGE(PG8_SA(1, 0), a3, voffA);
;             PG8_WAIT_V(8); PG8_WAIT_L(0); PG8_BAR; PG8_MMA(1, 0, At, B0); PG8_MMA(1, 1, At, B1); PG8_BAR; PG8_SCHED;
	s_add_i32 s53, 0, 0x18000
	s_add_i32 s54, 0, 0x1c000
	v_add_u32_e32 v162, s53, v145
	v_add_u32_e32 v174, s54, v145
	ds_read_b128 v[150:153], v162
	ds_read_b128 v[154:157], v162 offset:1024
	ds_read_b128 v[158:161], v162 offset:2048
	ds_read_b128 v[162:165], v162 offset:3072
	ds_read_b128 v[166:169], v174
	ds_read_b128 v[170:173], v174 offset:1024
	ds_read_b128 v[176:179], v174 offset:2048
	ds_read_b128 v[180:183], v174 offset:3072
	s_add_u32 s28, s28, 0x40000
	s_addc_u32 s29, s29, 0
	s_mov_b32 m0, s35
	ds_read_b128 v[184:187], v149 offset:32768
	ds_read_b128 v[188:191], v149 offset:33792
	ds_read_b128 v[192:195], v149 offset:34816
	ds_read_b128 v[196:199], v149 offset:35840
	ds_read_b128 v[200:203], v149 offset:36864
	ds_read_b128 v[204:207], v149 offset:37888
	ds_read_b128 v[208:211], v149 offset:38912
	ds_read_b128 v[212:215], v149 offset:39936
	global_load_lds_dwordx4 v134, s[28:29]
	s_mov_b32 m0, s36
	s_nop 0
	global_load_lds_dwordx4 v130, s[28:29]
	s_waitcnt vmcnt(8)
	s_waitcnt lgkmcnt(0)
	s_barrier
	s_setprio 1
	s_waitcnt lgkmcnt(0)
	v_mfma_f32_16x16x32_bf16 v[124:127], v[150:153], v[184:187], v[124:127]
	v_mfma_f32_16x16x32_bf16 v[120:123], v[158:161], v[184:187], v[120:123]
	v_mfma_f32_16x16x32_bf16 v[108:111], v[150:153], v[192:195], v[108:111]
	v_mfma_f32_16x16x32_bf16 v[104:107], v[158:161], v[192:195], v[104:107]
	v_mfma_f32_16x16x32_bf16 v[92:95], v[150:153], v[200:203], v[92:95]
	v_mfma_f32_16x16x32_bf16 v[88:91], v[158:161], v[200:203], v[88:91]
	v_mfma_f32_16x16x32_bf16 v[76:79], v[150:153], v[208:211], v[76:79]
	v_mfma_f32_16x16x32_bf16 v[72:75], v[158:161], v[208:211], v[72:75]
	v_mfma_f32_16x16x32_bf16 v[124:127], v[154:157], v[188:191], v[124:127]
	v_mfma_f32_16x16x32_bf16 v[120:123], v[162:165], v[188:191], v[120:123]
	v_mfma_f32_16x16x32_bf16 v[108:111], v[154:157], v[196:199], v[108:111]
	v_mfma_f32_16x16x32_bf16 v[104:107], v[162:165], v[196:199], v[104:107]
	v_mfma_f32_16x16x32_bf16 v[92:95], v[154:157], v[204:207], v[92:95]
	v_mfma_f32_16x16x32_bf16 v[88:91], v[162:165], v[204:207], v[88:91]
	v_mfma_f32_16x16x32_bf16 v[76:79], v[154:157], v[212:215], v[76:79]
	v_mfma_f32_16x16x32_bf16 v[72:75], v[162:165], v[212:215], v[72:75]
	s_setprio 0
	s_setprio 1
	v_mfma_f32_16x16x32_bf16 v[116:119], v[166:169], v[184:187], v[116:119]
	v_mfma_f32_16x16x32_bf16 v[112:115], v[176:179], v[184:187], v[112:115]
	v_mfma_f32_16x16x32_bf16 v[100:103], v[166:169], v[192:195], v[100:103]
	v_mfma_f32_16x16x32_bf16 v[96:99], v[176:179], v[192:195], v[96:99]
	v_mfma_f32_16x16x32_bf16 v[84:87], v[166:169], v[200:203], v[84:87]
	v_mfma_f32_16x16x32_bf16 v[80:83], v[176:179], v[200:203], v[80:83]
	v_mfma_f32_16x16x32_bf16 v[68:71], v[166:169], v[208:211], v[68:71]
	v_mfma_f32_16x16x32_bf16 v[64:67], v[176:179], v[208:211], v[64:67]
	v_mfma_f32_16x16x32_bf16 v[116:119], v[170:173], v[188:191], v[116:119]
	v_mfma_f32_16x16x32_bf16 v[112:115], v[180:183], v[188:191], v[112:115]
	v_mfma_f32_16x16x32_bf16 v[100:103], v[170:173], v[196:199], v[100:103]
	v_mfma_f32_16x16x32_bf16 v[96:99], v[180:183], v[196:199], v[96:99]
	v_mfma_f32_16x16x32_bf16 v[84:87], v[170:173], v[204:207], v[84:87]
	v_mfma_f32_16x16x32_bf16 v[80:83], v[180:183], v[204:207], v[80:83]
	v_mfma_f32_16x16x32_bf16 v[68:71], v[170:173], v[212:215], v[68:71]
	v_mfma_f32_16x16x32_bf16 v[64:67], v[180:183], v[212:215], v[64:67]
	s_setprio 0
	s_barrier
	s_add_u32 s100, s28, 0xfffc0080
	s_addc_u32 s101, s29, -1
	s_add_u32 s98, s26, 0x80
	s_addc_u32 s99, s27, 0
	s_add_i32 s28, s53, s30
	s_mov_b32 m0, s28
	ds_read_b128 v[184:187], v149 offset:49152
	ds_read_b128 v[188:191], v149 offset:50176
	ds_read_b128 v[192:195], v149 offset:51200
	ds_read_b128 v[196:199], v149 offset:52224
	ds_read_b128 v[200:203], v149 offset:53248
	ds_read_b128 v[204:207], v149 offset:54272
	ds_read_b128 v[208:211], v149 offset:55296
	ds_read_b128 v[212:215], v149 offset:56320
	global_load_lds_dwordx4 v132, s[98:99]
	s_add_i32 m0, s28, 0x2000
	s_add_u32 s26, s26, 0x40080
	s_addc_u32 s27, s27, 0
	s_add_i32 s28, s54, s30
	global_load_lds_dwordx4 v128, s[98:99]
	s_mov_b32 m0, s28
	s_nop 0
	global_load_lds_dwordx4 v132, s[26:27]
	s_add_i32 m0, s28, 0x2000
	s_nop 0
	global_load_lds_dwordx4 v128, s[26:27]
	s_mov_b32 m0, s38
	s_nop 0
	global_load_lds_dwordx4 v134, s[100:101]
	s_mov_b32 m0, s39
	s_nop 0
	global_load_lds_dwordx4 v130, s[100:101]
	s_waitcnt vmcnt(8)
	s_waitcnt lgkmcnt(0)
	s_barrier
	s_setprio 1
	s_waitcnt lgkmcnt(0)
	v_mfma_f32_16x16x32_bf16 v[60:63], v[150:153], v[184:187], v[60:63]
	v_mfma_f32_16x16x32_bf16 v[56:59], v[158:161], v[184:187], v[56:59]
	v_mfma_f32_16x16x32_bf16 v[44:47], v[150:153], v[192:195], v[44:47]
	v_mfma_f32_16x16x32_bf16 v[40:43], v[158:161], v[192:195], v[40:43]
	v_mfma_f32_16x16x32_bf16 v[28:31], v[150:153], v[200:203], v[28:31]
	v_mfma_f32_16x16x32_bf16 v[24:27], v[158:161], v[200:203], v[24:27]
	v_mfma_f32_16x16x32_bf16 v[12:15], v[150:153], v[208:211], v[12:15]
	v_mfma_f32_16x16x32_bf16 v[8:11], v[158:161], v[208:211], v[8:11]
	v_mfma_f32_16x16x32_bf16 v[60:63], v[154:157], v[188:191], v[60:63]
	v_mfma_f32_16x16x32_bf16 v[56:59], v[162:165], v[188:191], v[56:59]
	v_mfma_f32_16x16x32_bf16 v[44:47], v[154:157], v[196:199], v[44:47]
	v_mfma_f32_16x16x32_bf16 v[40:43], v[162:165], v[196:199], v[40:43]
	v_mfma_f32_16x16x32_bf16 v[28:31], v[154:157], v[204:207], v[28:31]
	v_mfma_f32_16x16x32_bf16 v[24:27], v[162:165], v[204:207], v[24:27]
	v_mfma_f32_16x16x32_bf16 v[12:15], v[154:157], v[212:215], v[12:15]
	v_mfma_f32_16x16x32_bf16 v[8:11], v[162:165], v[212:215], v[8:11]
	s_setprio 0
	s_setprio 1
	v_mfma_f32_16x16x32_bf16 v[52:55], v[166:169], v[184:187], v[52:55]
	v_mfma_f32_16x16x32_bf16 v[48:51], v[176:179], v[184:187], v[48:51]
	v_mfma_f32_16x16x32_bf16 v[36:39], v[166:169], v[192:195], v[36:39]
	v_mfma_f32_16x16x32_bf16 v[32:35], v[176:179], v[192:195], v[32:35]
	v_mfma_f32_16x16x32_bf16 v[20:23], v[166:169], v[200:203], v[20:23]
	v_mfma_f32_16x16x32_bf16 v[16:19], v[176:179], v[200:203], v[16:19]
	v_mfma_f32_16x16x32_bf16 v[4:7], v[166:169], v[208:211], v[4:7]
	v_mfma_f32_16x16x32_bf16 v[0:3], v[176:179], v[208:211], v[0:3]
	v_mfma_f32_16x16x32_bf16 v[52:55], v[170:173], v[188:191], v[52:55]
	v_mfma_f32_16x16x32_bf16 v[48:51], v[180:183], v[188:191], v[48:51]
	v_mfma_f32_16x16x32_bf16 v[36:39], v[170:173], v[196:199], v[36:39]
	v_mfma_f32_16x16x32_bf16 v[32:35], v[180:183], v[196:199], v[32:35]
	v_mfma_f32_16x16x32_bf16 v[20:23], v[170:173], v[204:207], v[20:23]
	v_mfma_f32_16x16x32_bf16 v[16:19], v[180:183], v[204:207], v[16:19]
	v_mfma_f32_16x16x32_bf16 v[4:7], v[170:173], v[212:215], v[4:7]
	v_mfma_f32_16x16x32_bf16 v[0:3], v[180:183], v[212:215], v[0:3]
	s_setprio 0
	s_barrier
	s_add_i32 s52, s52, 2
	s_add_u32 s24, s24, 0x100
	s_addc_u32 s25, s25, 0
	s_add_u32 s50, s50, 0x100
	s_addc_u32 s51, s51, 0
	s_cmp_gt_u32 s52, 13
	s_cbranch_scc0 .LBB0_683
	s_and_b64 vcc, exec, s[12:13]
	s_cbranch_vccz .LBB0_686
	s_barrier

; #define PG8_STAGE(bufoff, gbase, voff) do { _Pragma("unroll") for (int _i = 0; _i < 2; ++_i) \
;         __builtin_amdgcn_global_load_lds((const unsigned*)((const char*)(gbase) + (voff)[_i]), (LAS unsigned*)(lds + (bufoff) + ldsw + _i * 8192), 16, 0, 0); } while (0)
; #define PG8_LDA(dst, b, h) do { _Pragma("unroll") for (int m = 0; m < 4; ++m) _Pragma("unroll") for (int k = 0; k < 2; ++k) dst[m][k] = *(const LAS bf16x8*)(lds + PG8_SA(b, h) + aoff + m * 2048 + k * 1024); } while (0)
; #define PG8_LDB(dst, b, h) do { _Pragma("unroll") for (int n = 0; n < 2; ++n) _Pragma("unroll") for (int k = 0; k < 2; ++k) dst[n][k] = *(const LAS bf16x8*)(lds + PG8_SB(b, h) + boff + n * 2048 + k * 1024); } while (0)
; #define PG8_MMA(ai, bj, At, Bt) do { __builtin_amdgcn_s_setprio(1); _Pragma("unroll") for (int m = 0; m < 4; ++m) _Pragma("unroll") for (int n = 0; n < 2; ++n) _Pragma("unroll") for (int k = 0; k < 2; ++k) \
;         acc[ai][bj][m][n] = __builtin_amdgcn_mfma_f32_16x16x32_bf16(Bt[n][k], At[m][k], acc[ai][bj][m][n], 0, 0, 0); __builtin_amdgcn_s_setprio(0); } while (0)
; #define PG8_WAIT_V(n) asm volatile("s_waitcnt vmcnt(" #n ")" ::: "memory")
; #define PG8_WAIT_L(n) asm volatile("s_waitcnt lgkmcnt(" #n ")" ::: "memory")
; #define PG8_BAR __builtin_amdgcn_s_barrier()
; template <class Epi, class Sched, bool ALIGN_EPI, bool SP2>
; __device__ __forceinline__ void gemm_phase(LAS unsigned char* lds, const Gemm g, const Sched& S, const Epi& E) {
;     ...
;         for (int t = 0; t < nt; t += 2) {
;             const bool last = (t == nt - 2);
;             const char* a1 = cA + (size_t)(t + 1) * kstep;
;             const char* a2 = last ? nA : cA + (size_t)(t + 2) * kstep; const char* b2 = last ? nB : cB + (size_t)(t + 2) * kstep;
;             const char* a3 = a2 + kstep; const char* b3 = b2 + kstep;
;             if constexpr (SP2) {
;             PG8_LDB(B0, 0, 0); PG8_LDB(B1, 0, 1); PG8_SCHED; PG8_LDA(At, 0, 0); PG8_STAGE(PG8_SA(1, 1), a1 + hstep, voffA);
;             PG8_WAIT_V(8); PG8_WAIT_L(0); PG8_BAR; PG8_MMA(0, 0, At, B0); PG8_MMA(0, 1, At, B1); PG8_BAR; PG8_SCHED;
;             PG8_LDA(At, 0, 1); PG8_STAGE(PG8_SB(0, 0), b2, voffB); PG8_STAGE(PG8_SB(0, 1), b2 + hstep, voffB); PG8_STAGE(PG8_SA(0, 0), a2, voffA);
;             PG8_WAIT_V(8); PG8_WAIT_L(0); PG8_BAR; PG8_MMA(1, 0, At, B0); PG8_MMA(1, 1, At, B1); PG8_BAR; PG8_SCHED;
.LBB0_766:
	ds_read_b128 v[120:123], v169
	ds_read_b128 v[124:127], v169 offset:1024
	ds_read_b128 v[136:139], v169 offset:2048
	ds_read_b128 v[140:143], v169 offset:3072
	ds_read_b128 v[160:163], v170
	ds_read_b128 v[172:175], v170 offset:1024
	ds_read_b128 v[176:179], v170 offset:2048
	ds_read_b128 v[180:183], v170 offset:3072
	s_add_u32 s26, s24, 0x100
	s_addc_u32 s27, s25, 0
	s_cmp_eq_u32 s56, 40
	s_cselect_b32 s31, s5, s27
	s_cselect_b32 s30, s4, s26
	s_cselect_b32 s29, s23, s55
	s_cselect_b32 s28, s22, s54
	s_add_i32 m0, s37, 0xc000
	ds_read_b128 v[184:187], v171
	ds_read_b128 v[188:191], v171 offset:1024
	ds_read_b128 v[192:195], v171 offset:2048
	ds_read_b128 v[196:199], v171 offset:3072
	ds_read_b128 v[200:203], v171 offset:4096
	ds_read_b128 v[204:207], v171 offset:5120
	ds_read_b128 v[208:211], v171 offset:6144
	ds_read_b128 v[212:215], v171 offset:7168
	global_load_lds_dwordx4 v152, s[24:25]
	s_add_i32 m0, s37, 0xe000
	s_nop 0
	global_load_lds_dwordx4 v154, s[24:25]
	s_waitcnt vmcnt(8)
	s_waitcnt lgkmcnt(0)
	s_barrier
	s_setprio 1
	s_waitcnt lgkmcnt(0)
	v_mfma_f32_16x16x32_bf16 v[132:135], v[120:123], v[184:187], v[132:135]
	v_mfma_f32_16x16x32_bf16 v[128:131], v[136:139], v[184:187], v[128:131]
	v_mfma_f32_16x16x32_bf16 v[108:111], v[120:123], v[192:195], v[108:111]
	v_mfma_f32_16x16x32_bf16 v[104:107], v[136:139], v[192:195], v[104:107]
	v_mfma_f32_16x16x32_bf16 v[92:95], v[120:123], v[200:203], v[92:95]
	v_mfma_f32_16x16x32_bf16 v[88:91], v[136:139], v[200:203], v[88:91]
	v_mfma_f32_16x16x32_bf16 v[76:79], v[120:123], v[208:211], v[76:79]
	v_mfma_f32_16x16x32_bf16 v[72:75], v[136:139], v[208:211], v[72:75]
	v_mfma_f32_16x16x32_bf16 v[132:135], v[124:127], v[188:191], v[132:135]
	v_mfma_f32_16x16x32_bf16 v[128:131], v[140:143], v[188:191], v[128:131]
	v_mfma_f32_16x16x32_bf16 v[108:111], v[124:127], v[196:199], v[108:111]
	v_mfma_f32_16x16x32_bf16 v[104:107], v[140:143], v[196:199], v[104:107]
	v_mfma_f32_16x16x32_bf16 v[92:95], v[124:127], v[204:207], v[92:95]
	v_mfma_f32_16x16x32_bf16 v[88:91], v[140:143], v[204:207], v[88:91]
	v_mfma_f32_16x16x32_bf16 v[76:79], v[124:127], v[212:215], v[76:79]
	v_mfma_f32_16x16x32_bf16 v[72:75], v[140:143], v[212:215], v[72:75]
	s_setprio 0
	s_setprio 1
	v_mfma_f32_16x16x32_bf16 v[116:119], v[160:163], v[184:187], v[116:119]
	v_mfma_f32_16x16x32_bf16 v[112:115], v[176:179], v[184:187], v[112:115]
	v_mfma_f32_16x16x32_bf16 v[100:103], v[160:163], v[192:195], v[100:103]
	v_mfma_f32_16x16x32_bf16 v[96:99], v[176:179], v[192:195], v[96:99]
	v_mfma_f32_16x16x32_bf16 v[84:87], v[160:163], v[200:203], v[84:87]
	v_mfma_f32_16x16x32_bf16 v[80:83], v[176:179], v[200:203], v[80:83]
	v_mfma_f32_16x16x32_bf16 v[68:71], v[160:163], v[208:211], v[68:71]
	v_mfma_f32_16x16x32_bf16 v[64:67], v[176:179], v[208:211], v[64:67]
	v_mfma_f32_16x16x32_bf16 v[116:119], v[172:175], v[188:191], v[116:119]
	v_mfma_f32_16x16x32_bf16 v[112:115], v[180:183], v[188:191], v[112:115]
	v_mfma_f32_16x16x32_bf16 v[100:103], v[172:175], v[196:199], v[100:103]
	v_mfma_f32_16x16x32_bf16 v[96:99], v[180:183], v[196:199], v[96:99]
	v_mfma_f32_16x16x32_bf16 v[84:87], v[172:175], v[204:207], v[84:87]
	v_mfma_f32_16x16x32_bf16 v[80:83], v[180:183], v[204:207], v[80:83]
	v_mfma_f32_16x16x32_bf16 v[68:71], v[172:175], v[212:215], v[68:71]
	v_mfma_f32_16x16x32_bf16 v[64:67], v[180:183], v[212:215], v[64:67]
	s_setprio 0
	s_barrier
	s_add_i32 s24, s48, s36
	s_mov_b32 m0, s24
	ds_read_b128 v[184:187], v171 offset:16384
	ds_read_b128 v[188:191], v171 offset:17408
	ds_read_b128 v[192:195], v171 offset:18432
	ds_read_b128 v[196:199], v171 offset:19456
	ds_read_b128 v[200:203], v171 offset:20480
	ds_read_b128 v[204:207], v171 offset:21504
	ds_read_b128 v[208:211], v171 offset:22528
	ds_read_b128 v[212:215], v171 offset:23552
	global_load_lds_dwordx4 v146, s[28:29]
	s_add_i32 m0, s24, 0x2000
	s_add_u32 s24, s28, 0xb0000
	s_addc_u32 s25, s29, 0
	s_add_i32 s57, s49, s36
	global_load_lds_dwordx4 v150, s[28:29]
	s_mov_b32 m0, s57
	s_nop 0
	global_load_lds_dwordx4 v146, s[24:25]
	s_add_i32 m0, s57, 0x2000
	s_nop 0
	global_load_lds_dwordx4 v150, s[24:25]
	s_mov_b32 m0, s37
	s_nop 0
	global_load_lds_dwordx4 v144, s[30:31]
	s_mov_b32 m0, s38
	s_nop 0
	global_load_lds_dwordx4 v148, s[30:31]
	s_waitcnt vmcnt(8)
	s_waitcnt lgkmcnt(0)
	s_barrier
	s_setprio 1
	s_waitcnt lgkmcnt(0)
	v_mfma_f32_16x16x32_bf16 v[60:63], v[120:123], v[184:187], v[60:63]
	v_mfma_f32_16x16x32_bf16 v[56:59], v[136:139], v[184:187], v[56:59]
	v_mfma_f32_16x16x32_bf16 v[44:47], v[120:123], v[192:195], v[44:47]
	v_mfma_f32_16x16x32_bf16 v[40:43], v[136:139], v[192:195], v[40:43]
	v_mfma_f32_16x16x32_bf16 v[28:31], v[120:123], v[200:203], v[28:31]
	v_mfma_f32_16x16x32_bf16 v[24:27], v[136:139], v[200:203], v[24:27]
	v_mfma_f32_16x16x32_bf16 v[12:15], v[120:123], v[208:211], v[12:15]
	v_mfma_f32_16x16x32_bf16 v[8:11], v[136:139], v[208:211], v[8:11]
	v_mfma_f32_16x16x32_bf16 v[60:63], v[124:127], v[188:191], v[60:63]
	v_mfma_f32_16x16x32_bf16 v[56:59], v[140:143], v[188:191], v[56:59]
	v_mfma_f32_16x16x32_bf16 v[44:47], v[124:127], v[196:199], v[44:47]
	v_mfma_f32_16x16x32_bf16 v[40:43], v[140:143], v[196:199], v[40:43]
	v_mfma_f32_16x16x32_bf16 v[28:31], v[124:127], v[204:207], v[28:31]
	v_mfma_f32_16x16x32_bf16 v[24:27], v[140:143], v[204:207], v[24:27]
	v_mfma_f32_16x16x32_bf16 v[12:15], v[124:127], v[212:215], v[12:15]
	v_mfma_f32_16x16x32_bf16 v[8:11], v[140:143], v[212:215], v[8:11]
	s_setprio 0
	s_setprio 1
	v_mfma_f32_16x16x32_bf16 v[52:55], v[160:163], v[184:187], v[52:55]
	v_mfma_f32_16x16x32_bf16 v[48:51], v[176:179], v[184:187], v[48:51]
	v_mfma_f32_16x16x32_bf16 v[36:39], v[160:163], v[192:195], v[36:39]
	v_mfma_f32_16x16x32_bf16 v[32:35], v[176:179], v[192:195], v[32:35]
	v_mfma_f32_16x16x32_bf16 v[20:23], v[160:163], v[200:203], v[20:23]
	v_mfma_f32_16x16x32_bf16 v[16:19], v[176:179], v[200:203], v[16:19]
	v_mfma_f32_16x16x32_bf16 v[4:7], v[160:163], v[208:211], v[4:7]
	v_mfma_f32_16x16x32_bf16 v[0:3], v[176:179], v[208:211], v[0:3]
	v_mfma_f32_16x16x32_bf16 v[52:55], v[172:175], v[188:191], v[52:55]
	v_mfma_f32_16x16x32_bf16 v[48:51], v[180:183], v[188:191], v[48:51]
	v_mfma_f32_16x16x32_bf16 v[36:39], v[172:175], v[196:199], v[36:39]
	v_mfma_f32_16x16x32_bf16 v[32:35], v[180:183], v[196:199], v[32:35]
	v_mfma_f32_16x16x32_bf16 v[20:23], v[172:175], v[204:207], v[20:23]
	v_mfma_f32_16x16x32_bf16 v[16:19], v[180:183], v[204:207], v[16:19]
	v_mfma_f32_16x16x32_bf16 v[4:7], v[172:175], v[212:215], v[4:7]
	v_mfma_f32_16x16x32_bf16 v[0:3], v[180:183], v[212:215], v[0:3]
	s_setprio 0
	s_barrier
; #define PG8_STAGE(bufoff, gbase, voff) do { _Pragma("unroll") for (int _i = 0; _i < 2; ++_i) \
;         __builtin_amdgcn_global_load_lds((const unsigned*)((const char*)(gbase) + (voff)[_i]), (LAS unsigned*)(lds + (bufoff) + ldsw + _i * 8192), 16, 0, 0); } while (0)
; #define PG8_WAIT_V(n) asm volatile("s_waitcnt vmcnt(" #n ")" ::: "memory")
; template <class Epi, class Sched, bool ALIGN_EPI, bool SP2>
; __device__ __forceinline__ void gemm_phase(LAS unsigned char* lds, const Gemm g, const Sched& S, const Epi& E) {
;     ...
;             PG8_LDB(B0, 1, 0); PG8_LDB(B1, 1, 1); PG8_SCHED; PG8_LDA(At, 1, 0); PG8_STAGE(PG8_SA(0, 1), a2 + hstep, voffA);
;             PG8_WAIT_V(8); PG8_WAIT_L(0); PG8_BAR; PG8_MMA(0, 0, At, B0); PG8_MMA(0, 1, At, B1); PG8_BAR; PG8_SCHED;
;             PG8_LDA(At, 1, 1); PG8_STAGE(PG8_SB(1, 0), b3, voffB); PG8_STAGE(PG8_SB(1, 1), b3 + hstep, voffB); PG8_STAGE(PG8_SA(1, 0), a3, voffA);
;             PG8_WAIT_V(8); PG8_WAIT_L(0); PG8_BAR; PG8_MMA(1, 0, At, B0); PG8_MMA(1, 1, At, B1); PG8_BAR; PG8_SCHED;
;             } else {
;             PG8_LDB(B0, 0, 0); PG8_SCHED; PG8_LDA(At, 0, 0); PG8_STAGE(PG8_SA(1, 1), a1 + hstep, voffA);
;             PG8_WAIT_L(8); PG8_BAR; PG8_WAIT_L(0); PG8_MMA(0, 0, At, B0); PG8_BAR; PG8_SCHED;
;             PG8_LDB(B1, 0, 1); PG8_STAGE(PG8_SB(0, 0), b2, voffB);
;             PG8_BAR; PG8_WAIT_L(0); PG8_MMA(0, 1, At, B1); PG8_BAR;
;             PG8_LDA(At, 0, 1); PG8_STAGE(PG8_SA(0, 0), a2, voffA);
;             PG8_BAR; PG8_WAIT_L(0); PG8_MMA(1, 0, At, B0); PG8_BAR; PG8_SCHED;
;             PG8_STAGE(PG8_SB(0, 1), b2 + hstep, voffB);
;             PG8_WAIT_V(6); PG8_BAR; PG8_MMA(1, 1, At, B1); PG8_BAR;
;             PG8_LDB(B0, 1, 0); PG8_SCHED; PG8_LDA(At, 1, 0); PG8_STAGE(PG8_SA(0, 1), a2 + hstep, voffA);
;             PG8_WAIT_L(8); PG8_BAR; PG8_WAIT_L(0); PG8_MMA(0, 0, At, B0); PG8_BAR; PG8_SCHED;
;             PG8_LDB(B1, 1, 1); PG8_STAGE(PG8_SB(1, 0), b3, voffB);
;             PG8_BAR; PG8_WAIT_L(0); PG8_MMA(0, 1, At, B1); PG8_BAR;
;             PG8_LDA(At, 1, 1); PG8_STAGE(PG8_SA(1, 0), a3, voffA);
;             PG8_BAR; PG8_WAIT_L(0); PG8_MMA(1, 0, At, B0); PG8_BAR; PG8_SCHED;
;             PG8_STAGE(PG8_SB(1, 1), b3 + hstep, voffB);
;             PG8_WAIT_V(6); PG8_BAR; PG8_MMA(1, 1, At, B1); PG8_BAR;
;             }
;         }
;         if constexpr (ALIGN_EPI) { if (wr == 0) PG8_BAR; }
	s_add_i32 s57, 0, 0x18000
	s_add_i32 s58, 0, 0x1c000
	v_add_u32_e32 v140, s57, v167
	v_add_u32_e32 v180, s58, v167
	ds_read_b128 v[120:123], v140
	ds_read_b128 v[124:127], v140 offset:1024
	ds_read_b128 v[136:139], v140 offset:2048
	ds_read_b128 v[140:143], v140 offset:3072
	ds_read_b128 v[160:163], v180
	ds_read_b128 v[172:175], v180 offset:1024
	ds_read_b128 v[176:179], v180 offset:2048
	ds_read_b128 v[180:183], v180 offset:3072
	s_add_u32 s24, s30, 0xb0000
	s_addc_u32 s25, s31, 0
	s_mov_b32 m0, s39
	ds_read_b128 v[184:187], v171 offset:32768
	ds_read_b128 v[188:191], v171 offset:33792
	ds_read_b128 v[192:195], v171 offset:34816
	ds_read_b128 v[196:199], v171 offset:35840
	ds_read_b128 v[200:203], v171 offset:36864
	ds_read_b128 v[204:207], v171 offset:37888
	ds_read_b128 v[208:211], v171 offset:38912
	ds_read_b128 v[212:215], v171 offset:39936
	global_load_lds_dwordx4 v144, s[24:25]
	s_mov_b32 m0, s40
	s_nop 0
	global_load_lds_dwordx4 v148, s[24:25]
	s_waitcnt vmcnt(8)
	s_waitcnt lgkmcnt(0)
	s_barrier
	s_setprio 1
	s_waitcnt lgkmcnt(0)
	v_mfma_f32_16x16x32_bf16 v[132:135], v[120:123], v[184:187], v[132:135]
	v_mfma_f32_16x16x32_bf16 v[128:131], v[136:139], v[184:187], v[128:131]
	v_mfma_f32_16x16x32_bf16 v[108:111], v[120:123], v[192:195], v[108:111]
	v_mfma_f32_16x16x32_bf16 v[104:107], v[136:139], v[192:195], v[104:107]
	v_mfma_f32_16x16x32_bf16 v[92:95], v[120:123], v[200:203], v[92:95]
	v_mfma_f32_16x16x32_bf16 v[88:91], v[136:139], v[200:203], v[88:91]
	v_mfma_f32_16x16x32_bf16 v[76:79], v[120:123], v[208:211], v[76:79]
	v_mfma_f32_16x16x32_bf16 v[72:75], v[136:139], v[208:211], v[72:75]
	v_mfma_f32_16x16x32_bf16 v[132:135], v[124:127], v[188:191], v[132:135]
	v_mfma_f32_16x16x32_bf16 v[128:131], v[140:143], v[188:191], v[128:131]
	v_mfma_f32_16x16x32_bf16 v[108:111], v[124:127], v[196:199], v[108:111]
	v_mfma_f32_16x16x32_bf16 v[104:107], v[140:143], v[196:199], v[104:107]
	v_mfma_f32_16x16x32_bf16 v[92:95], v[124:127], v[204:207], v[92:95]
	v_mfma_f32_16x16x32_bf16 v[88:91], v[140:143], v[204:207], v[88:91]
	v_mfma_f32_16x16x32_bf16 v[76:79], v[124:127], v[212:215], v[76:79]
	v_mfma_f32_16x16x32_bf16 v[72:75], v[140:143], v[212:215], v[72:75]
	s_setprio 0
	s_setprio 1
	v_mfma_f32_16x16x32_bf16 v[116:119], v[160:163], v[184:187], v[116:119]
	v_mfma_f32_16x16x32_bf16 v[112:115], v[176:179], v[184:187], v[112:115]
	v_mfma_f32_16x16x32_bf16 v[100:103], v[160:163], v[192:195], v[100:103]
	v_mfma_f32_16x16x32_bf16 v[96:99], v[176:179], v[192:195], v[96:99]
	v_mfma_f32_16x16x32_bf16 v[84:87], v[160:163], v[200:203], v[84:87]
	v_mfma_f32_16x16x32_bf16 v[80:83], v[176:179], v[200:203], v[80:83]
	v_mfma_f32_16x16x32_bf16 v[68:71], v[160:163], v[208:211], v[68:71]
	v_mfma_f32_16x16x32_bf16 v[64:67], v[176:179], v[208:211], v[64:67]
	v_mfma_f32_16x16x32_bf16 v[116:119], v[172:175], v[188:191], v[116:119]
	v_mfma_f32_16x16x32_bf16 v[112:115], v[180:183], v[188:191], v[112:115]
	v_mfma_f32_16x16x32_bf16 v[100:103], v[172:175], v[196:199], v[100:103]
	v_mfma_f32_16x16x32_bf16 v[96:99], v[180:183], v[196:199], v[96:99]
	v_mfma_f32_16x16x32_bf16 v[84:87], v[172:175], v[204:207], v[84:87]
	v_mfma_f32_16x16x32_bf16 v[80:83], v[180:183], v[204:207], v[80:83]
	v_mfma_f32_16x16x32_bf16 v[68:71], v[172:175], v[212:215], v[68:71]
	v_mfma_f32_16x16x32_bf16 v[64:67], v[180:183], v[212:215], v[64:67]
	s_setprio 0
	s_barrier
	s_add_u32 s100, s24, 0xfff50080
	s_addc_u32 s101, s25, -1
	s_add_u32 s98, s28, 0x80
	s_addc_u32 s99, s29, 0
	s_add_i32 s24, s57, s36
	s_mov_b32 m0, s24
	ds_read_b128 v[184:187], v171 offset:49152
	ds_read_b128 v[188:191], v171 offset:50176
	ds_read_b128 v[192:195], v171 offset:51200
	ds_read_b128 v[196:199], v171 offset:52224
	ds_read_b128 v[200:203], v171 offset:53248
	ds_read_b128 v[204:207], v171 offset:54272
	ds_read_b128 v[208:211], v171 offset:55296
	ds_read_b128 v[212:215], v171 offset:56320
	global_load_lds_dwordx4 v146, s[98:99]
	s_add_i32 m0, s24, 0x2000
	s_add_u32 s24, s28, 0xb0080
	s_addc_u32 s25, s29, 0
	s_add_i32 s28, s58, s36
	global_load_lds_dwordx4 v150, s[98:99]
	s_mov_b32 m0, s28
	s_nop 0
	global_load_lds_dwordx4 v146, s[24:25]
	s_add_i32 m0, s28, 0x2000
	s_nop 0
	global_load_lds_dwordx4 v150, s[24:25]
	s_mov_b32 m0, s45
	s_nop 0
	global_load_lds_dwordx4 v144, s[100:101]
	s_mov_b32 m0, s46
	s_nop 0
	global_load_lds_dwordx4 v148, s[100:101]
	s_waitcnt vmcnt(8)
	s_waitcnt lgkmcnt(0)
	s_barrier
	s_setprio 1
	s_waitcnt lgkmcnt(0)
	v_mfma_f32_16x16x32_bf16 v[60:63], v[120:123], v[184:187], v[60:63]
	v_mfma_f32_16x16x32_bf16 v[56:59], v[136:139], v[184:187], v[56:59]
	v_mfma_f32_16x16x32_bf16 v[44:47], v[120:123], v[192:195], v[44:47]
	v_mfma_f32_16x16x32_bf16 v[40:43], v[136:139], v[192:195], v[40:43]
	v_mfma_f32_16x16x32_bf16 v[28:31], v[120:123], v[200:203], v[28:31]
	v_mfma_f32_16x16x32_bf16 v[24:27], v[136:139], v[200:203], v[24:27]
	v_mfma_f32_16x16x32_bf16 v[12:15], v[120:123], v[208:211], v[12:15]
	v_mfma_f32_16x16x32_bf16 v[8:11], v[136:139], v[208:211], v[8:11]
	v_mfma_f32_16x16x32_bf16 v[60:63], v[124:127], v[188:191], v[60:63]
	v_mfma_f32_16x16x32_bf16 v[56:59], v[140:143], v[188:191], v[56:59]
	v_mfma_f32_16x16x32_bf16 v[44:47], v[124:127], v[196:199], v[44:47]
	v_mfma_f32_16x16x32_bf16 v[40:43], v[140:143], v[196:199], v[40:43]
	v_mfma_f32_16x16x32_bf16 v[28:31], v[124:127], v[204:207], v[28:31]
	v_mfma_f32_16x16x32_bf16 v[24:27], v[140:143], v[204:207], v[24:27]
	v_mfma_f32_16x16x32_bf16 v[12:15], v[124:127], v[212:215], v[12:15]
	v_mfma_f32_16x16x32_bf16 v[8:11], v[140:143], v[212:215], v[8:11]
	s_setprio 0
	s_setprio 1
	v_mfma_f32_16x16x32_bf16 v[52:55], v[160:163], v[184:187], v[52:55]
	v_mfma_f32_16x16x32_bf16 v[48:51], v[176:179], v[184:187], v[48:51]
	v_mfma_f32_16x16x32_bf16 v[36:39], v[160:163], v[192:195], v[36:39]
	v_mfma_f32_16x16x32_bf16 v[32:35], v[176:179], v[192:195], v[32:35]
	v_mfma_f32_16x16x32_bf16 v[20:23], v[160:163], v[200:203], v[20:23]
	v_mfma_f32_16x16x32_bf16 v[16:19], v[176:179], v[200:203], v[16:19]
	v_mfma_f32_16x16x32_bf16 v[4:7], v[160:163], v[208:211], v[4:7]
	v_mfma_f32_16x16x32_bf16 v[0:3], v[176:179], v[208:211], v[0:3]
	v_mfma_f32_16x16x32_bf16 v[52:55], v[172:175], v[188:191], v[52:55]
	v_mfma_f32_16x16x32_bf16 v[48:51], v[180:183], v[188:191], v[48:51]
	v_mfma_f32_16x16x32_bf16 v[36:39], v[172:175], v[196:199], v[36:39]
	v_mfma_f32_16x16x32_bf16 v[32:35], v[180:183], v[196:199], v[32:35]
	v_mfma_f32_16x16x32_bf16 v[20:23], v[172:175], v[204:207], v[20:23]
	v_mfma_f32_16x16x32_bf16 v[16:19], v[180:183], v[204:207], v[16:19]
	v_mfma_f32_16x16x32_bf16 v[4:7], v[172:175], v[212:215], v[4:7]
	v_mfma_f32_16x16x32_bf16 v[0:3], v[180:183], v[212:215], v[0:3]
	s_setprio 0
	s_barrier
	s_add_i32 s56, s56, 2
	s_add_u32 s54, s54, 0x100
	s_addc_u32 s55, s55, 0
	s_cmp_gt_u32 s56, 41
	s_mov_b64 s[24:25], s[26:27]
	s_cbranch_scc0 .LBB0_766
	s_and_b64 vcc, exec, s[12:13]
	s_cbranch_vccz .LBB0_769
	s_barrier

; #define LAS __attribute__((address_space(3)))
; __global__ void __launch_bounds__(512, 2) fwd_kernel(Args args) {
;     extern __shared__ __attribute__((aligned(16))) unsigned char lds_raw[];
;     LAS unsigned char* lds = (LAS unsigned char*)lds_raw;
	.amdhsa_kernel _Z10fwd_kernel4Args
		.amdhsa_group_segment_fixed_size 0
		.amdhsa_private_segment_fixed_size 0
		.amdhsa_kernarg_size 456
		.amdhsa_user_sgpr_count 2
		.amdhsa_user_sgpr_dispatch_ptr 0
		.amdhsa_user_sgpr_queue_ptr 0
		.amdhsa_user_sgpr_kernarg_segment_ptr 1
		.amdhsa_user_sgpr_dispatch_id 0
		.amdhsa_user_sgpr_kernarg_preload_length 0
		.amdhsa_user_sgpr_kernarg_preload_offset 0
		.amdhsa_user_sgpr_private_segment_size 0
		.amdhsa_uses_dynamic_stack 0
		.amdhsa_enable_private_segment 0
		.amdhsa_system_sgpr_workgroup_id_x 1
		.amdhsa_system_sgpr_workgroup_id_y 0
		.amdhsa_system_sgpr_workgroup_id_z 0
		.amdhsa_system_sgpr_workgroup_info 0
		.amdhsa_system_vgpr_workitem_id 2
		.amdhsa_next_free_vgpr 237
		.amdhsa_next_free_sgpr 102
		.amdhsa_accum_offset 240
		.amdhsa_reserve_vcc 1
		.amdhsa_float_round_mode_32 0
		.amdhsa_float_round_mode_16_64 0
		.amdhsa_float_denorm_mode_32 3
		.amdhsa_float_denorm_mode_16_64 3
		.amdhsa_dx10_clamp 1
		.amdhsa_ieee_mode 1
		.amdhsa_fp16_overflow 0
		.amdhsa_tg_split 0
		.amdhsa_exception_fp_ieee_invalid_op 0
		.amdhsa_exception_fp_denorm_src 0
		.amdhsa_exception_fp_ieee_div_zero 0
		.amdhsa_exception_fp_ieee_overflow 0
		.amdhsa_exception_fp_ieee_underflow 0
		.amdhsa_exception_fp_ieee_inexact 0
		.amdhsa_exception_int_div_zero 0
	.end_amdhsa_kernel

amdhsa.kernels:
  - .agpr_count:     0
    .args:
      - .offset:         0
        .size:           200
        .value_kind:     by_value
      - .offset:         200
        .size:           4
        .value_kind:     hidden_block_count_x
      - .offset:         204
        .size:           4
        .value_kind:     hidden_block_count_y
      - .offset:         208
        .size:           4
        .value_kind:     hidden_block_count_z
      - .offset:         212
        .size:           2
        .value_kind:     hidden_group_size_x
      - .offset:         214
        .size:           2
        .value_kind:     hidden_group_size_y
      - .offset:         216
        .size:           2
        .value_kind:     hidden_group_size_z
      - .offset:         218
        .size:           2
        .value_kind:     hidden_remainder_x
      - .offset:         220
        .size:           2
        .value_kind:     hidden_remainder_y
      - .offset:         222
        .size:           2
        .value_kind:     hidden_remainder_z
      - .offset:         240
        .size:           8
        .value_kind:     hidden_global_offset_x
      - .offset:         248
        .size:           8
        .value_kind:     hidden_global_offset_y
      - .offset:         256
        .size:           8
        .value_kind:     hidden_global_offset_z
      - .offset:         264
        .size:           2
        .value_kind:     hidden_grid_dims
      - .offset:         288
        .size:           8
        .value_kind:     hidden_multigrid_sync_arg
      - .offset:         320
        .size:           4
        .value_kind:     hidden_dynamic_lds_size
    .group_segment_fixed_size: 0
    .kernarg_segment_align: 8
    .kernarg_segment_size: 456
    .language:       OpenCL C
    .language_version:
      - 2
      - 0
    .max_flat_workgroup_size: 512
    .name:           _Z10fwd_kernel4Args
    .private_segment_fixed_size: 0
    .sgpr_count:     108
    .sgpr_spill_count: 53
    .symbol:         _Z10fwd_kernel4Args.kd
    .uniform_work_group_size: 1
    .uses_dynamic_stack: false
    .vgpr_count:     237
    .vgpr_spill_count: 0
    .wavefront_size: 64
